# GEMM loops: all per-segment setprio removed, redundant lgkmcnt(0) after barrier removed
# baseline (speedup 1.0000x reference)
; #define PG8_STAGE(bufoff, gbase, voff) do { _Pragma("unroll") for (int _i = 0; _i < 2; ++_i) \
;         __builtin_amdgcn_global_load_lds((const unsigned*)((const char*)(gbase) + (voff)[_i]), (PG8_LAS unsigned*)(lds + (bufoff) + ldsw + _i * 8192), 16, 0, 0); } while (0)
; #define PG8_LDA(dst, b, h) do { _Pragma("unroll") for (int m = 0; m < 4; ++m) _Pragma("unroll") for (int k = 0; k < 2; ++k) dst[m][k] = *(const PG8_LAS bf16x8*)(lds + PG8_SA(b, h) + aoff + m * 2048 + k * 1024); } while (0)
; #define PG8_LDB(dst, b, h) do { _Pragma("unroll") for (int n = 0; n < 2; ++n) _Pragma("unroll") for (int k = 0; k < 2; ++k) dst[n][k] = *(const PG8_LAS bf16x8*)(lds + PG8_SB(b, h) + boff + n * 2048 + k * 1024); } while (0)
; #define PG8_MMA(ai, bj, At, Bt) do { __builtin_amdgcn_s_setprio(1); _Pragma("unroll") for (int m = 0; m < 4; ++m) _Pragma("unroll") for (int n = 0; n < 2; ++n) _Pragma("unroll") for (int k = 0; k < 2; ++k) \
;         acc[ai][bj][m][n] = __builtin_amdgcn_mfma_f32_16x16x32_bf16(Bt[n][k], At[m][k], acc[ai][bj][m][n], 0, 0, 0); __builtin_amdgcn_s_setprio(0); } while (0)
; #define PG8_WAIT_V(n) asm volatile("s_waitcnt vmcnt(" #n ")" ::: "memory")
; #define PG8_WAIT_L(n) asm volatile("s_waitcnt lgkmcnt(" #n ")" ::: "memory")
; #define PG8_BAR __builtin_amdgcn_s_barrier()
; template <class Epi, class Sched, bool ALIGN_EPI = false, bool SP2 = false>
; __device__ __forceinline__ void gemm_phase(PG8_LAS unsigned char* lds, const Gemm g, const Sched& S, const Epi& E) {
;     ...
;             const char* a1 = cA + (size_t)(t + 1) * kstep;
;             const char* a2 = last ? nA : cA + (size_t)(t + 2) * kstep; const char* b2 = last ? nB : cB + (size_t)(t + 2) * kstep;
;             const char* a3 = a2 + kstep; const char* b3 = b2 + kstep;
;             if (last && has_next) S.a_ready(nxt);
;             if constexpr (SP2) {
;             PG8_LDB(B0, 0, 0); PG8_LDB(B1, 0, 1); PG8_SCHED; PG8_LDA(At, 0, 0); PG8_STAGE(PG8_SA(1, 1), a1 + hstep, voffA);
;             PG8_WAIT_V(8); PG8_WAIT_L(0); PG8_BAR; PG8_MMA(0, 0, At, B0); PG8_MMA(0, 1, At, B1); PG8_BAR; PG8_SCHED;
;             PG8_LDA(At, 0, 1); PG8_STAGE(PG8_SB(0, 0), b2, voffB); PG8_STAGE(PG8_SB(0, 1), b2 + hstep, voffB); PG8_STAGE(PG8_SA(0, 0), a2, voffA);
;             PG8_WAIT_V(8); PG8_WAIT_L(0); PG8_BAR; PG8_MMA(1, 0, At, B0); PG8_MMA(1, 1, At, B1); PG8_BAR; PG8_SCHED;
.LBB0_232:
	ds_read_b128 v[154:157], v149
	ds_read_b128 v[158:161], v149 offset:1024
	ds_read_b128 v[162:165], v149 offset:2048
	ds_read_b128 v[166:169], v149 offset:3072
	ds_read_b128 v[170:173], v150
	ds_read_b128 v[174:177], v150 offset:1024
	ds_read_b128 v[178:181], v150 offset:2048
	ds_read_b128 v[182:185], v150 offset:3072
	s_add_u32 s40, s38, 0xfffc0080
	s_addc_u32 s41, s39, -1
	s_cmp_eq_u32 s68, 12
	s_cselect_b32 s43, s21, s41
	s_cselect_b32 s42, s64, s40
	s_cselect_b32 s41, s19, s67
	s_cselect_b32 s40, s65, s66
	v_lshl_add_u64 v[144:145], s[38:39], 0, v[136:137]
	s_add_i32 m0, s37, 0xc000
	ds_read_b128 v[186:189], v151
	ds_read_b128 v[190:193], v151 offset:1024
	ds_read_b128 v[194:197], v151 offset:2048
	ds_read_b128 v[198:201], v151 offset:3072
	ds_read_b128 v[202:205], v151 offset:4096
	ds_read_b128 v[206:209], v151 offset:5120
	ds_read_b128 v[210:213], v151 offset:6144
	ds_read_b128 v[214:217], v151 offset:7168
	global_load_lds_dwordx4 v[144:145], off
	v_lshl_add_u64 v[144:145], s[38:39], 0, v[138:139]
	s_add_i32 m0, s37, 0xe000
	s_nop 0
	global_load_lds_dwordx4 v[144:145], off
	s_waitcnt vmcnt(8)
	s_waitcnt lgkmcnt(0)
	s_barrier
	v_mfma_f32_16x16x32_bf16 v[120:123], v[154:157], v[186:189], v[120:123]
	v_mfma_f32_16x16x32_bf16 v[116:119], v[162:165], v[186:189], v[116:119]
	v_mfma_f32_16x16x32_bf16 v[108:111], v[154:157], v[194:197], v[108:111]
	v_mfma_f32_16x16x32_bf16 v[100:103], v[162:165], v[194:197], v[100:103]
	v_mfma_f32_16x16x32_bf16 v[92:95], v[154:157], v[202:205], v[92:95]
	v_mfma_f32_16x16x32_bf16 v[84:87], v[162:165], v[202:205], v[84:87]
	v_mfma_f32_16x16x32_bf16 v[76:79], v[154:157], v[210:213], v[76:79]
	v_mfma_f32_16x16x32_bf16 v[68:71], v[162:165], v[210:213], v[68:71]
	v_mfma_f32_16x16x32_bf16 v[120:123], v[158:161], v[190:193], v[120:123]
	v_mfma_f32_16x16x32_bf16 v[116:119], v[166:169], v[190:193], v[116:119]
	v_mfma_f32_16x16x32_bf16 v[108:111], v[158:161], v[198:201], v[108:111]
	v_mfma_f32_16x16x32_bf16 v[100:103], v[166:169], v[198:201], v[100:103]
	v_mfma_f32_16x16x32_bf16 v[92:95], v[158:161], v[206:209], v[92:95]
	v_mfma_f32_16x16x32_bf16 v[84:87], v[166:169], v[206:209], v[84:87]
	v_mfma_f32_16x16x32_bf16 v[76:79], v[158:161], v[214:217], v[76:79]
	v_mfma_f32_16x16x32_bf16 v[68:71], v[166:169], v[214:217], v[68:71]
	v_mfma_f32_16x16x32_bf16 v[124:127], v[170:173], v[186:189], v[124:127]
	v_mfma_f32_16x16x32_bf16 v[112:115], v[178:181], v[186:189], v[112:115]
	v_mfma_f32_16x16x32_bf16 v[104:107], v[170:173], v[194:197], v[104:107]
	v_mfma_f32_16x16x32_bf16 v[96:99], v[178:181], v[194:197], v[96:99]
	v_mfma_f32_16x16x32_bf16 v[88:91], v[170:173], v[202:205], v[88:91]
	v_mfma_f32_16x16x32_bf16 v[80:83], v[178:181], v[202:205], v[80:83]
	v_mfma_f32_16x16x32_bf16 v[72:75], v[170:173], v[210:213], v[72:75]
	v_mfma_f32_16x16x32_bf16 v[64:67], v[178:181], v[210:213], v[64:67]
	v_mfma_f32_16x16x32_bf16 v[124:127], v[174:177], v[190:193], v[124:127]
	v_mfma_f32_16x16x32_bf16 v[112:115], v[182:185], v[190:193], v[112:115]
	v_mfma_f32_16x16x32_bf16 v[104:107], v[174:177], v[198:201], v[104:107]
	v_mfma_f32_16x16x32_bf16 v[96:99], v[182:185], v[198:201], v[96:99]
	v_mfma_f32_16x16x32_bf16 v[88:91], v[174:177], v[206:209], v[88:91]
	v_mfma_f32_16x16x32_bf16 v[80:83], v[182:185], v[206:209], v[80:83]
	v_mfma_f32_16x16x32_bf16 v[72:75], v[174:177], v[214:217], v[72:75]
	v_mfma_f32_16x16x32_bf16 v[64:67], v[182:185], v[214:217], v[64:67]
	s_barrier
	s_add_i32 s69, s57, s48
	v_lshl_add_u64 v[144:145], s[40:41], 0, v[132:133]
	s_mov_b32 m0, s69
	ds_read_b128 v[186:189], v151 offset:16384
	ds_read_b128 v[190:193], v151 offset:17408
	ds_read_b128 v[194:197], v151 offset:18432
	ds_read_b128 v[198:201], v151 offset:19456
	ds_read_b128 v[202:205], v151 offset:20480
	ds_read_b128 v[206:209], v151 offset:21504
	ds_read_b128 v[210:213], v151 offset:22528
	ds_read_b128 v[214:217], v151 offset:23552
	global_load_lds_dwordx4 v[144:145], off
	s_add_i32 m0, s69, 0x2000
	s_add_u32 s70, s40, 0x40000
	v_lshl_add_u64 v[218:219], s[40:41], 0, v[128:129]
	s_addc_u32 s71, s41, 0
	s_add_i32 s69, s58, s48
	global_load_lds_dwordx4 v[218:219], off
	v_lshl_add_u64 v[220:221], s[70:71], 0, v[132:133]
	s_mov_b32 m0, s69
	v_lshl_add_u64 v[222:223], s[42:43], 0, v[130:131]
	global_load_lds_dwordx4 v[220:221], off
	v_lshl_add_u64 v[220:221], s[70:71], 0, v[128:129]
	s_add_i32 m0, s69, 0x2000
	s_nop 0
	global_load_lds_dwordx4 v[220:221], off
	v_lshl_add_u64 v[220:221], s[42:43], 0, v[134:135]
	s_mov_b32 m0, s37
	s_nop 0
	global_load_lds_dwordx4 v[220:221], off
	s_mov_b32 m0, s50
	s_nop 0
	global_load_lds_dwordx4 v[222:223], off
	s_waitcnt vmcnt(8)
	s_waitcnt lgkmcnt(0)
	s_barrier
; #define PG8_STAGE(bufoff, gbase, voff) do { _Pragma("unroll") for (int _i = 0; _i < 2; ++_i) \
;         __builtin_amdgcn_global_load_lds((const unsigned*)((const char*)(gbase) + (voff)[_i]), (PG8_LAS unsigned*)(lds + (bufoff) + ldsw + _i * 8192), 16, 0, 0); } while (0)
; #define PG8_LDA(dst, b, h) do { _Pragma("unroll") for (int m = 0; m < 4; ++m) _Pragma("unroll") for (int k = 0; k < 2; ++k) dst[m][k] = *(const PG8_LAS bf16x8*)(lds + PG8_SA(b, h) + aoff + m * 2048 + k * 1024); } while (0)
; #define PG8_LDB(dst, b, h) do { _Pragma("unroll") for (int n = 0; n < 2; ++n) _Pragma("unroll") for (int k = 0; k < 2; ++k) dst[n][k] = *(const PG8_LAS bf16x8*)(lds + PG8_SB(b, h) + boff + n * 2048 + k * 1024); } while (0)
; #define PG8_MMA(ai, bj, At, Bt) do { __builtin_amdgcn_s_setprio(1); _Pragma("unroll") for (int m = 0; m < 4; ++m) _Pragma("unroll") for (int n = 0; n < 2; ++n) _Pragma("unroll") for (int k = 0; k < 2; ++k) \
;         acc[ai][bj][m][n] = __builtin_amdgcn_mfma_f32_16x16x32_bf16(Bt[n][k], At[m][k], acc[ai][bj][m][n], 0, 0, 0); __builtin_amdgcn_s_setprio(0); } while (0)
; #define PG8_WAIT_V(n) asm volatile("s_waitcnt vmcnt(" #n ")" ::: "memory")
; #define PG8_WAIT_L(n) asm volatile("s_waitcnt lgkmcnt(" #n ")" ::: "memory")
; #define PG8_BAR __builtin_amdgcn_s_barrier()
; #define PG8_SCHED __builtin_amdgcn_sched_barrier(0)
; template <class Epi, class Sched, bool ALIGN_EPI = false, bool SP2 = false>
; __device__ __forceinline__ void gemm_phase(PG8_LAS unsigned char* lds, const Gemm g, const Sched& S, const Epi& E) {
;     ...
;             PG8_WAIT_V(8); PG8_WAIT_L(0); PG8_BAR; PG8_MMA(1, 0, At, B0); PG8_MMA(1, 1, At, B1); PG8_BAR; PG8_SCHED;
;             PG8_LDB(B0, 1, 0); PG8_LDB(B1, 1, 1); PG8_SCHED; PG8_LDA(At, 1, 0); PG8_STAGE(PG8_SA(0, 1), a2 + hstep, voffA);
;             PG8_WAIT_V(8); PG8_WAIT_L(0); PG8_BAR; PG8_MMA(0, 0, At, B0); PG8_MMA(0, 1, At, B1); PG8_BAR; PG8_SCHED;
	v_mfma_f32_16x16x32_bf16 v[60:63], v[154:157], v[186:189], v[60:63]
	v_mfma_f32_16x16x32_bf16 v[52:55], v[162:165], v[186:189], v[52:55]
	v_mfma_f32_16x16x32_bf16 v[44:47], v[154:157], v[194:197], v[44:47]
	v_mfma_f32_16x16x32_bf16 v[36:39], v[162:165], v[194:197], v[36:39]
	v_mfma_f32_16x16x32_bf16 v[28:31], v[154:157], v[202:205], v[28:31]
	v_mfma_f32_16x16x32_bf16 v[20:23], v[162:165], v[202:205], v[20:23]
	v_mfma_f32_16x16x32_bf16 v[12:15], v[154:157], v[210:213], v[12:15]
	v_mfma_f32_16x16x32_bf16 v[4:7], v[162:165], v[210:213], v[4:7]
	v_mfma_f32_16x16x32_bf16 v[60:63], v[158:161], v[190:193], v[60:63]
	v_mfma_f32_16x16x32_bf16 v[52:55], v[166:169], v[190:193], v[52:55]
	v_mfma_f32_16x16x32_bf16 v[44:47], v[158:161], v[198:201], v[44:47]
	v_mfma_f32_16x16x32_bf16 v[36:39], v[166:169], v[198:201], v[36:39]
	v_mfma_f32_16x16x32_bf16 v[28:31], v[158:161], v[206:209], v[28:31]
	v_mfma_f32_16x16x32_bf16 v[20:23], v[166:169], v[206:209], v[20:23]
	v_mfma_f32_16x16x32_bf16 v[12:15], v[158:161], v[214:217], v[12:15]
	v_mfma_f32_16x16x32_bf16 v[4:7], v[166:169], v[214:217], v[4:7]
	v_mfma_f32_16x16x32_bf16 v[56:59], v[170:173], v[186:189], v[56:59]
	v_mfma_f32_16x16x32_bf16 v[48:51], v[178:181], v[186:189], v[48:51]
	v_mfma_f32_16x16x32_bf16 v[40:43], v[170:173], v[194:197], v[40:43]
	v_mfma_f32_16x16x32_bf16 v[32:35], v[178:181], v[194:197], v[32:35]
	v_mfma_f32_16x16x32_bf16 v[24:27], v[170:173], v[202:205], v[24:27]
	v_mfma_f32_16x16x32_bf16 v[16:19], v[178:181], v[202:205], v[16:19]
	v_mfma_f32_16x16x32_bf16 v[8:11], v[170:173], v[210:213], v[8:11]
	v_mfma_f32_16x16x32_bf16 v[0:3], v[178:181], v[210:213], v[0:3]
	v_mfma_f32_16x16x32_bf16 v[56:59], v[174:177], v[190:193], v[56:59]
	v_mfma_f32_16x16x32_bf16 v[48:51], v[182:185], v[190:193], v[48:51]
	v_mfma_f32_16x16x32_bf16 v[40:43], v[174:177], v[198:201], v[40:43]
	v_mfma_f32_16x16x32_bf16 v[32:35], v[182:185], v[198:201], v[32:35]
	v_mfma_f32_16x16x32_bf16 v[24:27], v[174:177], v[206:209], v[24:27]
	v_mfma_f32_16x16x32_bf16 v[16:19], v[182:185], v[206:209], v[16:19]
	v_mfma_f32_16x16x32_bf16 v[8:11], v[174:177], v[214:217], v[8:11]
	v_mfma_f32_16x16x32_bf16 v[0:3], v[182:185], v[214:217], v[0:3]
	s_barrier
	s_add_i32 s69, 0, 0x18000
	v_add_u32_e32 v153, s69, v147
	s_add_i32 s70, 0, 0x1c000
	ds_read_b128 v[154:157], v153
	ds_read_b128 v[158:161], v153 offset:1024
	ds_read_b128 v[162:165], v153 offset:2048
	ds_read_b128 v[166:169], v153 offset:3072
	v_add_u32_e32 v153, s70, v147
	ds_read_b128 v[170:173], v153
	ds_read_b128 v[174:177], v153 offset:1024
	ds_read_b128 v[178:181], v153 offset:2048
	ds_read_b128 v[182:185], v153 offset:3072
	s_add_u32 s42, s42, 0x40000
	s_addc_u32 s43, s43, 0
	s_mov_b32 m0, s51
	v_lshl_add_u64 v[224:225], s[42:43], 0, v[134:135]
	ds_read_b128 v[186:189], v151 offset:32768
	ds_read_b128 v[190:193], v151 offset:33792
	ds_read_b128 v[194:197], v151 offset:34816
	ds_read_b128 v[198:201], v151 offset:35840
	ds_read_b128 v[202:205], v151 offset:36864
	ds_read_b128 v[206:209], v151 offset:37888
	ds_read_b128 v[210:213], v151 offset:38912
	ds_read_b128 v[214:217], v151 offset:39936
	global_load_lds_dwordx4 v[224:225], off
	v_lshl_add_u64 v[224:225], s[42:43], 0, v[130:131]
	s_mov_b32 m0, s52
	s_nop 0
	global_load_lds_dwordx4 v[224:225], off
	s_waitcnt vmcnt(8)
	s_waitcnt lgkmcnt(0)
	s_barrier
	v_mfma_f32_16x16x32_bf16 v[120:123], v[154:157], v[186:189], v[120:123]
	v_mfma_f32_16x16x32_bf16 v[116:119], v[162:165], v[186:189], v[116:119]
	v_mfma_f32_16x16x32_bf16 v[108:111], v[154:157], v[194:197], v[108:111]
	v_mfma_f32_16x16x32_bf16 v[100:103], v[162:165], v[194:197], v[100:103]
	v_mfma_f32_16x16x32_bf16 v[92:95], v[154:157], v[202:205], v[92:95]
	v_mfma_f32_16x16x32_bf16 v[84:87], v[162:165], v[202:205], v[84:87]
	v_mfma_f32_16x16x32_bf16 v[76:79], v[154:157], v[210:213], v[76:79]
	v_mfma_f32_16x16x32_bf16 v[68:71], v[162:165], v[210:213], v[68:71]
	v_mfma_f32_16x16x32_bf16 v[120:123], v[158:161], v[190:193], v[120:123]
	v_mfma_f32_16x16x32_bf16 v[116:119], v[166:169], v[190:193], v[116:119]
	v_mfma_f32_16x16x32_bf16 v[108:111], v[158:161], v[198:201], v[108:111]
	v_mfma_f32_16x16x32_bf16 v[100:103], v[166:169], v[198:201], v[100:103]
	v_mfma_f32_16x16x32_bf16 v[92:95], v[158:161], v[206:209], v[92:95]
	v_mfma_f32_16x16x32_bf16 v[84:87], v[166:169], v[206:209], v[84:87]
	v_mfma_f32_16x16x32_bf16 v[76:79], v[158:161], v[214:217], v[76:79]
	v_mfma_f32_16x16x32_bf16 v[68:71], v[166:169], v[214:217], v[68:71]
	v_mfma_f32_16x16x32_bf16 v[124:127], v[170:173], v[186:189], v[124:127]
	v_mfma_f32_16x16x32_bf16 v[112:115], v[178:181], v[186:189], v[112:115]
	v_mfma_f32_16x16x32_bf16 v[104:107], v[170:173], v[194:197], v[104:107]
	v_mfma_f32_16x16x32_bf16 v[96:99], v[178:181], v[194:197], v[96:99]
	v_mfma_f32_16x16x32_bf16 v[88:91], v[170:173], v[202:205], v[88:91]
	v_mfma_f32_16x16x32_bf16 v[80:83], v[178:181], v[202:205], v[80:83]
	v_mfma_f32_16x16x32_bf16 v[72:75], v[170:173], v[210:213], v[72:75]
	v_mfma_f32_16x16x32_bf16 v[64:67], v[178:181], v[210:213], v[64:67]
	v_mfma_f32_16x16x32_bf16 v[124:127], v[174:177], v[190:193], v[124:127]
	v_mfma_f32_16x16x32_bf16 v[112:115], v[182:185], v[190:193], v[112:115]
	v_mfma_f32_16x16x32_bf16 v[104:107], v[174:177], v[198:201], v[104:107]
	v_mfma_f32_16x16x32_bf16 v[96:99], v[182:185], v[198:201], v[96:99]
	v_mfma_f32_16x16x32_bf16 v[88:91], v[174:177], v[206:209], v[88:91]
	v_mfma_f32_16x16x32_bf16 v[80:83], v[182:185], v[206:209], v[80:83]
	v_mfma_f32_16x16x32_bf16 v[72:75], v[174:177], v[214:217], v[72:75]
	v_mfma_f32_16x16x32_bf16 v[64:67], v[182:185], v[214:217], v[64:67]
	s_barrier
; #define PG8_STAGE(bufoff, gbase, voff) do { _Pragma("unroll") for (int _i = 0; _i < 2; ++_i) \
;         __builtin_amdgcn_global_load_lds((const unsigned*)((const char*)(gbase) + (voff)[_i]), (PG8_LAS unsigned*)(lds + (bufoff) + ldsw + _i * 8192), 16, 0, 0); } while (0)
; #define PG8_LDA(dst, b, h) do { _Pragma("unroll") for (int m = 0; m < 4; ++m) _Pragma("unroll") for (int k = 0; k < 2; ++k) dst[m][k] = *(const PG8_LAS bf16x8*)(lds + PG8_SA(b, h) + aoff + m * 2048 + k * 1024); } while (0)
; #define PG8_MMA(ai, bj, At, Bt) do { __builtin_amdgcn_s_setprio(1); _Pragma("unroll") for (int m = 0; m < 4; ++m) _Pragma("unroll") for (int n = 0; n < 2; ++n) _Pragma("unroll") for (int k = 0; k < 2; ++k) \
;         acc[ai][bj][m][n] = __builtin_amdgcn_mfma_f32_16x16x32_bf16(Bt[n][k], At[m][k], acc[ai][bj][m][n], 0, 0, 0); __builtin_amdgcn_s_setprio(0); } while (0)
; #define PG8_WAIT_V(n) asm volatile("s_waitcnt vmcnt(" #n ")" ::: "memory")
; #define PG8_WAIT_L(n) asm volatile("s_waitcnt lgkmcnt(" #n ")" ::: "memory")
; #define PG8_BAR __builtin_amdgcn_s_barrier()
; #define PG8_SCHED __builtin_amdgcn_sched_barrier(0)
; template <class Epi, class Sched, bool ALIGN_EPI = false, bool SP2 = false>
; __device__ __forceinline__ void gemm_phase(PG8_LAS unsigned char* lds, const Gemm g, const Sched& S, const Epi& E) {
;     ...
;             PG8_LDA(At, 1, 1); PG8_STAGE(PG8_SB(1, 0), b3, voffB); PG8_STAGE(PG8_SB(1, 1), b3 + hstep, voffB); PG8_STAGE(PG8_SA(1, 0), a3, voffA);
;             PG8_WAIT_V(8); PG8_WAIT_L(0); PG8_BAR; PG8_MMA(1, 0, At, B0); PG8_MMA(1, 1, At, B1); PG8_BAR; PG8_SCHED;
;     ...
;         if constexpr (ALIGN_EPI) { if (wr == 0) PG8_BAR; }
	s_add_i32 s42, s69, s48
	v_lshl_add_u64 v[144:145], v[144:145], 0, s[14:15]
	s_mov_b32 m0, s42
	ds_read_b128 v[186:189], v151 offset:49152
	ds_read_b128 v[190:193], v151 offset:50176
	ds_read_b128 v[194:197], v151 offset:51200
	ds_read_b128 v[198:201], v151 offset:52224
	ds_read_b128 v[202:205], v151 offset:53248
	ds_read_b128 v[206:209], v151 offset:54272
	ds_read_b128 v[210:213], v151 offset:55296
	ds_read_b128 v[214:217], v151 offset:56320
	global_load_lds_dwordx4 v[144:145], off
	s_add_i32 m0, s42, 0x2000
	s_add_u32 s40, s40, 0x40080
	v_lshl_add_u64 v[144:145], v[218:219], 0, s[14:15]
	s_addc_u32 s41, s41, 0
	s_add_i32 s42, s70, s48
	global_load_lds_dwordx4 v[144:145], off
	v_lshl_add_u64 v[144:145], s[40:41], 0, v[132:133]
	s_mov_b32 m0, s42
	s_nop 0
	global_load_lds_dwordx4 v[144:145], off
	v_lshl_add_u64 v[144:145], s[40:41], 0, v[128:129]
	s_add_i32 m0, s42, 0x2000
	s_nop 0
	global_load_lds_dwordx4 v[144:145], off
	v_lshl_add_u64 v[144:145], v[220:221], 0, s[14:15]
	s_mov_b32 m0, s54
	s_nop 0
	global_load_lds_dwordx4 v[144:145], off
	v_lshl_add_u64 v[144:145], v[222:223], 0, s[14:15]
	s_mov_b32 m0, s55
	s_nop 0
	global_load_lds_dwordx4 v[144:145], off
	s_waitcnt vmcnt(8)
	s_waitcnt lgkmcnt(0)
	s_barrier
	v_mfma_f32_16x16x32_bf16 v[60:63], v[154:157], v[186:189], v[60:63]
	v_mfma_f32_16x16x32_bf16 v[52:55], v[162:165], v[186:189], v[52:55]
	v_mfma_f32_16x16x32_bf16 v[44:47], v[154:157], v[194:197], v[44:47]
	v_mfma_f32_16x16x32_bf16 v[36:39], v[162:165], v[194:197], v[36:39]
	v_mfma_f32_16x16x32_bf16 v[28:31], v[154:157], v[202:205], v[28:31]
	v_mfma_f32_16x16x32_bf16 v[20:23], v[162:165], v[202:205], v[20:23]
	v_mfma_f32_16x16x32_bf16 v[12:15], v[154:157], v[210:213], v[12:15]
	v_mfma_f32_16x16x32_bf16 v[4:7], v[162:165], v[210:213], v[4:7]
	v_mfma_f32_16x16x32_bf16 v[60:63], v[158:161], v[190:193], v[60:63]
	v_mfma_f32_16x16x32_bf16 v[52:55], v[166:169], v[190:193], v[52:55]
	v_mfma_f32_16x16x32_bf16 v[44:47], v[158:161], v[198:201], v[44:47]
	v_mfma_f32_16x16x32_bf16 v[36:39], v[166:169], v[198:201], v[36:39]
	v_mfma_f32_16x16x32_bf16 v[28:31], v[158:161], v[206:209], v[28:31]
	v_mfma_f32_16x16x32_bf16 v[20:23], v[166:169], v[206:209], v[20:23]
	v_mfma_f32_16x16x32_bf16 v[12:15], v[158:161], v[214:217], v[12:15]
	v_mfma_f32_16x16x32_bf16 v[4:7], v[166:169], v[214:217], v[4:7]
	v_mfma_f32_16x16x32_bf16 v[56:59], v[170:173], v[186:189], v[56:59]
	v_mfma_f32_16x16x32_bf16 v[48:51], v[178:181], v[186:189], v[48:51]
	v_mfma_f32_16x16x32_bf16 v[40:43], v[170:173], v[194:197], v[40:43]
	v_mfma_f32_16x16x32_bf16 v[32:35], v[178:181], v[194:197], v[32:35]
	v_mfma_f32_16x16x32_bf16 v[24:27], v[170:173], v[202:205], v[24:27]
	v_mfma_f32_16x16x32_bf16 v[16:19], v[178:181], v[202:205], v[16:19]
	v_mfma_f32_16x16x32_bf16 v[8:11], v[170:173], v[210:213], v[8:11]
	v_mfma_f32_16x16x32_bf16 v[0:3], v[178:181], v[210:213], v[0:3]
	v_mfma_f32_16x16x32_bf16 v[56:59], v[174:177], v[190:193], v[56:59]
	v_mfma_f32_16x16x32_bf16 v[48:51], v[182:185], v[190:193], v[48:51]
	v_mfma_f32_16x16x32_bf16 v[40:43], v[174:177], v[198:201], v[40:43]
	v_mfma_f32_16x16x32_bf16 v[32:35], v[182:185], v[198:201], v[32:35]
	v_mfma_f32_16x16x32_bf16 v[24:27], v[174:177], v[206:209], v[24:27]
	v_mfma_f32_16x16x32_bf16 v[16:19], v[182:185], v[206:209], v[16:19]
	v_mfma_f32_16x16x32_bf16 v[8:11], v[174:177], v[214:217], v[8:11]
	v_mfma_f32_16x16x32_bf16 v[0:3], v[182:185], v[214:217], v[0:3]
	s_barrier
	s_add_i32 s68, s68, 2
	s_add_u32 s38, s38, 0x100
	s_addc_u32 s39, s39, 0
	s_add_u32 s66, s66, 0x100
	s_addc_u32 s67, s67, 0
	s_cmp_gt_u32 s68, 13
	s_cbranch_scc0 .LBB0_232
	s_and_b64 vcc, exec, s[16:17]
	s_cbranch_vccz .LBB0_235
	s_barrier

; #define PG8_STAGE(bufoff, gbase, voff) do { _Pragma("unroll") for (int _i = 0; _i < 2; ++_i) \
;         __builtin_amdgcn_global_load_lds((const unsigned*)((const char*)(gbase) + (voff)[_i]), (PG8_LAS unsigned*)(lds + (bufoff) + ldsw + _i * 8192), 16, 0, 0); } while (0)
; #define PG8_LDA(dst, b, h) do { _Pragma("unroll") for (int m = 0; m < 4; ++m) _Pragma("unroll") for (int k = 0; k < 2; ++k) dst[m][k] = *(const PG8_LAS bf16x8*)(lds + PG8_SA(b, h) + aoff + m * 2048 + k * 1024); } while (0)
; #define PG8_LDB(dst, b, h) do { _Pragma("unroll") for (int n = 0; n < 2; ++n) _Pragma("unroll") for (int k = 0; k < 2; ++k) dst[n][k] = *(const PG8_LAS bf16x8*)(lds + PG8_SB(b, h) + boff + n * 2048 + k * 1024); } while (0)
; #define PG8_MMA(ai, bj, At, Bt) do { __builtin_amdgcn_s_setprio(1); _Pragma("unroll") for (int m = 0; m < 4; ++m) _Pragma("unroll") for (int n = 0; n < 2; ++n) _Pragma("unroll") for (int k = 0; k < 2; ++k) \
;         acc[ai][bj][m][n] = __builtin_amdgcn_mfma_f32_16x16x32_bf16(Bt[n][k], At[m][k], acc[ai][bj][m][n], 0, 0, 0); __builtin_amdgcn_s_setprio(0); } while (0)
; #define PG8_WAIT_V(n) asm volatile("s_waitcnt vmcnt(" #n ")" ::: "memory")
; #define PG8_WAIT_L(n) asm volatile("s_waitcnt lgkmcnt(" #n ")" ::: "memory")
; #define PG8_BAR __builtin_amdgcn_s_barrier()
; template <class Epi, class Sched, bool ALIGN_EPI = false, bool SP2 = false>
; __device__ __forceinline__ void gemm_phase(PG8_LAS unsigned char* lds, const Gemm g, const Sched& S, const Epi& E) {
;     ...
;             const char* a1 = cA + (size_t)(t + 1) * kstep;
;             const char* a2 = last ? nA : cA + (size_t)(t + 2) * kstep; const char* b2 = last ? nB : cB + (size_t)(t + 2) * kstep;
;             const char* a3 = a2 + kstep; const char* b3 = b2 + kstep;
;             if (last && has_next) S.a_ready(nxt);
;             if constexpr (SP2) {
;             PG8_LDB(B0, 0, 0); PG8_LDB(B1, 0, 1); PG8_SCHED; PG8_LDA(At, 0, 0); PG8_STAGE(PG8_SA(1, 1), a1 + hstep, voffA);
;             PG8_WAIT_V(8); PG8_WAIT_L(0); PG8_BAR; PG8_MMA(0, 0, At, B0); PG8_MMA(0, 1, At, B1); PG8_BAR; PG8_SCHED;
;             PG8_LDA(At, 0, 1); PG8_STAGE(PG8_SB(0, 0), b2, voffB); PG8_STAGE(PG8_SB(0, 1), b2 + hstep, voffB); PG8_STAGE(PG8_SA(0, 0), a2, voffA);
;             PG8_WAIT_V(8); PG8_WAIT_L(0); PG8_BAR; PG8_MMA(1, 0, At, B0); PG8_MMA(1, 1, At, B1); PG8_BAR; PG8_SCHED;
.LBB0_406:
	ds_read_b128 v[112:115], v246
	ds_read_b128 v[116:119], v246 offset:1024
	ds_read_b128 v[120:123], v246 offset:2048
	ds_read_b128 v[124:127], v246 offset:3072
	ds_read_b128 v[136:139], v247
	ds_read_b128 v[140:143], v247 offset:1024
	ds_read_b128 v[152:155], v247 offset:2048
	ds_read_b128 v[156:159], v247 offset:3072
	s_add_u32 s36, s34, 0xfff50080
	s_addc_u32 s37, s35, -1
	s_cmp_eq_u32 s64, 40
	s_cselect_b32 s39, s9, s37
	s_cselect_b32 s38, s8, s36
	s_cselect_b32 s37, s23, s63
	s_cselect_b32 s36, s22, s59
	v_lshl_add_u64 v[206:207], s[34:35], 0, v[200:201]
	s_add_i32 m0, s45, 0xc000
	ds_read_b128 v[160:163], v248
	ds_read_b128 v[164:167], v248 offset:1024
	ds_read_b128 v[168:171], v248 offset:2048
	ds_read_b128 v[172:175], v248 offset:3072
	ds_read_b128 v[176:179], v248 offset:4096
	ds_read_b128 v[180:183], v248 offset:5120
	ds_read_b128 v[184:187], v248 offset:6144
	ds_read_b128 v[188:191], v248 offset:7168
	global_load_lds_dwordx4 v[206:207], off
	v_lshl_add_u64 v[206:207], s[34:35], 0, v[202:203]
	s_add_i32 m0, s45, 0xe000
	s_nop 0
	global_load_lds_dwordx4 v[206:207], off
	s_waitcnt vmcnt(8)
	s_waitcnt lgkmcnt(0)
	s_barrier
	v_mfma_f32_16x16x32_bf16 v[148:151], v[112:115], v[160:163], v[148:151]
	v_mfma_f32_16x16x32_bf16 v[144:147], v[120:123], v[160:163], v[144:147]
	v_mfma_f32_16x16x32_bf16 v[108:111], v[112:115], v[168:171], v[108:111]
	v_mfma_f32_16x16x32_bf16 v[104:107], v[120:123], v[168:171], v[104:107]
	v_mfma_f32_16x16x32_bf16 v[92:95], v[112:115], v[176:179], v[92:95]
	v_mfma_f32_16x16x32_bf16 v[88:91], v[120:123], v[176:179], v[88:91]
	v_mfma_f32_16x16x32_bf16 v[76:79], v[112:115], v[184:187], v[76:79]
	v_mfma_f32_16x16x32_bf16 v[72:75], v[120:123], v[184:187], v[72:75]
	v_mfma_f32_16x16x32_bf16 v[148:151], v[116:119], v[164:167], v[148:151]
	v_mfma_f32_16x16x32_bf16 v[144:147], v[124:127], v[164:167], v[144:147]
	v_mfma_f32_16x16x32_bf16 v[108:111], v[116:119], v[172:175], v[108:111]
	v_mfma_f32_16x16x32_bf16 v[104:107], v[124:127], v[172:175], v[104:107]
	v_mfma_f32_16x16x32_bf16 v[92:95], v[116:119], v[180:183], v[92:95]
	v_mfma_f32_16x16x32_bf16 v[88:91], v[124:127], v[180:183], v[88:91]
	v_mfma_f32_16x16x32_bf16 v[76:79], v[116:119], v[188:191], v[76:79]
	v_mfma_f32_16x16x32_bf16 v[72:75], v[124:127], v[188:191], v[72:75]
	v_mfma_f32_16x16x32_bf16 v[132:135], v[136:139], v[160:163], v[132:135]
	v_mfma_f32_16x16x32_bf16 v[128:131], v[152:155], v[160:163], v[128:131]
	v_mfma_f32_16x16x32_bf16 v[100:103], v[136:139], v[168:171], v[100:103]
	v_mfma_f32_16x16x32_bf16 v[96:99], v[152:155], v[168:171], v[96:99]
	v_mfma_f32_16x16x32_bf16 v[84:87], v[136:139], v[176:179], v[84:87]
	v_mfma_f32_16x16x32_bf16 v[80:83], v[152:155], v[176:179], v[80:83]
	v_mfma_f32_16x16x32_bf16 v[68:71], v[136:139], v[184:187], v[68:71]
	v_mfma_f32_16x16x32_bf16 v[64:67], v[152:155], v[184:187], v[64:67]
	v_mfma_f32_16x16x32_bf16 v[132:135], v[140:143], v[164:167], v[132:135]
	v_mfma_f32_16x16x32_bf16 v[128:131], v[156:159], v[164:167], v[128:131]
	v_mfma_f32_16x16x32_bf16 v[100:103], v[140:143], v[172:175], v[100:103]
	v_mfma_f32_16x16x32_bf16 v[96:99], v[156:159], v[172:175], v[96:99]
	v_mfma_f32_16x16x32_bf16 v[84:87], v[140:143], v[180:183], v[84:87]
	v_mfma_f32_16x16x32_bf16 v[80:83], v[156:159], v[180:183], v[80:83]
	v_mfma_f32_16x16x32_bf16 v[68:71], v[140:143], v[188:191], v[68:71]
	v_mfma_f32_16x16x32_bf16 v[64:67], v[156:159], v[188:191], v[64:67]
	s_barrier
	s_add_i32 s65, s53, s44
	v_lshl_add_u64 v[206:207], s[36:37], 0, v[194:195]
	s_mov_b32 m0, s65
	ds_read_b128 v[160:163], v248 offset:16384
	ds_read_b128 v[164:167], v248 offset:17408
	ds_read_b128 v[168:171], v248 offset:18432
	ds_read_b128 v[172:175], v248 offset:19456
	ds_read_b128 v[176:179], v248 offset:20480
	ds_read_b128 v[180:183], v248 offset:21504
	ds_read_b128 v[184:187], v248 offset:22528
	ds_read_b128 v[188:191], v248 offset:23552
	global_load_lds_dwordx4 v[206:207], off
	s_add_i32 m0, s65, 0x2000
	s_add_u32 s66, s36, 0xb0000
	v_lshl_add_u64 v[208:209], s[36:37], 0, v[198:199]
	s_addc_u32 s67, s37, 0
	s_add_i32 s65, s54, s44
	global_load_lds_dwordx4 v[208:209], off
	v_lshl_add_u64 v[210:211], s[66:67], 0, v[194:195]
	s_mov_b32 m0, s65
	v_lshl_add_u64 v[212:213], s[38:39], 0, v[196:197]
	global_load_lds_dwordx4 v[210:211], off
	v_lshl_add_u64 v[210:211], s[66:67], 0, v[198:199]
	s_add_i32 m0, s65, 0x2000
	s_nop 0
	global_load_lds_dwordx4 v[210:211], off
	v_lshl_add_u64 v[210:211], s[38:39], 0, v[192:193]
	s_mov_b32 m0, s45
	s_nop 0
	global_load_lds_dwordx4 v[210:211], off
	s_mov_b32 m0, s46
	s_nop 0
	global_load_lds_dwordx4 v[212:213], off
	s_waitcnt vmcnt(8)
	s_waitcnt lgkmcnt(0)
	s_barrier
; #define PG8_STAGE(bufoff, gbase, voff) do { _Pragma("unroll") for (int _i = 0; _i < 2; ++_i) \
;         __builtin_amdgcn_global_load_lds((const unsigned*)((const char*)(gbase) + (voff)[_i]), (PG8_LAS unsigned*)(lds + (bufoff) + ldsw + _i * 8192), 16, 0, 0); } while (0)
; #define PG8_LDA(dst, b, h) do { _Pragma("unroll") for (int m = 0; m < 4; ++m) _Pragma("unroll") for (int k = 0; k < 2; ++k) dst[m][k] = *(const PG8_LAS bf16x8*)(lds + PG8_SA(b, h) + aoff + m * 2048 + k * 1024); } while (0)
; #define PG8_LDB(dst, b, h) do { _Pragma("unroll") for (int n = 0; n < 2; ++n) _Pragma("unroll") for (int k = 0; k < 2; ++k) dst[n][k] = *(const PG8_LAS bf16x8*)(lds + PG8_SB(b, h) + boff + n * 2048 + k * 1024); } while (0)
; #define PG8_MMA(ai, bj, At, Bt) do { __builtin_amdgcn_s_setprio(1); _Pragma("unroll") for (int m = 0; m < 4; ++m) _Pragma("unroll") for (int n = 0; n < 2; ++n) _Pragma("unroll") for (int k = 0; k < 2; ++k) \
;         acc[ai][bj][m][n] = __builtin_amdgcn_mfma_f32_16x16x32_bf16(Bt[n][k], At[m][k], acc[ai][bj][m][n], 0, 0, 0); __builtin_amdgcn_s_setprio(0); } while (0)
; #define PG8_WAIT_V(n) asm volatile("s_waitcnt vmcnt(" #n ")" ::: "memory")
; #define PG8_WAIT_L(n) asm volatile("s_waitcnt lgkmcnt(" #n ")" ::: "memory")
; #define PG8_BAR __builtin_amdgcn_s_barrier()
; #define PG8_SCHED __builtin_amdgcn_sched_barrier(0)
; template <class Epi, class Sched, bool ALIGN_EPI = false, bool SP2 = false>
; __device__ __forceinline__ void gemm_phase(PG8_LAS unsigned char* lds, const Gemm g, const Sched& S, const Epi& E) {
;     ...
;             PG8_WAIT_V(8); PG8_WAIT_L(0); PG8_BAR; PG8_MMA(1, 0, At, B0); PG8_MMA(1, 1, At, B1); PG8_BAR; PG8_SCHED;
;             PG8_LDB(B0, 1, 0); PG8_LDB(B1, 1, 1); PG8_SCHED; PG8_LDA(At, 1, 0); PG8_STAGE(PG8_SA(0, 1), a2 + hstep, voffA);
;             PG8_WAIT_V(8); PG8_WAIT_L(0); PG8_BAR; PG8_MMA(0, 0, At, B0); PG8_MMA(0, 1, At, B1); PG8_BAR; PG8_SCHED;
	v_mfma_f32_16x16x32_bf16 v[60:63], v[112:115], v[160:163], v[60:63]
	v_mfma_f32_16x16x32_bf16 v[56:59], v[120:123], v[160:163], v[56:59]
	v_mfma_f32_16x16x32_bf16 v[44:47], v[112:115], v[168:171], v[44:47]
	v_mfma_f32_16x16x32_bf16 v[40:43], v[120:123], v[168:171], v[40:43]
	v_mfma_f32_16x16x32_bf16 v[28:31], v[112:115], v[176:179], v[28:31]
	v_mfma_f32_16x16x32_bf16 v[24:27], v[120:123], v[176:179], v[24:27]
	v_mfma_f32_16x16x32_bf16 v[12:15], v[112:115], v[184:187], v[12:15]
	v_mfma_f32_16x16x32_bf16 v[8:11], v[120:123], v[184:187], v[8:11]
	v_mfma_f32_16x16x32_bf16 v[60:63], v[116:119], v[164:167], v[60:63]
	v_mfma_f32_16x16x32_bf16 v[56:59], v[124:127], v[164:167], v[56:59]
	v_mfma_f32_16x16x32_bf16 v[44:47], v[116:119], v[172:175], v[44:47]
	v_mfma_f32_16x16x32_bf16 v[40:43], v[124:127], v[172:175], v[40:43]
	v_mfma_f32_16x16x32_bf16 v[28:31], v[116:119], v[180:183], v[28:31]
	v_mfma_f32_16x16x32_bf16 v[24:27], v[124:127], v[180:183], v[24:27]
	v_mfma_f32_16x16x32_bf16 v[12:15], v[116:119], v[188:191], v[12:15]
	v_mfma_f32_16x16x32_bf16 v[8:11], v[124:127], v[188:191], v[8:11]
	v_mfma_f32_16x16x32_bf16 v[52:55], v[136:139], v[160:163], v[52:55]
	v_mfma_f32_16x16x32_bf16 v[48:51], v[152:155], v[160:163], v[48:51]
	v_mfma_f32_16x16x32_bf16 v[36:39], v[136:139], v[168:171], v[36:39]
	v_mfma_f32_16x16x32_bf16 v[32:35], v[152:155], v[168:171], v[32:35]
	v_mfma_f32_16x16x32_bf16 v[20:23], v[136:139], v[176:179], v[20:23]
	v_mfma_f32_16x16x32_bf16 v[16:19], v[152:155], v[176:179], v[16:19]
	v_mfma_f32_16x16x32_bf16 v[4:7], v[136:139], v[184:187], v[4:7]
	v_mfma_f32_16x16x32_bf16 v[0:3], v[152:155], v[184:187], v[0:3]
	v_mfma_f32_16x16x32_bf16 v[52:55], v[140:143], v[164:167], v[52:55]
	v_mfma_f32_16x16x32_bf16 v[48:51], v[156:159], v[164:167], v[48:51]
	v_mfma_f32_16x16x32_bf16 v[36:39], v[140:143], v[172:175], v[36:39]
	v_mfma_f32_16x16x32_bf16 v[32:35], v[156:159], v[172:175], v[32:35]
	v_mfma_f32_16x16x32_bf16 v[20:23], v[140:143], v[180:183], v[20:23]
	v_mfma_f32_16x16x32_bf16 v[16:19], v[156:159], v[180:183], v[16:19]
	v_mfma_f32_16x16x32_bf16 v[4:7], v[140:143], v[188:191], v[4:7]
	v_mfma_f32_16x16x32_bf16 v[0:3], v[156:159], v[188:191], v[0:3]
	s_barrier
	s_add_i32 s65, 0, 0x18000
	s_add_i32 s66, 0, 0x1c000
	v_add_u32_e32 v124, s65, v244
	v_add_u32_e32 v156, s66, v244
	ds_read_b128 v[112:115], v124
	ds_read_b128 v[116:119], v124 offset:1024
	ds_read_b128 v[120:123], v124 offset:2048
	ds_read_b128 v[124:127], v124 offset:3072
	ds_read_b128 v[136:139], v156
	ds_read_b128 v[140:143], v156 offset:1024
	ds_read_b128 v[152:155], v156 offset:2048
	ds_read_b128 v[156:159], v156 offset:3072
	s_add_u32 s38, s38, 0xb0000
	s_addc_u32 s39, s39, 0
	s_mov_b32 m0, s47
	v_lshl_add_u64 v[214:215], s[38:39], 0, v[192:193]
	ds_read_b128 v[160:163], v248 offset:32768
	ds_read_b128 v[164:167], v248 offset:33792
	ds_read_b128 v[168:171], v248 offset:34816
	ds_read_b128 v[172:175], v248 offset:35840
	ds_read_b128 v[176:179], v248 offset:36864
	ds_read_b128 v[180:183], v248 offset:37888
	ds_read_b128 v[184:187], v248 offset:38912
	ds_read_b128 v[188:191], v248 offset:39936
	global_load_lds_dwordx4 v[214:215], off
	v_lshl_add_u64 v[214:215], s[38:39], 0, v[196:197]
	s_mov_b32 m0, s48
	s_nop 0
	global_load_lds_dwordx4 v[214:215], off
	s_waitcnt vmcnt(8)
	s_waitcnt lgkmcnt(0)
	s_barrier
	v_mfma_f32_16x16x32_bf16 v[148:151], v[112:115], v[160:163], v[148:151]
	v_mfma_f32_16x16x32_bf16 v[144:147], v[120:123], v[160:163], v[144:147]
	v_mfma_f32_16x16x32_bf16 v[108:111], v[112:115], v[168:171], v[108:111]
	v_mfma_f32_16x16x32_bf16 v[104:107], v[120:123], v[168:171], v[104:107]
	v_mfma_f32_16x16x32_bf16 v[92:95], v[112:115], v[176:179], v[92:95]
	v_mfma_f32_16x16x32_bf16 v[88:91], v[120:123], v[176:179], v[88:91]
	v_mfma_f32_16x16x32_bf16 v[76:79], v[112:115], v[184:187], v[76:79]
	v_mfma_f32_16x16x32_bf16 v[72:75], v[120:123], v[184:187], v[72:75]
	v_mfma_f32_16x16x32_bf16 v[148:151], v[116:119], v[164:167], v[148:151]
	v_mfma_f32_16x16x32_bf16 v[144:147], v[124:127], v[164:167], v[144:147]
	v_mfma_f32_16x16x32_bf16 v[108:111], v[116:119], v[172:175], v[108:111]
	v_mfma_f32_16x16x32_bf16 v[104:107], v[124:127], v[172:175], v[104:107]
	v_mfma_f32_16x16x32_bf16 v[92:95], v[116:119], v[180:183], v[92:95]
	v_mfma_f32_16x16x32_bf16 v[88:91], v[124:127], v[180:183], v[88:91]
	v_mfma_f32_16x16x32_bf16 v[76:79], v[116:119], v[188:191], v[76:79]
	v_mfma_f32_16x16x32_bf16 v[72:75], v[124:127], v[188:191], v[72:75]
	v_mfma_f32_16x16x32_bf16 v[132:135], v[136:139], v[160:163], v[132:135]
	v_mfma_f32_16x16x32_bf16 v[128:131], v[152:155], v[160:163], v[128:131]
	v_mfma_f32_16x16x32_bf16 v[100:103], v[136:139], v[168:171], v[100:103]
	v_mfma_f32_16x16x32_bf16 v[96:99], v[152:155], v[168:171], v[96:99]
	v_mfma_f32_16x16x32_bf16 v[84:87], v[136:139], v[176:179], v[84:87]
	v_mfma_f32_16x16x32_bf16 v[80:83], v[152:155], v[176:179], v[80:83]
	v_mfma_f32_16x16x32_bf16 v[68:71], v[136:139], v[184:187], v[68:71]
	v_mfma_f32_16x16x32_bf16 v[64:67], v[152:155], v[184:187], v[64:67]
	v_mfma_f32_16x16x32_bf16 v[132:135], v[140:143], v[164:167], v[132:135]
	v_mfma_f32_16x16x32_bf16 v[128:131], v[156:159], v[164:167], v[128:131]
	v_mfma_f32_16x16x32_bf16 v[100:103], v[140:143], v[172:175], v[100:103]
	v_mfma_f32_16x16x32_bf16 v[96:99], v[156:159], v[172:175], v[96:99]
	v_mfma_f32_16x16x32_bf16 v[84:87], v[140:143], v[180:183], v[84:87]
	v_mfma_f32_16x16x32_bf16 v[80:83], v[156:159], v[180:183], v[80:83]
	v_mfma_f32_16x16x32_bf16 v[68:71], v[140:143], v[188:191], v[68:71]
	v_mfma_f32_16x16x32_bf16 v[64:67], v[156:159], v[188:191], v[64:67]
	s_barrier
; #define PG8_STAGE(bufoff, gbase, voff) do { _Pragma("unroll") for (int _i = 0; _i < 2; ++_i) \
;         __builtin_amdgcn_global_load_lds((const unsigned*)((const char*)(gbase) + (voff)[_i]), (PG8_LAS unsigned*)(lds + (bufoff) + ldsw + _i * 8192), 16, 0, 0); } while (0)
; #define PG8_LDA(dst, b, h) do { _Pragma("unroll") for (int m = 0; m < 4; ++m) _Pragma("unroll") for (int k = 0; k < 2; ++k) dst[m][k] = *(const PG8_LAS bf16x8*)(lds + PG8_SA(b, h) + aoff + m * 2048 + k * 1024); } while (0)
; #define PG8_MMA(ai, bj, At, Bt) do { __builtin_amdgcn_s_setprio(1); _Pragma("unroll") for (int m = 0; m < 4; ++m) _Pragma("unroll") for (int n = 0; n < 2; ++n) _Pragma("unroll") for (int k = 0; k < 2; ++k) \
;         acc[ai][bj][m][n] = __builtin_amdgcn_mfma_f32_16x16x32_bf16(Bt[n][k], At[m][k], acc[ai][bj][m][n], 0, 0, 0); __builtin_amdgcn_s_setprio(0); } while (0)
; #define PG8_WAIT_V(n) asm volatile("s_waitcnt vmcnt(" #n ")" ::: "memory")
; #define PG8_WAIT_L(n) asm volatile("s_waitcnt lgkmcnt(" #n ")" ::: "memory")
; #define PG8_BAR __builtin_amdgcn_s_barrier()
; #define PG8_SCHED __builtin_amdgcn_sched_barrier(0)
; template <class Epi, class Sched, bool ALIGN_EPI = false, bool SP2 = false>
; __device__ __forceinline__ void gemm_phase(PG8_LAS unsigned char* lds, const Gemm g, const Sched& S, const Epi& E) {
;     ...
;             PG8_LDA(At, 1, 1); PG8_STAGE(PG8_SB(1, 0), b3, voffB); PG8_STAGE(PG8_SB(1, 1), b3 + hstep, voffB); PG8_STAGE(PG8_SA(1, 0), a3, voffA);
;             PG8_WAIT_V(8); PG8_WAIT_L(0); PG8_BAR; PG8_MMA(1, 0, At, B0); PG8_MMA(1, 1, At, B1); PG8_BAR; PG8_SCHED;
;     ...
;         if constexpr (ALIGN_EPI) { if (wr == 0) PG8_BAR; }
	s_add_i32 s38, s65, s44
	v_lshl_add_u64 v[206:207], v[206:207], 0, s[18:19]
	s_mov_b32 m0, s38
	ds_read_b128 v[160:163], v248 offset:49152
	ds_read_b128 v[164:167], v248 offset:50176
	ds_read_b128 v[168:171], v248 offset:51200
	ds_read_b128 v[172:175], v248 offset:52224
	ds_read_b128 v[176:179], v248 offset:53248
	ds_read_b128 v[180:183], v248 offset:54272
	ds_read_b128 v[184:187], v248 offset:55296
	ds_read_b128 v[188:191], v248 offset:56320
	global_load_lds_dwordx4 v[206:207], off
	s_add_i32 m0, s38, 0x2000
	s_add_u32 s36, s36, 0xb0080
	v_lshl_add_u64 v[206:207], v[208:209], 0, s[18:19]
	s_addc_u32 s37, s37, 0
	s_add_i32 s38, s66, s44
	global_load_lds_dwordx4 v[206:207], off
	v_lshl_add_u64 v[206:207], s[36:37], 0, v[194:195]
	s_mov_b32 m0, s38
	s_nop 0
	global_load_lds_dwordx4 v[206:207], off
	v_lshl_add_u64 v[206:207], s[36:37], 0, v[198:199]
	s_add_i32 m0, s38, 0x2000
	s_nop 0
	global_load_lds_dwordx4 v[206:207], off
	v_lshl_add_u64 v[206:207], v[210:211], 0, s[18:19]
	s_mov_b32 m0, s50
	s_nop 0
	global_load_lds_dwordx4 v[206:207], off
	v_lshl_add_u64 v[206:207], v[212:213], 0, s[18:19]
	s_mov_b32 m0, s51
	s_nop 0
	global_load_lds_dwordx4 v[206:207], off
	s_waitcnt vmcnt(8)
	s_waitcnt lgkmcnt(0)
	s_barrier
	v_mfma_f32_16x16x32_bf16 v[60:63], v[112:115], v[160:163], v[60:63]
	v_mfma_f32_16x16x32_bf16 v[56:59], v[120:123], v[160:163], v[56:59]
	v_mfma_f32_16x16x32_bf16 v[44:47], v[112:115], v[168:171], v[44:47]
	v_mfma_f32_16x16x32_bf16 v[40:43], v[120:123], v[168:171], v[40:43]
	v_mfma_f32_16x16x32_bf16 v[28:31], v[112:115], v[176:179], v[28:31]
	v_mfma_f32_16x16x32_bf16 v[24:27], v[120:123], v[176:179], v[24:27]
	v_mfma_f32_16x16x32_bf16 v[12:15], v[112:115], v[184:187], v[12:15]
	v_mfma_f32_16x16x32_bf16 v[8:11], v[120:123], v[184:187], v[8:11]
	v_mfma_f32_16x16x32_bf16 v[60:63], v[116:119], v[164:167], v[60:63]
	v_mfma_f32_16x16x32_bf16 v[56:59], v[124:127], v[164:167], v[56:59]
	v_mfma_f32_16x16x32_bf16 v[44:47], v[116:119], v[172:175], v[44:47]
	v_mfma_f32_16x16x32_bf16 v[40:43], v[124:127], v[172:175], v[40:43]
	v_mfma_f32_16x16x32_bf16 v[28:31], v[116:119], v[180:183], v[28:31]
	v_mfma_f32_16x16x32_bf16 v[24:27], v[124:127], v[180:183], v[24:27]
	v_mfma_f32_16x16x32_bf16 v[12:15], v[116:119], v[188:191], v[12:15]
	v_mfma_f32_16x16x32_bf16 v[8:11], v[124:127], v[188:191], v[8:11]
	v_mfma_f32_16x16x32_bf16 v[52:55], v[136:139], v[160:163], v[52:55]
	v_mfma_f32_16x16x32_bf16 v[48:51], v[152:155], v[160:163], v[48:51]
	v_mfma_f32_16x16x32_bf16 v[36:39], v[136:139], v[168:171], v[36:39]
	v_mfma_f32_16x16x32_bf16 v[32:35], v[152:155], v[168:171], v[32:35]
	v_mfma_f32_16x16x32_bf16 v[20:23], v[136:139], v[176:179], v[20:23]
	v_mfma_f32_16x16x32_bf16 v[16:19], v[152:155], v[176:179], v[16:19]
	v_mfma_f32_16x16x32_bf16 v[4:7], v[136:139], v[184:187], v[4:7]
	v_mfma_f32_16x16x32_bf16 v[0:3], v[152:155], v[184:187], v[0:3]
	v_mfma_f32_16x16x32_bf16 v[52:55], v[140:143], v[164:167], v[52:55]
	v_mfma_f32_16x16x32_bf16 v[48:51], v[156:159], v[164:167], v[48:51]
	v_mfma_f32_16x16x32_bf16 v[36:39], v[140:143], v[172:175], v[36:39]
	v_mfma_f32_16x16x32_bf16 v[32:35], v[156:159], v[172:175], v[32:35]
	v_mfma_f32_16x16x32_bf16 v[20:23], v[140:143], v[180:183], v[20:23]
	v_mfma_f32_16x16x32_bf16 v[16:19], v[156:159], v[180:183], v[16:19]
	v_mfma_f32_16x16x32_bf16 v[4:7], v[140:143], v[188:191], v[4:7]
	v_mfma_f32_16x16x32_bf16 v[0:3], v[156:159], v[188:191], v[0:3]
	s_barrier
	s_add_i32 s64, s64, 2
	s_add_u32 s34, s34, 0x100
	s_addc_u32 s35, s35, 0
	s_add_u32 s59, s59, 0x100
	s_addc_u32 s63, s63, 0
	s_cmp_gt_u32 s64, 41
	s_cbranch_scc0 .LBB0_406
	s_and_b64 vcc, exec, s[20:21]
	s_cbranch_vccz .LBB0_409
	s_barrier

; #define PG8_STAGE(bufoff, gbase, voff) do { _Pragma("unroll") for (int _i = 0; _i < 2; ++_i) \
;         __builtin_amdgcn_global_load_lds((const unsigned*)((const char*)(gbase) + (voff)[_i]), (PG8_LAS unsigned*)(lds + (bufoff) + ldsw + _i * 8192), 16, 0, 0); } while (0)
; #define PG8_LDA(dst, b, h) do { _Pragma("unroll") for (int m = 0; m < 4; ++m) _Pragma("unroll") for (int k = 0; k < 2; ++k) dst[m][k] = *(const PG8_LAS bf16x8*)(lds + PG8_SA(b, h) + aoff + m * 2048 + k * 1024); } while (0)
; #define PG8_LDB(dst, b, h) do { _Pragma("unroll") for (int n = 0; n < 2; ++n) _Pragma("unroll") for (int k = 0; k < 2; ++k) dst[n][k] = *(const PG8_LAS bf16x8*)(lds + PG8_SB(b, h) + boff + n * 2048 + k * 1024); } while (0)
; #define PG8_MMA(ai, bj, At, Bt) do { __builtin_amdgcn_s_setprio(1); _Pragma("unroll") for (int m = 0; m < 4; ++m) _Pragma("unroll") for (int n = 0; n < 2; ++n) _Pragma("unroll") for (int k = 0; k < 2; ++k) \
;         acc[ai][bj][m][n] = __builtin_amdgcn_mfma_f32_16x16x32_bf16(Bt[n][k], At[m][k], acc[ai][bj][m][n], 0, 0, 0); __builtin_amdgcn_s_setprio(0); } while (0)
; template <class Epi, class Sched, bool ALIGN_EPI = false, bool SP2 = false>
; __device__ __forceinline__ void gemm_phase(PG8_LAS unsigned char* lds, const Gemm g, const Sched& S, const Epi& E) {
;     ...
;         for (int t = 0; t < nt; t += 2) {
;             const bool last = (t == nt - 2);
;             if constexpr (Epi::PREFETCH) { if (t == nt - 4) E.prefetch(cur, lds + STAGE_BYTES + 1024, tid); }
;             const char* a1 = cA + (size_t)(t + 1) * kstep;
;             const char* a2 = last ? nA : cA + (size_t)(t + 2) * kstep; const char* b2 = last ? nB : cB + (size_t)(t + 2) * kstep;
;             const char* a3 = a2 + kstep; const char* b3 = b2 + kstep;
;             if (last && has_next) S.a_ready(nxt);
;             if constexpr (SP2) {
;             PG8_LDB(B0, 0, 0); PG8_LDB(B1, 0, 1); PG8_SCHED; PG8_LDA(At, 0, 0); PG8_STAGE(PG8_SA(1, 1), a1 + hstep, voffA);
;             PG8_WAIT_V(8); PG8_WAIT_L(0); PG8_BAR; PG8_MMA(0, 0, At, B0); PG8_MMA(0, 1, At, B1); PG8_BAR; PG8_SCHED;
;             PG8_LDA(At, 0, 1); PG8_STAGE(PG8_SB(0, 0), b2, voffB); PG8_STAGE(PG8_SB(0, 1), b2 + hstep, voffB); PG8_STAGE(PG8_SA(0, 0), a2, voffA);
;             PG8_WAIT_V(8); PG8_WAIT_L(0); PG8_BAR; PG8_MMA(1, 0, At, B0); PG8_MMA(1, 1, At, B1); PG8_BAR; PG8_SCHED;
.LBB0_593:
	ds_read_b128 v[144:147], v151
	ds_read_b128 v[156:159], v151 offset:1024
	ds_read_b128 v[160:163], v151 offset:2048
	ds_read_b128 v[164:167], v151 offset:3072
	ds_read_b128 v[168:171], v152
	ds_read_b128 v[172:175], v152 offset:1024
	ds_read_b128 v[176:179], v152 offset:2048
	ds_read_b128 v[180:183], v152 offset:3072
	s_add_u32 s46, s44, 0xfffc0080
	s_addc_u32 s47, s45, -1
	s_cmp_eq_u32 s80, 12
	s_cselect_b32 s49, s37, s47
	s_cselect_b32 s48, s76, s46
	s_cselect_b32 s47, s35, s79
	s_cselect_b32 s46, s77, s78
	v_lshl_add_u64 v[216:217], s[44:45], 0, v[136:137]
	s_add_i32 m0, s43, 0xc000
	ds_read_b128 v[184:187], v153
	ds_read_b128 v[188:191], v153 offset:1024
	ds_read_b128 v[192:195], v153 offset:2048
	ds_read_b128 v[196:199], v153 offset:3072
	ds_read_b128 v[200:203], v153 offset:4096
	ds_read_b128 v[204:207], v153 offset:5120
	ds_read_b128 v[208:211], v153 offset:6144
	ds_read_b128 v[212:215], v153 offset:7168
	global_load_lds_dwordx4 v[216:217], off
	v_lshl_add_u64 v[216:217], s[44:45], 0, v[138:139]
	s_add_i32 m0, s43, 0xe000
	s_nop 0
	global_load_lds_dwordx4 v[216:217], off
	s_waitcnt vmcnt(8)
	s_waitcnt lgkmcnt(0)
	s_barrier
	v_mfma_f32_16x16x32_bf16 v[124:127], v[144:147], v[184:187], v[124:127]
	v_mfma_f32_16x16x32_bf16 v[120:123], v[160:163], v[184:187], v[120:123]
	v_mfma_f32_16x16x32_bf16 v[108:111], v[144:147], v[192:195], v[108:111]
	v_mfma_f32_16x16x32_bf16 v[104:107], v[160:163], v[192:195], v[104:107]
	v_mfma_f32_16x16x32_bf16 v[92:95], v[144:147], v[200:203], v[92:95]
	v_mfma_f32_16x16x32_bf16 v[88:91], v[160:163], v[200:203], v[88:91]
	v_mfma_f32_16x16x32_bf16 v[76:79], v[144:147], v[208:211], v[76:79]
	v_mfma_f32_16x16x32_bf16 v[72:75], v[160:163], v[208:211], v[72:75]
	v_mfma_f32_16x16x32_bf16 v[124:127], v[156:159], v[188:191], v[124:127]
	v_mfma_f32_16x16x32_bf16 v[120:123], v[164:167], v[188:191], v[120:123]
	v_mfma_f32_16x16x32_bf16 v[108:111], v[156:159], v[196:199], v[108:111]
	v_mfma_f32_16x16x32_bf16 v[104:107], v[164:167], v[196:199], v[104:107]
	v_mfma_f32_16x16x32_bf16 v[92:95], v[156:159], v[204:207], v[92:95]
	v_mfma_f32_16x16x32_bf16 v[88:91], v[164:167], v[204:207], v[88:91]
	v_mfma_f32_16x16x32_bf16 v[76:79], v[156:159], v[212:215], v[76:79]
	v_mfma_f32_16x16x32_bf16 v[72:75], v[164:167], v[212:215], v[72:75]
	v_mfma_f32_16x16x32_bf16 v[116:119], v[168:171], v[184:187], v[116:119]
	v_mfma_f32_16x16x32_bf16 v[112:115], v[176:179], v[184:187], v[112:115]
	v_mfma_f32_16x16x32_bf16 v[100:103], v[168:171], v[192:195], v[100:103]
	v_mfma_f32_16x16x32_bf16 v[96:99], v[176:179], v[192:195], v[96:99]
	v_mfma_f32_16x16x32_bf16 v[84:87], v[168:171], v[200:203], v[84:87]
	v_mfma_f32_16x16x32_bf16 v[80:83], v[176:179], v[200:203], v[80:83]
	v_mfma_f32_16x16x32_bf16 v[68:71], v[168:171], v[208:211], v[68:71]
	v_mfma_f32_16x16x32_bf16 v[64:67], v[176:179], v[208:211], v[64:67]
	v_mfma_f32_16x16x32_bf16 v[116:119], v[172:175], v[188:191], v[116:119]
	v_mfma_f32_16x16x32_bf16 v[112:115], v[180:183], v[188:191], v[112:115]
	v_mfma_f32_16x16x32_bf16 v[100:103], v[172:175], v[196:199], v[100:103]
	v_mfma_f32_16x16x32_bf16 v[96:99], v[180:183], v[196:199], v[96:99]
	v_mfma_f32_16x16x32_bf16 v[84:87], v[172:175], v[204:207], v[84:87]
	v_mfma_f32_16x16x32_bf16 v[80:83], v[180:183], v[204:207], v[80:83]
	v_mfma_f32_16x16x32_bf16 v[68:71], v[172:175], v[212:215], v[68:71]
	v_mfma_f32_16x16x32_bf16 v[64:67], v[180:183], v[212:215], v[64:67]
	s_barrier
	s_add_i32 s81, s69, s52
	v_lshl_add_u64 v[216:217], s[46:47], 0, v[132:133]
	s_mov_b32 m0, s81
	ds_read_b128 v[184:187], v153 offset:16384
	ds_read_b128 v[188:191], v153 offset:17408
	ds_read_b128 v[192:195], v153 offset:18432
	ds_read_b128 v[196:199], v153 offset:19456
	ds_read_b128 v[200:203], v153 offset:20480
	ds_read_b128 v[204:207], v153 offset:21504
	ds_read_b128 v[208:211], v153 offset:22528
	ds_read_b128 v[212:215], v153 offset:23552
	global_load_lds_dwordx4 v[216:217], off
	s_add_i32 m0, s81, 0x2000
	s_add_u32 s82, s46, 0x40000
	v_lshl_add_u64 v[218:219], s[46:47], 0, v[128:129]
	s_addc_u32 s83, s47, 0
	s_add_i32 s81, s70, s52
	global_load_lds_dwordx4 v[218:219], off
	v_lshl_add_u64 v[220:221], s[82:83], 0, v[132:133]
	s_mov_b32 m0, s81
	v_lshl_add_u64 v[222:223], s[48:49], 0, v[130:131]
	global_load_lds_dwordx4 v[220:221], off
	v_lshl_add_u64 v[220:221], s[82:83], 0, v[128:129]
	s_add_i32 m0, s81, 0x2000
	s_nop 0
	global_load_lds_dwordx4 v[220:221], off
	v_lshl_add_u64 v[220:221], s[48:49], 0, v[134:135]
	s_mov_b32 m0, s43
	s_nop 0
	global_load_lds_dwordx4 v[220:221], off
	s_mov_b32 m0, s56
	s_nop 0
	global_load_lds_dwordx4 v[222:223], off
	s_waitcnt vmcnt(8)
	s_waitcnt lgkmcnt(0)
	s_barrier
; #define PG8_STAGE(bufoff, gbase, voff) do { _Pragma("unroll") for (int _i = 0; _i < 2; ++_i) \
;         __builtin_amdgcn_global_load_lds((const unsigned*)((const char*)(gbase) + (voff)[_i]), (PG8_LAS unsigned*)(lds + (bufoff) + ldsw + _i * 8192), 16, 0, 0); } while (0)
; #define PG8_LDA(dst, b, h) do { _Pragma("unroll") for (int m = 0; m < 4; ++m) _Pragma("unroll") for (int k = 0; k < 2; ++k) dst[m][k] = *(const PG8_LAS bf16x8*)(lds + PG8_SA(b, h) + aoff + m * 2048 + k * 1024); } while (0)
; #define PG8_LDB(dst, b, h) do { _Pragma("unroll") for (int n = 0; n < 2; ++n) _Pragma("unroll") for (int k = 0; k < 2; ++k) dst[n][k] = *(const PG8_LAS bf16x8*)(lds + PG8_SB(b, h) + boff + n * 2048 + k * 1024); } while (0)
; #define PG8_MMA(ai, bj, At, Bt) do { __builtin_amdgcn_s_setprio(1); _Pragma("unroll") for (int m = 0; m < 4; ++m) _Pragma("unroll") for (int n = 0; n < 2; ++n) _Pragma("unroll") for (int k = 0; k < 2; ++k) \
;         acc[ai][bj][m][n] = __builtin_amdgcn_mfma_f32_16x16x32_bf16(Bt[n][k], At[m][k], acc[ai][bj][m][n], 0, 0, 0); __builtin_amdgcn_s_setprio(0); } while (0)
; #define PG8_WAIT_V(n) asm volatile("s_waitcnt vmcnt(" #n ")" ::: "memory")
; #define PG8_WAIT_L(n) asm volatile("s_waitcnt lgkmcnt(" #n ")" ::: "memory")
; #define PG8_BAR __builtin_amdgcn_s_barrier()
; #define PG8_SCHED __builtin_amdgcn_sched_barrier(0)
; template <class Epi, class Sched, bool ALIGN_EPI = false, bool SP2 = false>
; __device__ __forceinline__ void gemm_phase(PG8_LAS unsigned char* lds, const Gemm g, const Sched& S, const Epi& E) {
;     ...
;             PG8_WAIT_V(8); PG8_WAIT_L(0); PG8_BAR; PG8_MMA(1, 0, At, B0); PG8_MMA(1, 1, At, B1); PG8_BAR; PG8_SCHED;
;             PG8_LDB(B0, 1, 0); PG8_LDB(B1, 1, 1); PG8_SCHED; PG8_LDA(At, 1, 0); PG8_STAGE(PG8_SA(0, 1), a2 + hstep, voffA);
;             PG8_WAIT_V(8); PG8_WAIT_L(0); PG8_BAR; PG8_MMA(0, 0, At, B0); PG8_MMA(0, 1, At, B1); PG8_BAR; PG8_SCHED;
	v_mfma_f32_16x16x32_bf16 v[60:63], v[144:147], v[184:187], v[60:63]
	v_mfma_f32_16x16x32_bf16 v[56:59], v[160:163], v[184:187], v[56:59]
	v_mfma_f32_16x16x32_bf16 v[44:47], v[144:147], v[192:195], v[44:47]
	v_mfma_f32_16x16x32_bf16 v[40:43], v[160:163], v[192:195], v[40:43]
	v_mfma_f32_16x16x32_bf16 v[28:31], v[144:147], v[200:203], v[28:31]
	v_mfma_f32_16x16x32_bf16 v[24:27], v[160:163], v[200:203], v[24:27]
	v_mfma_f32_16x16x32_bf16 v[12:15], v[144:147], v[208:211], v[12:15]
	v_mfma_f32_16x16x32_bf16 v[8:11], v[160:163], v[208:211], v[8:11]
	v_mfma_f32_16x16x32_bf16 v[60:63], v[156:159], v[188:191], v[60:63]
	v_mfma_f32_16x16x32_bf16 v[56:59], v[164:167], v[188:191], v[56:59]
	v_mfma_f32_16x16x32_bf16 v[44:47], v[156:159], v[196:199], v[44:47]
	v_mfma_f32_16x16x32_bf16 v[40:43], v[164:167], v[196:199], v[40:43]
	v_mfma_f32_16x16x32_bf16 v[28:31], v[156:159], v[204:207], v[28:31]
	v_mfma_f32_16x16x32_bf16 v[24:27], v[164:167], v[204:207], v[24:27]
	v_mfma_f32_16x16x32_bf16 v[12:15], v[156:159], v[212:215], v[12:15]
	v_mfma_f32_16x16x32_bf16 v[8:11], v[164:167], v[212:215], v[8:11]
	v_mfma_f32_16x16x32_bf16 v[52:55], v[168:171], v[184:187], v[52:55]
	v_mfma_f32_16x16x32_bf16 v[48:51], v[176:179], v[184:187], v[48:51]
	v_mfma_f32_16x16x32_bf16 v[36:39], v[168:171], v[192:195], v[36:39]
	v_mfma_f32_16x16x32_bf16 v[32:35], v[176:179], v[192:195], v[32:35]
	v_mfma_f32_16x16x32_bf16 v[20:23], v[168:171], v[200:203], v[20:23]
	v_mfma_f32_16x16x32_bf16 v[16:19], v[176:179], v[200:203], v[16:19]
	v_mfma_f32_16x16x32_bf16 v[4:7], v[168:171], v[208:211], v[4:7]
	v_mfma_f32_16x16x32_bf16 v[0:3], v[176:179], v[208:211], v[0:3]
	v_mfma_f32_16x16x32_bf16 v[52:55], v[172:175], v[188:191], v[52:55]
	v_mfma_f32_16x16x32_bf16 v[48:51], v[180:183], v[188:191], v[48:51]
	v_mfma_f32_16x16x32_bf16 v[36:39], v[172:175], v[196:199], v[36:39]
	v_mfma_f32_16x16x32_bf16 v[32:35], v[180:183], v[196:199], v[32:35]
	v_mfma_f32_16x16x32_bf16 v[20:23], v[172:175], v[204:207], v[20:23]
	v_mfma_f32_16x16x32_bf16 v[16:19], v[180:183], v[204:207], v[16:19]
	v_mfma_f32_16x16x32_bf16 v[4:7], v[172:175], v[212:215], v[4:7]
	v_mfma_f32_16x16x32_bf16 v[0:3], v[180:183], v[212:215], v[0:3]
	s_barrier
	s_add_i32 s81, 0, 0x18000
	s_add_i32 s82, 0, 0x1c000
	v_add_u32_e32 v164, s81, v149
	v_add_u32_e32 v180, s82, v149
	ds_read_b128 v[144:147], v164
	ds_read_b128 v[156:159], v164 offset:1024
	ds_read_b128 v[160:163], v164 offset:2048
	ds_read_b128 v[164:167], v164 offset:3072
	ds_read_b128 v[168:171], v180
	ds_read_b128 v[172:175], v180 offset:1024
	ds_read_b128 v[176:179], v180 offset:2048
	ds_read_b128 v[180:183], v180 offset:3072
	s_add_u32 s48, s48, 0x40000
	s_addc_u32 s49, s49, 0
	s_mov_b32 m0, s57
	v_lshl_add_u64 v[224:225], s[48:49], 0, v[134:135]
	ds_read_b128 v[184:187], v153 offset:32768
	ds_read_b128 v[188:191], v153 offset:33792
	ds_read_b128 v[192:195], v153 offset:34816
	ds_read_b128 v[196:199], v153 offset:35840
	ds_read_b128 v[200:203], v153 offset:36864
	ds_read_b128 v[204:207], v153 offset:37888
	ds_read_b128 v[208:211], v153 offset:38912
	ds_read_b128 v[212:215], v153 offset:39936
	global_load_lds_dwordx4 v[224:225], off
	v_lshl_add_u64 v[224:225], s[48:49], 0, v[130:131]
	s_mov_b32 m0, s58
	s_nop 0
	global_load_lds_dwordx4 v[224:225], off
	s_waitcnt vmcnt(8)
	s_waitcnt lgkmcnt(0)
	s_barrier
	v_mfma_f32_16x16x32_bf16 v[124:127], v[144:147], v[184:187], v[124:127]
	v_mfma_f32_16x16x32_bf16 v[120:123], v[160:163], v[184:187], v[120:123]
	v_mfma_f32_16x16x32_bf16 v[108:111], v[144:147], v[192:195], v[108:111]
	v_mfma_f32_16x16x32_bf16 v[104:107], v[160:163], v[192:195], v[104:107]
	v_mfma_f32_16x16x32_bf16 v[92:95], v[144:147], v[200:203], v[92:95]
	v_mfma_f32_16x16x32_bf16 v[88:91], v[160:163], v[200:203], v[88:91]
	v_mfma_f32_16x16x32_bf16 v[76:79], v[144:147], v[208:211], v[76:79]
	v_mfma_f32_16x16x32_bf16 v[72:75], v[160:163], v[208:211], v[72:75]
	v_mfma_f32_16x16x32_bf16 v[124:127], v[156:159], v[188:191], v[124:127]
	v_mfma_f32_16x16x32_bf16 v[120:123], v[164:167], v[188:191], v[120:123]
	v_mfma_f32_16x16x32_bf16 v[108:111], v[156:159], v[196:199], v[108:111]
	v_mfma_f32_16x16x32_bf16 v[104:107], v[164:167], v[196:199], v[104:107]
	v_mfma_f32_16x16x32_bf16 v[92:95], v[156:159], v[204:207], v[92:95]
	v_mfma_f32_16x16x32_bf16 v[88:91], v[164:167], v[204:207], v[88:91]
	v_mfma_f32_16x16x32_bf16 v[76:79], v[156:159], v[212:215], v[76:79]
	v_mfma_f32_16x16x32_bf16 v[72:75], v[164:167], v[212:215], v[72:75]
	v_mfma_f32_16x16x32_bf16 v[116:119], v[168:171], v[184:187], v[116:119]
	v_mfma_f32_16x16x32_bf16 v[112:115], v[176:179], v[184:187], v[112:115]
	v_mfma_f32_16x16x32_bf16 v[100:103], v[168:171], v[192:195], v[100:103]
	v_mfma_f32_16x16x32_bf16 v[96:99], v[176:179], v[192:195], v[96:99]
	v_mfma_f32_16x16x32_bf16 v[84:87], v[168:171], v[200:203], v[84:87]
	v_mfma_f32_16x16x32_bf16 v[80:83], v[176:179], v[200:203], v[80:83]
	v_mfma_f32_16x16x32_bf16 v[68:71], v[168:171], v[208:211], v[68:71]
	v_mfma_f32_16x16x32_bf16 v[64:67], v[176:179], v[208:211], v[64:67]
	v_mfma_f32_16x16x32_bf16 v[116:119], v[172:175], v[188:191], v[116:119]
	v_mfma_f32_16x16x32_bf16 v[112:115], v[180:183], v[188:191], v[112:115]
	v_mfma_f32_16x16x32_bf16 v[100:103], v[172:175], v[196:199], v[100:103]
	v_mfma_f32_16x16x32_bf16 v[96:99], v[180:183], v[196:199], v[96:99]
	v_mfma_f32_16x16x32_bf16 v[84:87], v[172:175], v[204:207], v[84:87]
	v_mfma_f32_16x16x32_bf16 v[80:83], v[180:183], v[204:207], v[80:83]
	v_mfma_f32_16x16x32_bf16 v[68:71], v[172:175], v[212:215], v[68:71]
	v_mfma_f32_16x16x32_bf16 v[64:67], v[180:183], v[212:215], v[64:67]
	s_barrier
; #define PG8_STAGE(bufoff, gbase, voff) do { _Pragma("unroll") for (int _i = 0; _i < 2; ++_i) \
;         __builtin_amdgcn_global_load_lds((const unsigned*)((const char*)(gbase) + (voff)[_i]), (PG8_LAS unsigned*)(lds + (bufoff) + ldsw + _i * 8192), 16, 0, 0); } while (0)
; #define PG8_LDA(dst, b, h) do { _Pragma("unroll") for (int m = 0; m < 4; ++m) _Pragma("unroll") for (int k = 0; k < 2; ++k) dst[m][k] = *(const PG8_LAS bf16x8*)(lds + PG8_SA(b, h) + aoff + m * 2048 + k * 1024); } while (0)
; #define PG8_MMA(ai, bj, At, Bt) do { __builtin_amdgcn_s_setprio(1); _Pragma("unroll") for (int m = 0; m < 4; ++m) _Pragma("unroll") for (int n = 0; n < 2; ++n) _Pragma("unroll") for (int k = 0; k < 2; ++k) \
;         acc[ai][bj][m][n] = __builtin_amdgcn_mfma_f32_16x16x32_bf16(Bt[n][k], At[m][k], acc[ai][bj][m][n], 0, 0, 0); __builtin_amdgcn_s_setprio(0); } while (0)
; #define PG8_WAIT_V(n) asm volatile("s_waitcnt vmcnt(" #n ")" ::: "memory")
; #define PG8_WAIT_L(n) asm volatile("s_waitcnt lgkmcnt(" #n ")" ::: "memory")
; #define PG8_BAR __builtin_amdgcn_s_barrier()
; #define PG8_SCHED __builtin_amdgcn_sched_barrier(0)
; template <class Epi, class Sched, bool ALIGN_EPI = false, bool SP2 = false>
; __device__ __forceinline__ void gemm_phase(PG8_LAS unsigned char* lds, const Gemm g, const Sched& S, const Epi& E) {
;     ...
;             PG8_LDA(At, 1, 1); PG8_STAGE(PG8_SB(1, 0), b3, voffB); PG8_STAGE(PG8_SB(1, 1), b3 + hstep, voffB); PG8_STAGE(PG8_SA(1, 0), a3, voffA);
;             PG8_WAIT_V(8); PG8_WAIT_L(0); PG8_BAR; PG8_MMA(1, 0, At, B0); PG8_MMA(1, 1, At, B1); PG8_BAR; PG8_SCHED;
;     ...
;         if constexpr (ALIGN_EPI) { if (wr == 0) PG8_BAR; }
	s_add_i32 s48, s81, s52
	v_lshl_add_u64 v[216:217], v[216:217], 0, s[14:15]
	s_mov_b32 m0, s48
	ds_read_b128 v[184:187], v153 offset:49152
	ds_read_b128 v[188:191], v153 offset:50176
	ds_read_b128 v[192:195], v153 offset:51200
	ds_read_b128 v[196:199], v153 offset:52224
	ds_read_b128 v[200:203], v153 offset:53248
	ds_read_b128 v[204:207], v153 offset:54272
	ds_read_b128 v[208:211], v153 offset:55296
	ds_read_b128 v[212:215], v153 offset:56320
	global_load_lds_dwordx4 v[216:217], off
	s_add_i32 m0, s48, 0x2000
	s_add_u32 s46, s46, 0x40080
	v_lshl_add_u64 v[216:217], v[218:219], 0, s[14:15]
	s_addc_u32 s47, s47, 0
	s_add_i32 s48, s82, s52
	global_load_lds_dwordx4 v[216:217], off
	v_lshl_add_u64 v[216:217], s[46:47], 0, v[132:133]
	s_mov_b32 m0, s48
	s_nop 0
	global_load_lds_dwordx4 v[216:217], off
	v_lshl_add_u64 v[216:217], s[46:47], 0, v[128:129]
	s_add_i32 m0, s48, 0x2000
	s_nop 0
	global_load_lds_dwordx4 v[216:217], off
	v_lshl_add_u64 v[216:217], v[220:221], 0, s[14:15]
	s_mov_b32 m0, s65
	s_nop 0
	global_load_lds_dwordx4 v[216:217], off
	v_lshl_add_u64 v[216:217], v[222:223], 0, s[14:15]
	s_mov_b32 m0, s66
	s_nop 0
	global_load_lds_dwordx4 v[216:217], off
	s_waitcnt vmcnt(8)
	s_waitcnt lgkmcnt(0)
	s_barrier
	v_mfma_f32_16x16x32_bf16 v[60:63], v[144:147], v[184:187], v[60:63]
	v_mfma_f32_16x16x32_bf16 v[56:59], v[160:163], v[184:187], v[56:59]
	v_mfma_f32_16x16x32_bf16 v[44:47], v[144:147], v[192:195], v[44:47]
	v_mfma_f32_16x16x32_bf16 v[40:43], v[160:163], v[192:195], v[40:43]
	v_mfma_f32_16x16x32_bf16 v[28:31], v[144:147], v[200:203], v[28:31]
	v_mfma_f32_16x16x32_bf16 v[24:27], v[160:163], v[200:203], v[24:27]
	v_mfma_f32_16x16x32_bf16 v[12:15], v[144:147], v[208:211], v[12:15]
	v_mfma_f32_16x16x32_bf16 v[8:11], v[160:163], v[208:211], v[8:11]
	v_mfma_f32_16x16x32_bf16 v[60:63], v[156:159], v[188:191], v[60:63]
	v_mfma_f32_16x16x32_bf16 v[56:59], v[164:167], v[188:191], v[56:59]
	v_mfma_f32_16x16x32_bf16 v[44:47], v[156:159], v[196:199], v[44:47]
	v_mfma_f32_16x16x32_bf16 v[40:43], v[164:167], v[196:199], v[40:43]
	v_mfma_f32_16x16x32_bf16 v[28:31], v[156:159], v[204:207], v[28:31]
	v_mfma_f32_16x16x32_bf16 v[24:27], v[164:167], v[204:207], v[24:27]
	v_mfma_f32_16x16x32_bf16 v[12:15], v[156:159], v[212:215], v[12:15]
	v_mfma_f32_16x16x32_bf16 v[8:11], v[164:167], v[212:215], v[8:11]
	v_mfma_f32_16x16x32_bf16 v[52:55], v[168:171], v[184:187], v[52:55]
	v_mfma_f32_16x16x32_bf16 v[48:51], v[176:179], v[184:187], v[48:51]
	v_mfma_f32_16x16x32_bf16 v[36:39], v[168:171], v[192:195], v[36:39]
	v_mfma_f32_16x16x32_bf16 v[32:35], v[176:179], v[192:195], v[32:35]
	v_mfma_f32_16x16x32_bf16 v[20:23], v[168:171], v[200:203], v[20:23]
	v_mfma_f32_16x16x32_bf16 v[16:19], v[176:179], v[200:203], v[16:19]
	v_mfma_f32_16x16x32_bf16 v[4:7], v[168:171], v[208:211], v[4:7]
	v_mfma_f32_16x16x32_bf16 v[0:3], v[176:179], v[208:211], v[0:3]
	v_mfma_f32_16x16x32_bf16 v[52:55], v[172:175], v[188:191], v[52:55]
	v_mfma_f32_16x16x32_bf16 v[48:51], v[180:183], v[188:191], v[48:51]
	v_mfma_f32_16x16x32_bf16 v[36:39], v[172:175], v[196:199], v[36:39]
	v_mfma_f32_16x16x32_bf16 v[32:35], v[180:183], v[196:199], v[32:35]
	v_mfma_f32_16x16x32_bf16 v[20:23], v[172:175], v[204:207], v[20:23]
	v_mfma_f32_16x16x32_bf16 v[16:19], v[180:183], v[204:207], v[16:19]
	v_mfma_f32_16x16x32_bf16 v[4:7], v[172:175], v[212:215], v[4:7]
	v_mfma_f32_16x16x32_bf16 v[0:3], v[180:183], v[212:215], v[0:3]
	s_barrier
	s_add_i32 s80, s80, 2
	s_add_u32 s44, s44, 0x100
	s_addc_u32 s45, s45, 0
	s_add_u32 s78, s78, 0x100
	s_addc_u32 s79, s79, 0
	s_cmp_gt_u32 s80, 13
	s_cbranch_scc0 .LBB0_593
	s_and_b64 vcc, exec, s[16:17]
	s_cbranch_vccz .LBB0_596
	s_barrier

; #define PG8_STAGE(bufoff, gbase, voff) do { _Pragma("unroll") for (int _i = 0; _i < 2; ++_i) \
;         __builtin_amdgcn_global_load_lds((const unsigned*)((const char*)(gbase) + (voff)[_i]), (PG8_LAS unsigned*)(lds + (bufoff) + ldsw + _i * 8192), 16, 0, 0); } while (0)
; #define PG8_LDA(dst, b, h) do { _Pragma("unroll") for (int m = 0; m < 4; ++m) _Pragma("unroll") for (int k = 0; k < 2; ++k) dst[m][k] = *(const PG8_LAS bf16x8*)(lds + PG8_SA(b, h) + aoff + m * 2048 + k * 1024); } while (0)
; #define PG8_LDB(dst, b, h) do { _Pragma("unroll") for (int n = 0; n < 2; ++n) _Pragma("unroll") for (int k = 0; k < 2; ++k) dst[n][k] = *(const PG8_LAS bf16x8*)(lds + PG8_SB(b, h) + boff + n * 2048 + k * 1024); } while (0)
; #define PG8_MMA(ai, bj, At, Bt) do { __builtin_amdgcn_s_setprio(1); _Pragma("unroll") for (int m = 0; m < 4; ++m) _Pragma("unroll") for (int n = 0; n < 2; ++n) _Pragma("unroll") for (int k = 0; k < 2; ++k) \
;         acc[ai][bj][m][n] = __builtin_amdgcn_mfma_f32_16x16x32_bf16(Bt[n][k], At[m][k], acc[ai][bj][m][n], 0, 0, 0); __builtin_amdgcn_s_setprio(0); } while (0)
; template <class Epi, class Sched, bool ALIGN_EPI = false, bool SP2 = false>
; __device__ __forceinline__ void gemm_phase(PG8_LAS unsigned char* lds, const Gemm g, const Sched& S, const Epi& E) {
;     ...
;         for (int t = 0; t < nt; t += 2) {
;             const bool last = (t == nt - 2);
;             if constexpr (Epi::PREFETCH) { if (t == nt - 4) E.prefetch(cur, lds + STAGE_BYTES + 1024, tid); }
;             const char* a1 = cA + (size_t)(t + 1) * kstep;
;             const char* a2 = last ? nA : cA + (size_t)(t + 2) * kstep; const char* b2 = last ? nB : cB + (size_t)(t + 2) * kstep;
;             const char* a3 = a2 + kstep; const char* b3 = b2 + kstep;
;             if (last && has_next) S.a_ready(nxt);
;             if constexpr (SP2) {
;             PG8_LDB(B0, 0, 0); PG8_LDB(B1, 0, 1); PG8_SCHED; PG8_LDA(At, 0, 0); PG8_STAGE(PG8_SA(1, 1), a1 + hstep, voffA);
;             PG8_WAIT_V(8); PG8_WAIT_L(0); PG8_BAR; PG8_MMA(0, 0, At, B0); PG8_MMA(0, 1, At, B1); PG8_BAR; PG8_SCHED;
;             PG8_LDA(At, 0, 1); PG8_STAGE(PG8_SB(0, 0), b2, voffB); PG8_STAGE(PG8_SB(0, 1), b2 + hstep, voffB); PG8_STAGE(PG8_SA(0, 0), a2, voffA);
;             PG8_WAIT_V(8); PG8_WAIT_L(0); PG8_BAR; PG8_MMA(1, 0, At, B0); PG8_MMA(1, 1, At, B1); PG8_BAR; PG8_SCHED;
.LBB0_1012:
	ds_read_b128 v[112:115], v246
	ds_read_b128 v[116:119], v246 offset:1024
	ds_read_b128 v[120:123], v246 offset:2048
	ds_read_b128 v[124:127], v246 offset:3072
	ds_read_b128 v[136:139], v247
	ds_read_b128 v[140:143], v247 offset:1024
	ds_read_b128 v[152:155], v247 offset:2048
	ds_read_b128 v[156:159], v247 offset:3072
	s_add_u32 s44, s42, 0xfffc0080
	s_addc_u32 s45, s43, -1
	s_cmp_eq_u32 s68, 12
	s_cselect_b32 s47, s23, s45
	s_cselect_b32 s46, s39, s44
	s_cselect_b32 s45, s21, s67
	s_cselect_b32 s44, s65, s66
	v_lshl_add_u64 v[206:207], s[42:43], 0, v[200:201]
	s_add_i32 m0, s41, 0xc000
	ds_read_b128 v[160:163], v248
	ds_read_b128 v[164:167], v248 offset:1024
	ds_read_b128 v[168:171], v248 offset:2048
	ds_read_b128 v[172:175], v248 offset:3072
	ds_read_b128 v[176:179], v248 offset:4096
	ds_read_b128 v[180:183], v248 offset:5120
	ds_read_b128 v[184:187], v248 offset:6144
	ds_read_b128 v[188:191], v248 offset:7168
	global_load_lds_dwordx4 v[206:207], off
	v_lshl_add_u64 v[206:207], s[42:43], 0, v[202:203]
	s_add_i32 m0, s41, 0xe000
	s_nop 0
	global_load_lds_dwordx4 v[206:207], off
	s_waitcnt vmcnt(8)
	s_waitcnt lgkmcnt(0)
	s_barrier
	v_mfma_f32_16x16x32_bf16 v[148:151], v[112:115], v[160:163], v[148:151]
	v_mfma_f32_16x16x32_bf16 v[144:147], v[120:123], v[160:163], v[144:147]
	v_mfma_f32_16x16x32_bf16 v[108:111], v[112:115], v[168:171], v[108:111]
	v_mfma_f32_16x16x32_bf16 v[104:107], v[120:123], v[168:171], v[104:107]
	v_mfma_f32_16x16x32_bf16 v[92:95], v[112:115], v[176:179], v[92:95]
	v_mfma_f32_16x16x32_bf16 v[88:91], v[120:123], v[176:179], v[88:91]
	v_mfma_f32_16x16x32_bf16 v[76:79], v[112:115], v[184:187], v[76:79]
	v_mfma_f32_16x16x32_bf16 v[72:75], v[120:123], v[184:187], v[72:75]
	v_mfma_f32_16x16x32_bf16 v[148:151], v[116:119], v[164:167], v[148:151]
	v_mfma_f32_16x16x32_bf16 v[144:147], v[124:127], v[164:167], v[144:147]
	v_mfma_f32_16x16x32_bf16 v[108:111], v[116:119], v[172:175], v[108:111]
	v_mfma_f32_16x16x32_bf16 v[104:107], v[124:127], v[172:175], v[104:107]
	v_mfma_f32_16x16x32_bf16 v[92:95], v[116:119], v[180:183], v[92:95]
	v_mfma_f32_16x16x32_bf16 v[88:91], v[124:127], v[180:183], v[88:91]
	v_mfma_f32_16x16x32_bf16 v[76:79], v[116:119], v[188:191], v[76:79]
	v_mfma_f32_16x16x32_bf16 v[72:75], v[124:127], v[188:191], v[72:75]
	v_mfma_f32_16x16x32_bf16 v[132:135], v[136:139], v[160:163], v[132:135]
	v_mfma_f32_16x16x32_bf16 v[128:131], v[152:155], v[160:163], v[128:131]
	v_mfma_f32_16x16x32_bf16 v[100:103], v[136:139], v[168:171], v[100:103]
	v_mfma_f32_16x16x32_bf16 v[96:99], v[152:155], v[168:171], v[96:99]
	v_mfma_f32_16x16x32_bf16 v[84:87], v[136:139], v[176:179], v[84:87]
	v_mfma_f32_16x16x32_bf16 v[80:83], v[152:155], v[176:179], v[80:83]
	v_mfma_f32_16x16x32_bf16 v[68:71], v[136:139], v[184:187], v[68:71]
	v_mfma_f32_16x16x32_bf16 v[64:67], v[152:155], v[184:187], v[64:67]
	v_mfma_f32_16x16x32_bf16 v[132:135], v[140:143], v[164:167], v[132:135]
	v_mfma_f32_16x16x32_bf16 v[128:131], v[156:159], v[164:167], v[128:131]
	v_mfma_f32_16x16x32_bf16 v[100:103], v[140:143], v[172:175], v[100:103]
	v_mfma_f32_16x16x32_bf16 v[96:99], v[156:159], v[172:175], v[96:99]
	v_mfma_f32_16x16x32_bf16 v[84:87], v[140:143], v[180:183], v[84:87]
	v_mfma_f32_16x16x32_bf16 v[80:83], v[156:159], v[180:183], v[80:83]
	v_mfma_f32_16x16x32_bf16 v[68:71], v[140:143], v[188:191], v[68:71]
	v_mfma_f32_16x16x32_bf16 v[64:67], v[156:159], v[188:191], v[64:67]
	s_barrier
	s_add_i32 s69, s63, s52
	v_lshl_add_u64 v[206:207], s[44:45], 0, v[194:195]
	s_mov_b32 m0, s69
	ds_read_b128 v[160:163], v248 offset:16384
	ds_read_b128 v[164:167], v248 offset:17408
	ds_read_b128 v[168:171], v248 offset:18432
	ds_read_b128 v[172:175], v248 offset:19456
	ds_read_b128 v[176:179], v248 offset:20480
	ds_read_b128 v[180:183], v248 offset:21504
	ds_read_b128 v[184:187], v248 offset:22528
	ds_read_b128 v[188:191], v248 offset:23552
	global_load_lds_dwordx4 v[206:207], off
	s_add_i32 m0, s69, 0x2000
	s_add_u32 s70, s44, 0x40000
	v_lshl_add_u64 v[208:209], s[44:45], 0, v[198:199]
	s_addc_u32 s71, s45, 0
	s_add_i32 s69, s64, s52
	global_load_lds_dwordx4 v[208:209], off
	v_lshl_add_u64 v[210:211], s[70:71], 0, v[194:195]
	s_mov_b32 m0, s69
	v_lshl_add_u64 v[212:213], s[46:47], 0, v[196:197]
	global_load_lds_dwordx4 v[210:211], off
	v_lshl_add_u64 v[210:211], s[70:71], 0, v[198:199]
	s_add_i32 m0, s69, 0x2000
	s_nop 0
	global_load_lds_dwordx4 v[210:211], off
	v_lshl_add_u64 v[210:211], s[46:47], 0, v[192:193]
	s_mov_b32 m0, s41
	s_nop 0
	global_load_lds_dwordx4 v[210:211], off
	s_mov_b32 m0, s53
	s_nop 0
	global_load_lds_dwordx4 v[212:213], off
	s_waitcnt vmcnt(8)
	s_waitcnt lgkmcnt(0)
	s_barrier
; #define PG8_STAGE(bufoff, gbase, voff) do { _Pragma("unroll") for (int _i = 0; _i < 2; ++_i) \
;         __builtin_amdgcn_global_load_lds((const unsigned*)((const char*)(gbase) + (voff)[_i]), (PG8_LAS unsigned*)(lds + (bufoff) + ldsw + _i * 8192), 16, 0, 0); } while (0)
; #define PG8_LDA(dst, b, h) do { _Pragma("unroll") for (int m = 0; m < 4; ++m) _Pragma("unroll") for (int k = 0; k < 2; ++k) dst[m][k] = *(const PG8_LAS bf16x8*)(lds + PG8_SA(b, h) + aoff + m * 2048 + k * 1024); } while (0)
; #define PG8_LDB(dst, b, h) do { _Pragma("unroll") for (int n = 0; n < 2; ++n) _Pragma("unroll") for (int k = 0; k < 2; ++k) dst[n][k] = *(const PG8_LAS bf16x8*)(lds + PG8_SB(b, h) + boff + n * 2048 + k * 1024); } while (0)
; #define PG8_MMA(ai, bj, At, Bt) do { __builtin_amdgcn_s_setprio(1); _Pragma("unroll") for (int m = 0; m < 4; ++m) _Pragma("unroll") for (int n = 0; n < 2; ++n) _Pragma("unroll") for (int k = 0; k < 2; ++k) \
;         acc[ai][bj][m][n] = __builtin_amdgcn_mfma_f32_16x16x32_bf16(Bt[n][k], At[m][k], acc[ai][bj][m][n], 0, 0, 0); __builtin_amdgcn_s_setprio(0); } while (0)
; #define PG8_WAIT_V(n) asm volatile("s_waitcnt vmcnt(" #n ")" ::: "memory")
; #define PG8_WAIT_L(n) asm volatile("s_waitcnt lgkmcnt(" #n ")" ::: "memory")
; #define PG8_BAR __builtin_amdgcn_s_barrier()
; #define PG8_SCHED __builtin_amdgcn_sched_barrier(0)
; template <class Epi, class Sched, bool ALIGN_EPI = false, bool SP2 = false>
; __device__ __forceinline__ void gemm_phase(PG8_LAS unsigned char* lds, const Gemm g, const Sched& S, const Epi& E) {
;     ...
;             PG8_WAIT_V(8); PG8_WAIT_L(0); PG8_BAR; PG8_MMA(1, 0, At, B0); PG8_MMA(1, 1, At, B1); PG8_BAR; PG8_SCHED;
;             PG8_LDB(B0, 1, 0); PG8_LDB(B1, 1, 1); PG8_SCHED; PG8_LDA(At, 1, 0); PG8_STAGE(PG8_SA(0, 1), a2 + hstep, voffA);
;             PG8_WAIT_V(8); PG8_WAIT_L(0); PG8_BAR; PG8_MMA(0, 0, At, B0); PG8_MMA(0, 1, At, B1); PG8_BAR; PG8_SCHED;
	v_mfma_f32_16x16x32_bf16 v[60:63], v[112:115], v[160:163], v[60:63]
	v_mfma_f32_16x16x32_bf16 v[56:59], v[120:123], v[160:163], v[56:59]
	v_mfma_f32_16x16x32_bf16 v[44:47], v[112:115], v[168:171], v[44:47]
	v_mfma_f32_16x16x32_bf16 v[40:43], v[120:123], v[168:171], v[40:43]
	v_mfma_f32_16x16x32_bf16 v[28:31], v[112:115], v[176:179], v[28:31]
	v_mfma_f32_16x16x32_bf16 v[24:27], v[120:123], v[176:179], v[24:27]
	v_mfma_f32_16x16x32_bf16 v[12:15], v[112:115], v[184:187], v[12:15]
	v_mfma_f32_16x16x32_bf16 v[8:11], v[120:123], v[184:187], v[8:11]
	v_mfma_f32_16x16x32_bf16 v[60:63], v[116:119], v[164:167], v[60:63]
	v_mfma_f32_16x16x32_bf16 v[56:59], v[124:127], v[164:167], v[56:59]
	v_mfma_f32_16x16x32_bf16 v[44:47], v[116:119], v[172:175], v[44:47]
	v_mfma_f32_16x16x32_bf16 v[40:43], v[124:127], v[172:175], v[40:43]
	v_mfma_f32_16x16x32_bf16 v[28:31], v[116:119], v[180:183], v[28:31]
	v_mfma_f32_16x16x32_bf16 v[24:27], v[124:127], v[180:183], v[24:27]
	v_mfma_f32_16x16x32_bf16 v[12:15], v[116:119], v[188:191], v[12:15]
	v_mfma_f32_16x16x32_bf16 v[8:11], v[124:127], v[188:191], v[8:11]
	v_mfma_f32_16x16x32_bf16 v[52:55], v[136:139], v[160:163], v[52:55]
	v_mfma_f32_16x16x32_bf16 v[48:51], v[152:155], v[160:163], v[48:51]
	v_mfma_f32_16x16x32_bf16 v[36:39], v[136:139], v[168:171], v[36:39]
	v_mfma_f32_16x16x32_bf16 v[32:35], v[152:155], v[168:171], v[32:35]
	v_mfma_f32_16x16x32_bf16 v[20:23], v[136:139], v[176:179], v[20:23]
	v_mfma_f32_16x16x32_bf16 v[16:19], v[152:155], v[176:179], v[16:19]
	v_mfma_f32_16x16x32_bf16 v[4:7], v[136:139], v[184:187], v[4:7]
	v_mfma_f32_16x16x32_bf16 v[0:3], v[152:155], v[184:187], v[0:3]
	v_mfma_f32_16x16x32_bf16 v[52:55], v[140:143], v[164:167], v[52:55]
	v_mfma_f32_16x16x32_bf16 v[48:51], v[156:159], v[164:167], v[48:51]
	v_mfma_f32_16x16x32_bf16 v[36:39], v[140:143], v[172:175], v[36:39]
	v_mfma_f32_16x16x32_bf16 v[32:35], v[156:159], v[172:175], v[32:35]
	v_mfma_f32_16x16x32_bf16 v[20:23], v[140:143], v[180:183], v[20:23]
	v_mfma_f32_16x16x32_bf16 v[16:19], v[156:159], v[180:183], v[16:19]
	v_mfma_f32_16x16x32_bf16 v[4:7], v[140:143], v[188:191], v[4:7]
	v_mfma_f32_16x16x32_bf16 v[0:3], v[156:159], v[188:191], v[0:3]
	s_barrier
	s_add_i32 s69, 0, 0x18000
	s_add_i32 s70, 0, 0x1c000
	v_add_u32_e32 v124, s69, v244
	v_add_u32_e32 v156, s70, v244
	ds_read_b128 v[112:115], v124
	ds_read_b128 v[116:119], v124 offset:1024
	ds_read_b128 v[120:123], v124 offset:2048
	ds_read_b128 v[124:127], v124 offset:3072
	ds_read_b128 v[136:139], v156
	ds_read_b128 v[140:143], v156 offset:1024
	ds_read_b128 v[152:155], v156 offset:2048
	ds_read_b128 v[156:159], v156 offset:3072
	s_add_u32 s46, s46, 0x40000
	s_addc_u32 s47, s47, 0
	s_mov_b32 m0, s54
	v_lshl_add_u64 v[214:215], s[46:47], 0, v[192:193]
	ds_read_b128 v[160:163], v248 offset:32768
	ds_read_b128 v[164:167], v248 offset:33792
	ds_read_b128 v[168:171], v248 offset:34816
	ds_read_b128 v[172:175], v248 offset:35840
	ds_read_b128 v[176:179], v248 offset:36864
	ds_read_b128 v[180:183], v248 offset:37888
	ds_read_b128 v[184:187], v248 offset:38912
	ds_read_b128 v[188:191], v248 offset:39936
	global_load_lds_dwordx4 v[214:215], off
	v_lshl_add_u64 v[214:215], s[46:47], 0, v[196:197]
	s_mov_b32 m0, s55
	s_nop 0
	global_load_lds_dwordx4 v[214:215], off
	s_waitcnt vmcnt(8)
	s_waitcnt lgkmcnt(0)
	s_barrier
	v_mfma_f32_16x16x32_bf16 v[148:151], v[112:115], v[160:163], v[148:151]
	v_mfma_f32_16x16x32_bf16 v[144:147], v[120:123], v[160:163], v[144:147]
	v_mfma_f32_16x16x32_bf16 v[108:111], v[112:115], v[168:171], v[108:111]
	v_mfma_f32_16x16x32_bf16 v[104:107], v[120:123], v[168:171], v[104:107]
	v_mfma_f32_16x16x32_bf16 v[92:95], v[112:115], v[176:179], v[92:95]
	v_mfma_f32_16x16x32_bf16 v[88:91], v[120:123], v[176:179], v[88:91]
	v_mfma_f32_16x16x32_bf16 v[76:79], v[112:115], v[184:187], v[76:79]
	v_mfma_f32_16x16x32_bf16 v[72:75], v[120:123], v[184:187], v[72:75]
	v_mfma_f32_16x16x32_bf16 v[148:151], v[116:119], v[164:167], v[148:151]
	v_mfma_f32_16x16x32_bf16 v[144:147], v[124:127], v[164:167], v[144:147]
	v_mfma_f32_16x16x32_bf16 v[108:111], v[116:119], v[172:175], v[108:111]
	v_mfma_f32_16x16x32_bf16 v[104:107], v[124:127], v[172:175], v[104:107]
	v_mfma_f32_16x16x32_bf16 v[92:95], v[116:119], v[180:183], v[92:95]
	v_mfma_f32_16x16x32_bf16 v[88:91], v[124:127], v[180:183], v[88:91]
	v_mfma_f32_16x16x32_bf16 v[76:79], v[116:119], v[188:191], v[76:79]
	v_mfma_f32_16x16x32_bf16 v[72:75], v[124:127], v[188:191], v[72:75]
	v_mfma_f32_16x16x32_bf16 v[132:135], v[136:139], v[160:163], v[132:135]
	v_mfma_f32_16x16x32_bf16 v[128:131], v[152:155], v[160:163], v[128:131]
	v_mfma_f32_16x16x32_bf16 v[100:103], v[136:139], v[168:171], v[100:103]
	v_mfma_f32_16x16x32_bf16 v[96:99], v[152:155], v[168:171], v[96:99]
	v_mfma_f32_16x16x32_bf16 v[84:87], v[136:139], v[176:179], v[84:87]
	v_mfma_f32_16x16x32_bf16 v[80:83], v[152:155], v[176:179], v[80:83]
	v_mfma_f32_16x16x32_bf16 v[68:71], v[136:139], v[184:187], v[68:71]
	v_mfma_f32_16x16x32_bf16 v[64:67], v[152:155], v[184:187], v[64:67]
	v_mfma_f32_16x16x32_bf16 v[132:135], v[140:143], v[164:167], v[132:135]
	v_mfma_f32_16x16x32_bf16 v[128:131], v[156:159], v[164:167], v[128:131]
	v_mfma_f32_16x16x32_bf16 v[100:103], v[140:143], v[172:175], v[100:103]
	v_mfma_f32_16x16x32_bf16 v[96:99], v[156:159], v[172:175], v[96:99]
	v_mfma_f32_16x16x32_bf16 v[84:87], v[140:143], v[180:183], v[84:87]
	v_mfma_f32_16x16x32_bf16 v[80:83], v[156:159], v[180:183], v[80:83]
	v_mfma_f32_16x16x32_bf16 v[68:71], v[140:143], v[188:191], v[68:71]
	v_mfma_f32_16x16x32_bf16 v[64:67], v[156:159], v[188:191], v[64:67]
	s_barrier
; #define PG8_STAGE(bufoff, gbase, voff) do { _Pragma("unroll") for (int _i = 0; _i < 2; ++_i) \
;         __builtin_amdgcn_global_load_lds((const unsigned*)((const char*)(gbase) + (voff)[_i]), (PG8_LAS unsigned*)(lds + (bufoff) + ldsw + _i * 8192), 16, 0, 0); } while (0)
; #define PG8_LDA(dst, b, h) do { _Pragma("unroll") for (int m = 0; m < 4; ++m) _Pragma("unroll") for (int k = 0; k < 2; ++k) dst[m][k] = *(const PG8_LAS bf16x8*)(lds + PG8_SA(b, h) + aoff + m * 2048 + k * 1024); } while (0)
; #define PG8_MMA(ai, bj, At, Bt) do { __builtin_amdgcn_s_setprio(1); _Pragma("unroll") for (int m = 0; m < 4; ++m) _Pragma("unroll") for (int n = 0; n < 2; ++n) _Pragma("unroll") for (int k = 0; k < 2; ++k) \
;         acc[ai][bj][m][n] = __builtin_amdgcn_mfma_f32_16x16x32_bf16(Bt[n][k], At[m][k], acc[ai][bj][m][n], 0, 0, 0); __builtin_amdgcn_s_setprio(0); } while (0)
; #define PG8_WAIT_V(n) asm volatile("s_waitcnt vmcnt(" #n ")" ::: "memory")
; #define PG8_WAIT_L(n) asm volatile("s_waitcnt lgkmcnt(" #n ")" ::: "memory")
; #define PG8_BAR __builtin_amdgcn_s_barrier()
; #define PG8_SCHED __builtin_amdgcn_sched_barrier(0)
; template <class Epi, class Sched, bool ALIGN_EPI = false, bool SP2 = false>
; __device__ __forceinline__ void gemm_phase(PG8_LAS unsigned char* lds, const Gemm g, const Sched& S, const Epi& E) {
;     ...
;             PG8_LDA(At, 1, 1); PG8_STAGE(PG8_SB(1, 0), b3, voffB); PG8_STAGE(PG8_SB(1, 1), b3 + hstep, voffB); PG8_STAGE(PG8_SA(1, 0), a3, voffA);
;             PG8_WAIT_V(8); PG8_WAIT_L(0); PG8_BAR; PG8_MMA(1, 0, At, B0); PG8_MMA(1, 1, At, B1); PG8_BAR; PG8_SCHED;
;     ...
;         if constexpr (ALIGN_EPI) { if (wr == 0) PG8_BAR; }
	s_add_i32 s46, s69, s52
	v_lshl_add_u64 v[206:207], v[206:207], 0, s[16:17]
	s_mov_b32 m0, s46
	ds_read_b128 v[160:163], v248 offset:49152
	ds_read_b128 v[164:167], v248 offset:50176
	ds_read_b128 v[168:171], v248 offset:51200
	ds_read_b128 v[172:175], v248 offset:52224
	ds_read_b128 v[176:179], v248 offset:53248
	ds_read_b128 v[180:183], v248 offset:54272
	ds_read_b128 v[184:187], v248 offset:55296
	ds_read_b128 v[188:191], v248 offset:56320
	global_load_lds_dwordx4 v[206:207], off
	s_add_i32 m0, s46, 0x2000
	s_add_u32 s44, s44, 0x40080
	v_lshl_add_u64 v[206:207], v[208:209], 0, s[16:17]
	s_addc_u32 s45, s45, 0
	s_add_i32 s46, s70, s52
	global_load_lds_dwordx4 v[206:207], off
	v_lshl_add_u64 v[206:207], s[44:45], 0, v[194:195]
	s_mov_b32 m0, s46
	s_nop 0
	global_load_lds_dwordx4 v[206:207], off
	v_lshl_add_u64 v[206:207], s[44:45], 0, v[198:199]
	s_add_i32 m0, s46, 0x2000
	s_nop 0
	global_load_lds_dwordx4 v[206:207], off
	v_lshl_add_u64 v[206:207], v[210:211], 0, s[16:17]
	s_mov_b32 m0, s57
	s_nop 0
	global_load_lds_dwordx4 v[206:207], off
	v_lshl_add_u64 v[206:207], v[212:213], 0, s[16:17]
	s_mov_b32 m0, s58
	s_nop 0
	global_load_lds_dwordx4 v[206:207], off
	s_waitcnt vmcnt(8)
	s_waitcnt lgkmcnt(0)
	s_barrier
	v_mfma_f32_16x16x32_bf16 v[60:63], v[112:115], v[160:163], v[60:63]
	v_mfma_f32_16x16x32_bf16 v[56:59], v[120:123], v[160:163], v[56:59]
	v_mfma_f32_16x16x32_bf16 v[44:47], v[112:115], v[168:171], v[44:47]
	v_mfma_f32_16x16x32_bf16 v[40:43], v[120:123], v[168:171], v[40:43]
	v_mfma_f32_16x16x32_bf16 v[28:31], v[112:115], v[176:179], v[28:31]
	v_mfma_f32_16x16x32_bf16 v[24:27], v[120:123], v[176:179], v[24:27]
	v_mfma_f32_16x16x32_bf16 v[12:15], v[112:115], v[184:187], v[12:15]
	v_mfma_f32_16x16x32_bf16 v[8:11], v[120:123], v[184:187], v[8:11]
	v_mfma_f32_16x16x32_bf16 v[60:63], v[116:119], v[164:167], v[60:63]
	v_mfma_f32_16x16x32_bf16 v[56:59], v[124:127], v[164:167], v[56:59]
	v_mfma_f32_16x16x32_bf16 v[44:47], v[116:119], v[172:175], v[44:47]
	v_mfma_f32_16x16x32_bf16 v[40:43], v[124:127], v[172:175], v[40:43]
	v_mfma_f32_16x16x32_bf16 v[28:31], v[116:119], v[180:183], v[28:31]
	v_mfma_f32_16x16x32_bf16 v[24:27], v[124:127], v[180:183], v[24:27]
	v_mfma_f32_16x16x32_bf16 v[12:15], v[116:119], v[188:191], v[12:15]
	v_mfma_f32_16x16x32_bf16 v[8:11], v[124:127], v[188:191], v[8:11]
	v_mfma_f32_16x16x32_bf16 v[52:55], v[136:139], v[160:163], v[52:55]
	v_mfma_f32_16x16x32_bf16 v[48:51], v[152:155], v[160:163], v[48:51]
	v_mfma_f32_16x16x32_bf16 v[36:39], v[136:139], v[168:171], v[36:39]
	v_mfma_f32_16x16x32_bf16 v[32:35], v[152:155], v[168:171], v[32:35]
	v_mfma_f32_16x16x32_bf16 v[20:23], v[136:139], v[176:179], v[20:23]
	v_mfma_f32_16x16x32_bf16 v[16:19], v[152:155], v[176:179], v[16:19]
	v_mfma_f32_16x16x32_bf16 v[4:7], v[136:139], v[184:187], v[4:7]
	v_mfma_f32_16x16x32_bf16 v[0:3], v[152:155], v[184:187], v[0:3]
	v_mfma_f32_16x16x32_bf16 v[52:55], v[140:143], v[164:167], v[52:55]
	v_mfma_f32_16x16x32_bf16 v[48:51], v[156:159], v[164:167], v[48:51]
	v_mfma_f32_16x16x32_bf16 v[36:39], v[140:143], v[172:175], v[36:39]
	v_mfma_f32_16x16x32_bf16 v[32:35], v[156:159], v[172:175], v[32:35]
	v_mfma_f32_16x16x32_bf16 v[20:23], v[140:143], v[180:183], v[20:23]
	v_mfma_f32_16x16x32_bf16 v[16:19], v[156:159], v[180:183], v[16:19]
	v_mfma_f32_16x16x32_bf16 v[4:7], v[140:143], v[188:191], v[4:7]
	v_mfma_f32_16x16x32_bf16 v[0:3], v[156:159], v[188:191], v[0:3]
	s_barrier
	s_add_i32 s68, s68, 2
	s_add_u32 s42, s42, 0x100
	s_addc_u32 s43, s43, 0
	s_add_u32 s66, s66, 0x100
	s_addc_u32 s67, s67, 0
	s_cmp_gt_u32 s68, 13
	s_cbranch_scc0 .LBB0_1012
	s_and_b64 vcc, exec, s[18:19]
	s_cbranch_vccz .LBB0_1015
	s_barrier

; #define PG8_STAGE(bufoff, gbase, voff) do { _Pragma("unroll") for (int _i = 0; _i < 2; ++_i) \
;         __builtin_amdgcn_global_load_lds((const unsigned*)((const char*)(gbase) + (voff)[_i]), (PG8_LAS unsigned*)(lds + (bufoff) + ldsw + _i * 8192), 16, 0, 0); } while (0)
; #define PG8_LDA(dst, b, h) do { _Pragma("unroll") for (int m = 0; m < 4; ++m) _Pragma("unroll") for (int k = 0; k < 2; ++k) dst[m][k] = *(const PG8_LAS bf16x8*)(lds + PG8_SA(b, h) + aoff + m * 2048 + k * 1024); } while (0)
; #define PG8_LDB(dst, b, h) do { _Pragma("unroll") for (int n = 0; n < 2; ++n) _Pragma("unroll") for (int k = 0; k < 2; ++k) dst[n][k] = *(const PG8_LAS bf16x8*)(lds + PG8_SB(b, h) + boff + n * 2048 + k * 1024); } while (0)
; #define PG8_MMA(ai, bj, At, Bt) do { __builtin_amdgcn_s_setprio(1); _Pragma("unroll") for (int m = 0; m < 4; ++m) _Pragma("unroll") for (int n = 0; n < 2; ++n) _Pragma("unroll") for (int k = 0; k < 2; ++k) \
;         acc[ai][bj][m][n] = __builtin_amdgcn_mfma_f32_16x16x32_bf16(Bt[n][k], At[m][k], acc[ai][bj][m][n], 0, 0, 0); __builtin_amdgcn_s_setprio(0); } while (0)
; template <class Epi, class Sched, bool ALIGN_EPI = false, bool SP2 = false>
; __device__ __forceinline__ void gemm_phase(PG8_LAS unsigned char* lds, const Gemm g, const Sched& S, const Epi& E) {
;     ...
;         for (int t = 0; t < nt; t += 2) {
;             const bool last = (t == nt - 2);
;             if constexpr (Epi::PREFETCH) { if (t == nt - 4) E.prefetch(cur, lds + STAGE_BYTES + 1024, tid); }
;             const char* a1 = cA + (size_t)(t + 1) * kstep;
;             const char* a2 = last ? nA : cA + (size_t)(t + 2) * kstep; const char* b2 = last ? nB : cB + (size_t)(t + 2) * kstep;
;             const char* a3 = a2 + kstep; const char* b3 = b2 + kstep;
;             if (last && has_next) S.a_ready(nxt);
;             if constexpr (SP2) {
;             PG8_LDB(B0, 0, 0); PG8_LDB(B1, 0, 1); PG8_SCHED; PG8_LDA(At, 0, 0); PG8_STAGE(PG8_SA(1, 1), a1 + hstep, voffA);
;             PG8_WAIT_V(8); PG8_WAIT_L(0); PG8_BAR; PG8_MMA(0, 0, At, B0); PG8_MMA(0, 1, At, B1); PG8_BAR; PG8_SCHED;
;             PG8_LDA(At, 0, 1); PG8_STAGE(PG8_SB(0, 0), b2, voffB); PG8_STAGE(PG8_SB(0, 1), b2 + hstep, voffB); PG8_STAGE(PG8_SA(0, 0), a2, voffA);
;             PG8_WAIT_V(8); PG8_WAIT_L(0); PG8_BAR; PG8_MMA(1, 0, At, B0); PG8_MMA(1, 1, At, B1); PG8_BAR; PG8_SCHED;
.LBB0_1194:
	ds_read_b128 v[154:157], v149
	ds_read_b128 v[158:161], v149 offset:1024
	ds_read_b128 v[162:165], v149 offset:2048
	ds_read_b128 v[166:169], v149 offset:3072
	ds_read_b128 v[170:173], v150
	ds_read_b128 v[174:177], v150 offset:1024
	ds_read_b128 v[178:181], v150 offset:2048
	ds_read_b128 v[182:185], v150 offset:3072
	s_add_u32 s40, s38, 0xfffc0080
	s_addc_u32 s41, s39, -1
	s_cmp_eq_u32 s68, 12
	s_cselect_b32 s43, s21, s41
	s_cselect_b32 s42, s64, s40
	s_cselect_b32 s41, s19, s67
	s_cselect_b32 s40, s65, s66
	v_lshl_add_u64 v[144:145], s[38:39], 0, v[136:137]
	s_add_i32 m0, s37, 0xc000
	ds_read_b128 v[186:189], v151
	ds_read_b128 v[190:193], v151 offset:1024
	ds_read_b128 v[194:197], v151 offset:2048
	ds_read_b128 v[198:201], v151 offset:3072
	ds_read_b128 v[202:205], v151 offset:4096
	ds_read_b128 v[206:209], v151 offset:5120
	ds_read_b128 v[210:213], v151 offset:6144
	ds_read_b128 v[214:217], v151 offset:7168
	global_load_lds_dwordx4 v[144:145], off
	v_lshl_add_u64 v[144:145], s[38:39], 0, v[138:139]
	s_add_i32 m0, s37, 0xe000
	s_nop 0
	global_load_lds_dwordx4 v[144:145], off
	s_waitcnt vmcnt(8)
	s_waitcnt lgkmcnt(0)
	s_barrier
	v_mfma_f32_16x16x32_bf16 v[120:123], v[154:157], v[186:189], v[120:123]
	v_mfma_f32_16x16x32_bf16 v[116:119], v[162:165], v[186:189], v[116:119]
	v_mfma_f32_16x16x32_bf16 v[108:111], v[154:157], v[194:197], v[108:111]
	v_mfma_f32_16x16x32_bf16 v[100:103], v[162:165], v[194:197], v[100:103]
	v_mfma_f32_16x16x32_bf16 v[92:95], v[154:157], v[202:205], v[92:95]
	v_mfma_f32_16x16x32_bf16 v[84:87], v[162:165], v[202:205], v[84:87]
	v_mfma_f32_16x16x32_bf16 v[76:79], v[154:157], v[210:213], v[76:79]
	v_mfma_f32_16x16x32_bf16 v[68:71], v[162:165], v[210:213], v[68:71]
	v_mfma_f32_16x16x32_bf16 v[120:123], v[158:161], v[190:193], v[120:123]
	v_mfma_f32_16x16x32_bf16 v[116:119], v[166:169], v[190:193], v[116:119]
	v_mfma_f32_16x16x32_bf16 v[108:111], v[158:161], v[198:201], v[108:111]
	v_mfma_f32_16x16x32_bf16 v[100:103], v[166:169], v[198:201], v[100:103]
	v_mfma_f32_16x16x32_bf16 v[92:95], v[158:161], v[206:209], v[92:95]
	v_mfma_f32_16x16x32_bf16 v[84:87], v[166:169], v[206:209], v[84:87]
	v_mfma_f32_16x16x32_bf16 v[76:79], v[158:161], v[214:217], v[76:79]
	v_mfma_f32_16x16x32_bf16 v[68:71], v[166:169], v[214:217], v[68:71]
	v_mfma_f32_16x16x32_bf16 v[124:127], v[170:173], v[186:189], v[124:127]
	v_mfma_f32_16x16x32_bf16 v[112:115], v[178:181], v[186:189], v[112:115]
	v_mfma_f32_16x16x32_bf16 v[104:107], v[170:173], v[194:197], v[104:107]
	v_mfma_f32_16x16x32_bf16 v[96:99], v[178:181], v[194:197], v[96:99]
	v_mfma_f32_16x16x32_bf16 v[88:91], v[170:173], v[202:205], v[88:91]
	v_mfma_f32_16x16x32_bf16 v[80:83], v[178:181], v[202:205], v[80:83]
	v_mfma_f32_16x16x32_bf16 v[72:75], v[170:173], v[210:213], v[72:75]
	v_mfma_f32_16x16x32_bf16 v[64:67], v[178:181], v[210:213], v[64:67]
	v_mfma_f32_16x16x32_bf16 v[124:127], v[174:177], v[190:193], v[124:127]
	v_mfma_f32_16x16x32_bf16 v[112:115], v[182:185], v[190:193], v[112:115]
	v_mfma_f32_16x16x32_bf16 v[104:107], v[174:177], v[198:201], v[104:107]
	v_mfma_f32_16x16x32_bf16 v[96:99], v[182:185], v[198:201], v[96:99]
	v_mfma_f32_16x16x32_bf16 v[88:91], v[174:177], v[206:209], v[88:91]
	v_mfma_f32_16x16x32_bf16 v[80:83], v[182:185], v[206:209], v[80:83]
	v_mfma_f32_16x16x32_bf16 v[72:75], v[174:177], v[214:217], v[72:75]
	v_mfma_f32_16x16x32_bf16 v[64:67], v[182:185], v[214:217], v[64:67]
	s_barrier
	s_add_i32 s69, s57, s48
	v_lshl_add_u64 v[144:145], s[40:41], 0, v[132:133]
	s_mov_b32 m0, s69
	ds_read_b128 v[186:189], v151 offset:16384
	ds_read_b128 v[190:193], v151 offset:17408
	ds_read_b128 v[194:197], v151 offset:18432
	ds_read_b128 v[198:201], v151 offset:19456
	ds_read_b128 v[202:205], v151 offset:20480
	ds_read_b128 v[206:209], v151 offset:21504
	ds_read_b128 v[210:213], v151 offset:22528
	ds_read_b128 v[214:217], v151 offset:23552
	global_load_lds_dwordx4 v[144:145], off
	s_add_i32 m0, s69, 0x2000
	s_add_u32 s70, s40, 0x40000
	v_lshl_add_u64 v[218:219], s[40:41], 0, v[128:129]
	s_addc_u32 s71, s41, 0
	s_add_i32 s69, s58, s48
	global_load_lds_dwordx4 v[218:219], off
	v_lshl_add_u64 v[220:221], s[70:71], 0, v[132:133]
	s_mov_b32 m0, s69
	v_lshl_add_u64 v[222:223], s[42:43], 0, v[130:131]
	global_load_lds_dwordx4 v[220:221], off
	v_lshl_add_u64 v[220:221], s[70:71], 0, v[128:129]
	s_add_i32 m0, s69, 0x2000
	s_nop 0
	global_load_lds_dwordx4 v[220:221], off
	v_lshl_add_u64 v[220:221], s[42:43], 0, v[134:135]
	s_mov_b32 m0, s37
	s_nop 0
	global_load_lds_dwordx4 v[220:221], off
	s_mov_b32 m0, s50
	s_nop 0
	global_load_lds_dwordx4 v[222:223], off
	s_waitcnt vmcnt(8)
	s_waitcnt lgkmcnt(0)
	s_barrier
; #define PG8_STAGE(bufoff, gbase, voff) do { _Pragma("unroll") for (int _i = 0; _i < 2; ++_i) \
;         __builtin_amdgcn_global_load_lds((const unsigned*)((const char*)(gbase) + (voff)[_i]), (PG8_LAS unsigned*)(lds + (bufoff) + ldsw + _i * 8192), 16, 0, 0); } while (0)
; #define PG8_LDA(dst, b, h) do { _Pragma("unroll") for (int m = 0; m < 4; ++m) _Pragma("unroll") for (int k = 0; k < 2; ++k) dst[m][k] = *(const PG8_LAS bf16x8*)(lds + PG8_SA(b, h) + aoff + m * 2048 + k * 1024); } while (0)
; #define PG8_LDB(dst, b, h) do { _Pragma("unroll") for (int n = 0; n < 2; ++n) _Pragma("unroll") for (int k = 0; k < 2; ++k) dst[n][k] = *(const PG8_LAS bf16x8*)(lds + PG8_SB(b, h) + boff + n * 2048 + k * 1024); } while (0)
; #define PG8_MMA(ai, bj, At, Bt) do { __builtin_amdgcn_s_setprio(1); _Pragma("unroll") for (int m = 0; m < 4; ++m) _Pragma("unroll") for (int n = 0; n < 2; ++n) _Pragma("unroll") for (int k = 0; k < 2; ++k) \
;         acc[ai][bj][m][n] = __builtin_amdgcn_mfma_f32_16x16x32_bf16(Bt[n][k], At[m][k], acc[ai][bj][m][n], 0, 0, 0); __builtin_amdgcn_s_setprio(0); } while (0)
; #define PG8_WAIT_V(n) asm volatile("s_waitcnt vmcnt(" #n ")" ::: "memory")
; #define PG8_WAIT_L(n) asm volatile("s_waitcnt lgkmcnt(" #n ")" ::: "memory")
; #define PG8_BAR __builtin_amdgcn_s_barrier()
; #define PG8_SCHED __builtin_amdgcn_sched_barrier(0)
; template <class Epi, class Sched, bool ALIGN_EPI = false, bool SP2 = false>
; __device__ __forceinline__ void gemm_phase(PG8_LAS unsigned char* lds, const Gemm g, const Sched& S, const Epi& E) {
;     ...
;             PG8_WAIT_V(8); PG8_WAIT_L(0); PG8_BAR; PG8_MMA(1, 0, At, B0); PG8_MMA(1, 1, At, B1); PG8_BAR; PG8_SCHED;
;             PG8_LDB(B0, 1, 0); PG8_LDB(B1, 1, 1); PG8_SCHED; PG8_LDA(At, 1, 0); PG8_STAGE(PG8_SA(0, 1), a2 + hstep, voffA);
;             PG8_WAIT_V(8); PG8_WAIT_L(0); PG8_BAR; PG8_MMA(0, 0, At, B0); PG8_MMA(0, 1, At, B1); PG8_BAR; PG8_SCHED;
	v_mfma_f32_16x16x32_bf16 v[60:63], v[154:157], v[186:189], v[60:63]
	v_mfma_f32_16x16x32_bf16 v[52:55], v[162:165], v[186:189], v[52:55]
	v_mfma_f32_16x16x32_bf16 v[44:47], v[154:157], v[194:197], v[44:47]
	v_mfma_f32_16x16x32_bf16 v[36:39], v[162:165], v[194:197], v[36:39]
	v_mfma_f32_16x16x32_bf16 v[28:31], v[154:157], v[202:205], v[28:31]
	v_mfma_f32_16x16x32_bf16 v[20:23], v[162:165], v[202:205], v[20:23]
	v_mfma_f32_16x16x32_bf16 v[12:15], v[154:157], v[210:213], v[12:15]
	v_mfma_f32_16x16x32_bf16 v[4:7], v[162:165], v[210:213], v[4:7]
	v_mfma_f32_16x16x32_bf16 v[60:63], v[158:161], v[190:193], v[60:63]
	v_mfma_f32_16x16x32_bf16 v[52:55], v[166:169], v[190:193], v[52:55]
	v_mfma_f32_16x16x32_bf16 v[44:47], v[158:161], v[198:201], v[44:47]
	v_mfma_f32_16x16x32_bf16 v[36:39], v[166:169], v[198:201], v[36:39]
	v_mfma_f32_16x16x32_bf16 v[28:31], v[158:161], v[206:209], v[28:31]
	v_mfma_f32_16x16x32_bf16 v[20:23], v[166:169], v[206:209], v[20:23]
	v_mfma_f32_16x16x32_bf16 v[12:15], v[158:161], v[214:217], v[12:15]
	v_mfma_f32_16x16x32_bf16 v[4:7], v[166:169], v[214:217], v[4:7]
	v_mfma_f32_16x16x32_bf16 v[56:59], v[170:173], v[186:189], v[56:59]
	v_mfma_f32_16x16x32_bf16 v[48:51], v[178:181], v[186:189], v[48:51]
	v_mfma_f32_16x16x32_bf16 v[40:43], v[170:173], v[194:197], v[40:43]
	v_mfma_f32_16x16x32_bf16 v[32:35], v[178:181], v[194:197], v[32:35]
	v_mfma_f32_16x16x32_bf16 v[24:27], v[170:173], v[202:205], v[24:27]
	v_mfma_f32_16x16x32_bf16 v[16:19], v[178:181], v[202:205], v[16:19]
	v_mfma_f32_16x16x32_bf16 v[8:11], v[170:173], v[210:213], v[8:11]
	v_mfma_f32_16x16x32_bf16 v[0:3], v[178:181], v[210:213], v[0:3]
	v_mfma_f32_16x16x32_bf16 v[56:59], v[174:177], v[190:193], v[56:59]
	v_mfma_f32_16x16x32_bf16 v[48:51], v[182:185], v[190:193], v[48:51]
	v_mfma_f32_16x16x32_bf16 v[40:43], v[174:177], v[198:201], v[40:43]
	v_mfma_f32_16x16x32_bf16 v[32:35], v[182:185], v[198:201], v[32:35]
	v_mfma_f32_16x16x32_bf16 v[24:27], v[174:177], v[206:209], v[24:27]
	v_mfma_f32_16x16x32_bf16 v[16:19], v[182:185], v[206:209], v[16:19]
	v_mfma_f32_16x16x32_bf16 v[8:11], v[174:177], v[214:217], v[8:11]
	v_mfma_f32_16x16x32_bf16 v[0:3], v[182:185], v[214:217], v[0:3]
	s_barrier
	s_add_i32 s69, 0, 0x18000
	v_add_u32_e32 v153, s69, v147
	s_add_i32 s70, 0, 0x1c000
	ds_read_b128 v[154:157], v153
	ds_read_b128 v[158:161], v153 offset:1024
	ds_read_b128 v[162:165], v153 offset:2048
	ds_read_b128 v[166:169], v153 offset:3072
	v_add_u32_e32 v153, s70, v147
	ds_read_b128 v[170:173], v153
	ds_read_b128 v[174:177], v153 offset:1024
	ds_read_b128 v[178:181], v153 offset:2048
	ds_read_b128 v[182:185], v153 offset:3072
	s_add_u32 s42, s42, 0x40000
	s_addc_u32 s43, s43, 0
	s_mov_b32 m0, s51
	v_lshl_add_u64 v[224:225], s[42:43], 0, v[134:135]
	ds_read_b128 v[186:189], v151 offset:32768
	ds_read_b128 v[190:193], v151 offset:33792
	ds_read_b128 v[194:197], v151 offset:34816
	ds_read_b128 v[198:201], v151 offset:35840
	ds_read_b128 v[202:205], v151 offset:36864
	ds_read_b128 v[206:209], v151 offset:37888
	ds_read_b128 v[210:213], v151 offset:38912
	ds_read_b128 v[214:217], v151 offset:39936
	global_load_lds_dwordx4 v[224:225], off
	v_lshl_add_u64 v[224:225], s[42:43], 0, v[130:131]
	s_mov_b32 m0, s52
	s_nop 0
	global_load_lds_dwordx4 v[224:225], off
	s_waitcnt vmcnt(8)
	s_waitcnt lgkmcnt(0)
	s_barrier
	v_mfma_f32_16x16x32_bf16 v[120:123], v[154:157], v[186:189], v[120:123]
	v_mfma_f32_16x16x32_bf16 v[116:119], v[162:165], v[186:189], v[116:119]
	v_mfma_f32_16x16x32_bf16 v[108:111], v[154:157], v[194:197], v[108:111]
	v_mfma_f32_16x16x32_bf16 v[100:103], v[162:165], v[194:197], v[100:103]
	v_mfma_f32_16x16x32_bf16 v[92:95], v[154:157], v[202:205], v[92:95]
	v_mfma_f32_16x16x32_bf16 v[84:87], v[162:165], v[202:205], v[84:87]
	v_mfma_f32_16x16x32_bf16 v[76:79], v[154:157], v[210:213], v[76:79]
	v_mfma_f32_16x16x32_bf16 v[68:71], v[162:165], v[210:213], v[68:71]
	v_mfma_f32_16x16x32_bf16 v[120:123], v[158:161], v[190:193], v[120:123]
	v_mfma_f32_16x16x32_bf16 v[116:119], v[166:169], v[190:193], v[116:119]
	v_mfma_f32_16x16x32_bf16 v[108:111], v[158:161], v[198:201], v[108:111]
	v_mfma_f32_16x16x32_bf16 v[100:103], v[166:169], v[198:201], v[100:103]
	v_mfma_f32_16x16x32_bf16 v[92:95], v[158:161], v[206:209], v[92:95]
	v_mfma_f32_16x16x32_bf16 v[84:87], v[166:169], v[206:209], v[84:87]
	v_mfma_f32_16x16x32_bf16 v[76:79], v[158:161], v[214:217], v[76:79]
	v_mfma_f32_16x16x32_bf16 v[68:71], v[166:169], v[214:217], v[68:71]
	v_mfma_f32_16x16x32_bf16 v[124:127], v[170:173], v[186:189], v[124:127]
	v_mfma_f32_16x16x32_bf16 v[112:115], v[178:181], v[186:189], v[112:115]
	v_mfma_f32_16x16x32_bf16 v[104:107], v[170:173], v[194:197], v[104:107]
	v_mfma_f32_16x16x32_bf16 v[96:99], v[178:181], v[194:197], v[96:99]
	v_mfma_f32_16x16x32_bf16 v[88:91], v[170:173], v[202:205], v[88:91]
	v_mfma_f32_16x16x32_bf16 v[80:83], v[178:181], v[202:205], v[80:83]
	v_mfma_f32_16x16x32_bf16 v[72:75], v[170:173], v[210:213], v[72:75]
	v_mfma_f32_16x16x32_bf16 v[64:67], v[178:181], v[210:213], v[64:67]
	v_mfma_f32_16x16x32_bf16 v[124:127], v[174:177], v[190:193], v[124:127]
	v_mfma_f32_16x16x32_bf16 v[112:115], v[182:185], v[190:193], v[112:115]
	v_mfma_f32_16x16x32_bf16 v[104:107], v[174:177], v[198:201], v[104:107]
	v_mfma_f32_16x16x32_bf16 v[96:99], v[182:185], v[198:201], v[96:99]
	v_mfma_f32_16x16x32_bf16 v[88:91], v[174:177], v[206:209], v[88:91]
	v_mfma_f32_16x16x32_bf16 v[80:83], v[182:185], v[206:209], v[80:83]
	v_mfma_f32_16x16x32_bf16 v[72:75], v[174:177], v[214:217], v[72:75]
	v_mfma_f32_16x16x32_bf16 v[64:67], v[182:185], v[214:217], v[64:67]
	s_barrier
; #define PG8_STAGE(bufoff, gbase, voff) do { _Pragma("unroll") for (int _i = 0; _i < 2; ++_i) \
;         __builtin_amdgcn_global_load_lds((const unsigned*)((const char*)(gbase) + (voff)[_i]), (PG8_LAS unsigned*)(lds + (bufoff) + ldsw + _i * 8192), 16, 0, 0); } while (0)
; #define PG8_LDA(dst, b, h) do { _Pragma("unroll") for (int m = 0; m < 4; ++m) _Pragma("unroll") for (int k = 0; k < 2; ++k) dst[m][k] = *(const PG8_LAS bf16x8*)(lds + PG8_SA(b, h) + aoff + m * 2048 + k * 1024); } while (0)
; #define PG8_MMA(ai, bj, At, Bt) do { __builtin_amdgcn_s_setprio(1); _Pragma("unroll") for (int m = 0; m < 4; ++m) _Pragma("unroll") for (int n = 0; n < 2; ++n) _Pragma("unroll") for (int k = 0; k < 2; ++k) \
;         acc[ai][bj][m][n] = __builtin_amdgcn_mfma_f32_16x16x32_bf16(Bt[n][k], At[m][k], acc[ai][bj][m][n], 0, 0, 0); __builtin_amdgcn_s_setprio(0); } while (0)
; #define PG8_WAIT_V(n) asm volatile("s_waitcnt vmcnt(" #n ")" ::: "memory")
; #define PG8_WAIT_L(n) asm volatile("s_waitcnt lgkmcnt(" #n ")" ::: "memory")
; #define PG8_BAR __builtin_amdgcn_s_barrier()
; #define PG8_SCHED __builtin_amdgcn_sched_barrier(0)
; template <class Epi, class Sched, bool ALIGN_EPI = false, bool SP2 = false>
; __device__ __forceinline__ void gemm_phase(PG8_LAS unsigned char* lds, const Gemm g, const Sched& S, const Epi& E) {
;     ...
;             PG8_LDA(At, 1, 1); PG8_STAGE(PG8_SB(1, 0), b3, voffB); PG8_STAGE(PG8_SB(1, 1), b3 + hstep, voffB); PG8_STAGE(PG8_SA(1, 0), a3, voffA);
;             PG8_WAIT_V(8); PG8_WAIT_L(0); PG8_BAR; PG8_MMA(1, 0, At, B0); PG8_MMA(1, 1, At, B1); PG8_BAR; PG8_SCHED;
;     ...
;         if constexpr (ALIGN_EPI) { if (wr == 0) PG8_BAR; }
	s_add_i32 s42, s69, s48
	v_lshl_add_u64 v[144:145], v[144:145], 0, s[14:15]
	s_mov_b32 m0, s42
	ds_read_b128 v[186:189], v151 offset:49152
	ds_read_b128 v[190:193], v151 offset:50176
	ds_read_b128 v[194:197], v151 offset:51200
	ds_read_b128 v[198:201], v151 offset:52224
	ds_read_b128 v[202:205], v151 offset:53248
	ds_read_b128 v[206:209], v151 offset:54272
	ds_read_b128 v[210:213], v151 offset:55296
	ds_read_b128 v[214:217], v151 offset:56320
	global_load_lds_dwordx4 v[144:145], off
	s_add_i32 m0, s42, 0x2000
	s_add_u32 s40, s40, 0x40080
	v_lshl_add_u64 v[144:145], v[218:219], 0, s[14:15]
	s_addc_u32 s41, s41, 0
	s_add_i32 s42, s70, s48
	global_load_lds_dwordx4 v[144:145], off
	v_lshl_add_u64 v[144:145], s[40:41], 0, v[132:133]
	s_mov_b32 m0, s42
	s_nop 0
	global_load_lds_dwordx4 v[144:145], off
	v_lshl_add_u64 v[144:145], s[40:41], 0, v[128:129]
	s_add_i32 m0, s42, 0x2000
	s_nop 0
	global_load_lds_dwordx4 v[144:145], off
	v_lshl_add_u64 v[144:145], v[220:221], 0, s[14:15]
	s_mov_b32 m0, s53
	s_nop 0
	global_load_lds_dwordx4 v[144:145], off
	v_lshl_add_u64 v[144:145], v[222:223], 0, s[14:15]
	s_mov_b32 m0, s54
	s_nop 0
	global_load_lds_dwordx4 v[144:145], off
	s_waitcnt vmcnt(8)
	s_waitcnt lgkmcnt(0)
	s_barrier
	v_mfma_f32_16x16x32_bf16 v[60:63], v[154:157], v[186:189], v[60:63]
	v_mfma_f32_16x16x32_bf16 v[52:55], v[162:165], v[186:189], v[52:55]
	v_mfma_f32_16x16x32_bf16 v[44:47], v[154:157], v[194:197], v[44:47]
	v_mfma_f32_16x16x32_bf16 v[36:39], v[162:165], v[194:197], v[36:39]
	v_mfma_f32_16x16x32_bf16 v[28:31], v[154:157], v[202:205], v[28:31]
	v_mfma_f32_16x16x32_bf16 v[20:23], v[162:165], v[202:205], v[20:23]
	v_mfma_f32_16x16x32_bf16 v[12:15], v[154:157], v[210:213], v[12:15]
	v_mfma_f32_16x16x32_bf16 v[4:7], v[162:165], v[210:213], v[4:7]
	v_mfma_f32_16x16x32_bf16 v[60:63], v[158:161], v[190:193], v[60:63]
	v_mfma_f32_16x16x32_bf16 v[52:55], v[166:169], v[190:193], v[52:55]
	v_mfma_f32_16x16x32_bf16 v[44:47], v[158:161], v[198:201], v[44:47]
	v_mfma_f32_16x16x32_bf16 v[36:39], v[166:169], v[198:201], v[36:39]
	v_mfma_f32_16x16x32_bf16 v[28:31], v[158:161], v[206:209], v[28:31]
	v_mfma_f32_16x16x32_bf16 v[20:23], v[166:169], v[206:209], v[20:23]
	v_mfma_f32_16x16x32_bf16 v[12:15], v[158:161], v[214:217], v[12:15]
	v_mfma_f32_16x16x32_bf16 v[4:7], v[166:169], v[214:217], v[4:7]
	v_mfma_f32_16x16x32_bf16 v[56:59], v[170:173], v[186:189], v[56:59]
	v_mfma_f32_16x16x32_bf16 v[48:51], v[178:181], v[186:189], v[48:51]
	v_mfma_f32_16x16x32_bf16 v[40:43], v[170:173], v[194:197], v[40:43]
	v_mfma_f32_16x16x32_bf16 v[32:35], v[178:181], v[194:197], v[32:35]
	v_mfma_f32_16x16x32_bf16 v[24:27], v[170:173], v[202:205], v[24:27]
	v_mfma_f32_16x16x32_bf16 v[16:19], v[178:181], v[202:205], v[16:19]
	v_mfma_f32_16x16x32_bf16 v[8:11], v[170:173], v[210:213], v[8:11]
	v_mfma_f32_16x16x32_bf16 v[0:3], v[178:181], v[210:213], v[0:3]
	v_mfma_f32_16x16x32_bf16 v[56:59], v[174:177], v[190:193], v[56:59]
	v_mfma_f32_16x16x32_bf16 v[48:51], v[182:185], v[190:193], v[48:51]
	v_mfma_f32_16x16x32_bf16 v[40:43], v[174:177], v[198:201], v[40:43]
	v_mfma_f32_16x16x32_bf16 v[32:35], v[182:185], v[198:201], v[32:35]
	v_mfma_f32_16x16x32_bf16 v[24:27], v[174:177], v[206:209], v[24:27]
	v_mfma_f32_16x16x32_bf16 v[16:19], v[182:185], v[206:209], v[16:19]
	v_mfma_f32_16x16x32_bf16 v[8:11], v[174:177], v[214:217], v[8:11]
	v_mfma_f32_16x16x32_bf16 v[0:3], v[182:185], v[214:217], v[0:3]
	s_barrier
	s_add_i32 s68, s68, 2
	s_add_u32 s38, s38, 0x100
	s_addc_u32 s39, s39, 0
	s_add_u32 s66, s66, 0x100
	s_addc_u32 s67, s67, 0
	s_cmp_gt_u32 s68, 13
	s_cbranch_scc0 .LBB0_1194
	s_and_b64 vcc, exec, s[16:17]
	s_cbranch_vccz .LBB0_1197
	s_barrier

; #define PG8_STAGE(bufoff, gbase, voff) do { _Pragma("unroll") for (int _i = 0; _i < 2; ++_i) \
;         __builtin_amdgcn_global_load_lds((const unsigned*)((const char*)(gbase) + (voff)[_i]), (PG8_LAS unsigned*)(lds + (bufoff) + ldsw + _i * 8192), 16, 0, 0); } while (0)
; #define PG8_LDA(dst, b, h) do { _Pragma("unroll") for (int m = 0; m < 4; ++m) _Pragma("unroll") for (int k = 0; k < 2; ++k) dst[m][k] = *(const PG8_LAS bf16x8*)(lds + PG8_SA(b, h) + aoff + m * 2048 + k * 1024); } while (0)
; #define PG8_LDB(dst, b, h) do { _Pragma("unroll") for (int n = 0; n < 2; ++n) _Pragma("unroll") for (int k = 0; k < 2; ++k) dst[n][k] = *(const PG8_LAS bf16x8*)(lds + PG8_SB(b, h) + boff + n * 2048 + k * 1024); } while (0)
; #define PG8_MMA(ai, bj, At, Bt) do { __builtin_amdgcn_s_setprio(1); _Pragma("unroll") for (int m = 0; m < 4; ++m) _Pragma("unroll") for (int n = 0; n < 2; ++n) _Pragma("unroll") for (int k = 0; k < 2; ++k) \
;         acc[ai][bj][m][n] = __builtin_amdgcn_mfma_f32_16x16x32_bf16(Bt[n][k], At[m][k], acc[ai][bj][m][n], 0, 0, 0); __builtin_amdgcn_s_setprio(0); } while (0)
; template <class Epi, class Sched, bool ALIGN_EPI = false, bool SP2 = false>
; __device__ __forceinline__ void gemm_phase(PG8_LAS unsigned char* lds, const Gemm g, const Sched& S, const Epi& E) {
;     ...
;         for (int t = 0; t < nt; t += 2) {
;             const bool last = (t == nt - 2);
;             if constexpr (Epi::PREFETCH) { if (t == nt - 4) E.prefetch(cur, lds + STAGE_BYTES + 1024, tid); }
;             const char* a1 = cA + (size_t)(t + 1) * kstep;
;             const char* a2 = last ? nA : cA + (size_t)(t + 2) * kstep; const char* b2 = last ? nB : cB + (size_t)(t + 2) * kstep;
;             const char* a3 = a2 + kstep; const char* b3 = b2 + kstep;
;             if (last && has_next) S.a_ready(nxt);
;             if constexpr (SP2) {
;             PG8_LDB(B0, 0, 0); PG8_LDB(B1, 0, 1); PG8_SCHED; PG8_LDA(At, 0, 0); PG8_STAGE(PG8_SA(1, 1), a1 + hstep, voffA);
;             PG8_WAIT_V(8); PG8_WAIT_L(0); PG8_BAR; PG8_MMA(0, 0, At, B0); PG8_MMA(0, 1, At, B1); PG8_BAR; PG8_SCHED;
;             PG8_LDA(At, 0, 1); PG8_STAGE(PG8_SB(0, 0), b2, voffB); PG8_STAGE(PG8_SB(0, 1), b2 + hstep, voffB); PG8_STAGE(PG8_SA(0, 0), a2, voffA);
;             PG8_WAIT_V(8); PG8_WAIT_L(0); PG8_BAR; PG8_MMA(1, 0, At, B0); PG8_MMA(1, 1, At, B1); PG8_BAR; PG8_SCHED;
.LBB0_1906:
	ds_read_b128 v[144:147], v151
	ds_read_b128 v[156:159], v151 offset:1024
	ds_read_b128 v[160:163], v151 offset:2048
	ds_read_b128 v[164:167], v151 offset:3072
	ds_read_b128 v[168:171], v152
	ds_read_b128 v[172:175], v152 offset:1024
	ds_read_b128 v[176:179], v152 offset:2048
	ds_read_b128 v[180:183], v152 offset:3072
	s_add_u32 s40, s38, 0xfffc0080
	s_addc_u32 s41, s39, -1
	s_cmp_eq_u32 s68, 12
	s_cselect_b32 s43, s21, s41
	s_cselect_b32 s42, s64, s40
	s_cselect_b32 s41, s19, s67
	s_cselect_b32 s40, s65, s66
	v_lshl_add_u64 v[216:217], s[38:39], 0, v[136:137]
	s_add_i32 m0, s37, 0xc000
	ds_read_b128 v[184:187], v153
	ds_read_b128 v[188:191], v153 offset:1024
	ds_read_b128 v[192:195], v153 offset:2048
	ds_read_b128 v[196:199], v153 offset:3072
	ds_read_b128 v[200:203], v153 offset:4096
	ds_read_b128 v[204:207], v153 offset:5120
	ds_read_b128 v[208:211], v153 offset:6144
	ds_read_b128 v[212:215], v153 offset:7168
	global_load_lds_dwordx4 v[216:217], off
	v_lshl_add_u64 v[216:217], s[38:39], 0, v[138:139]
	s_add_i32 m0, s37, 0xe000
	s_nop 0
	global_load_lds_dwordx4 v[216:217], off
	s_waitcnt vmcnt(8)
	s_waitcnt lgkmcnt(0)
	s_barrier
	v_mfma_f32_16x16x32_bf16 v[124:127], v[144:147], v[184:187], v[124:127]
	v_mfma_f32_16x16x32_bf16 v[120:123], v[160:163], v[184:187], v[120:123]
	v_mfma_f32_16x16x32_bf16 v[108:111], v[144:147], v[192:195], v[108:111]
	v_mfma_f32_16x16x32_bf16 v[104:107], v[160:163], v[192:195], v[104:107]
	v_mfma_f32_16x16x32_bf16 v[92:95], v[144:147], v[200:203], v[92:95]
	v_mfma_f32_16x16x32_bf16 v[88:91], v[160:163], v[200:203], v[88:91]
	v_mfma_f32_16x16x32_bf16 v[76:79], v[144:147], v[208:211], v[76:79]
	v_mfma_f32_16x16x32_bf16 v[72:75], v[160:163], v[208:211], v[72:75]
	v_mfma_f32_16x16x32_bf16 v[124:127], v[156:159], v[188:191], v[124:127]
	v_mfma_f32_16x16x32_bf16 v[120:123], v[164:167], v[188:191], v[120:123]
	v_mfma_f32_16x16x32_bf16 v[108:111], v[156:159], v[196:199], v[108:111]
	v_mfma_f32_16x16x32_bf16 v[104:107], v[164:167], v[196:199], v[104:107]
	v_mfma_f32_16x16x32_bf16 v[92:95], v[156:159], v[204:207], v[92:95]
	v_mfma_f32_16x16x32_bf16 v[88:91], v[164:167], v[204:207], v[88:91]
	v_mfma_f32_16x16x32_bf16 v[76:79], v[156:159], v[212:215], v[76:79]
	v_mfma_f32_16x16x32_bf16 v[72:75], v[164:167], v[212:215], v[72:75]
	v_mfma_f32_16x16x32_bf16 v[116:119], v[168:171], v[184:187], v[116:119]
	v_mfma_f32_16x16x32_bf16 v[112:115], v[176:179], v[184:187], v[112:115]
	v_mfma_f32_16x16x32_bf16 v[100:103], v[168:171], v[192:195], v[100:103]
	v_mfma_f32_16x16x32_bf16 v[96:99], v[176:179], v[192:195], v[96:99]
	v_mfma_f32_16x16x32_bf16 v[84:87], v[168:171], v[200:203], v[84:87]
	v_mfma_f32_16x16x32_bf16 v[80:83], v[176:179], v[200:203], v[80:83]
	v_mfma_f32_16x16x32_bf16 v[68:71], v[168:171], v[208:211], v[68:71]
	v_mfma_f32_16x16x32_bf16 v[64:67], v[176:179], v[208:211], v[64:67]
	v_mfma_f32_16x16x32_bf16 v[116:119], v[172:175], v[188:191], v[116:119]
	v_mfma_f32_16x16x32_bf16 v[112:115], v[180:183], v[188:191], v[112:115]
	v_mfma_f32_16x16x32_bf16 v[100:103], v[172:175], v[196:199], v[100:103]
	v_mfma_f32_16x16x32_bf16 v[96:99], v[180:183], v[196:199], v[96:99]
	v_mfma_f32_16x16x32_bf16 v[84:87], v[172:175], v[204:207], v[84:87]
	v_mfma_f32_16x16x32_bf16 v[80:83], v[180:183], v[204:207], v[80:83]
	v_mfma_f32_16x16x32_bf16 v[68:71], v[172:175], v[212:215], v[68:71]
	v_mfma_f32_16x16x32_bf16 v[64:67], v[180:183], v[212:215], v[64:67]
	s_barrier
	s_add_i32 s69, s57, s48
	v_lshl_add_u64 v[216:217], s[40:41], 0, v[132:133]
	s_mov_b32 m0, s69
	ds_read_b128 v[184:187], v153 offset:16384
	ds_read_b128 v[188:191], v153 offset:17408
	ds_read_b128 v[192:195], v153 offset:18432
	ds_read_b128 v[196:199], v153 offset:19456
	ds_read_b128 v[200:203], v153 offset:20480
	ds_read_b128 v[204:207], v153 offset:21504
	ds_read_b128 v[208:211], v153 offset:22528
	ds_read_b128 v[212:215], v153 offset:23552
	global_load_lds_dwordx4 v[216:217], off
	s_add_i32 m0, s69, 0x2000
	s_add_u32 s70, s40, 0x40000
	v_lshl_add_u64 v[218:219], s[40:41], 0, v[128:129]
	s_addc_u32 s71, s41, 0
	s_add_i32 s69, s58, s48
	global_load_lds_dwordx4 v[218:219], off
	v_lshl_add_u64 v[220:221], s[70:71], 0, v[132:133]
	s_mov_b32 m0, s69
	v_lshl_add_u64 v[222:223], s[42:43], 0, v[130:131]
	global_load_lds_dwordx4 v[220:221], off
	v_lshl_add_u64 v[220:221], s[70:71], 0, v[128:129]
	s_add_i32 m0, s69, 0x2000
	s_nop 0
	global_load_lds_dwordx4 v[220:221], off
	v_lshl_add_u64 v[220:221], s[42:43], 0, v[134:135]
	s_mov_b32 m0, s37
	s_nop 0
	global_load_lds_dwordx4 v[220:221], off
	s_mov_b32 m0, s50
	s_nop 0
	global_load_lds_dwordx4 v[222:223], off
	s_waitcnt vmcnt(8)
	s_waitcnt lgkmcnt(0)
	s_barrier
; #define PG8_STAGE(bufoff, gbase, voff) do { _Pragma("unroll") for (int _i = 0; _i < 2; ++_i) \
;         __builtin_amdgcn_global_load_lds((const unsigned*)((const char*)(gbase) + (voff)[_i]), (PG8_LAS unsigned*)(lds + (bufoff) + ldsw + _i * 8192), 16, 0, 0); } while (0)
; #define PG8_LDA(dst, b, h) do { _Pragma("unroll") for (int m = 0; m < 4; ++m) _Pragma("unroll") for (int k = 0; k < 2; ++k) dst[m][k] = *(const PG8_LAS bf16x8*)(lds + PG8_SA(b, h) + aoff + m * 2048 + k * 1024); } while (0)
; #define PG8_LDB(dst, b, h) do { _Pragma("unroll") for (int n = 0; n < 2; ++n) _Pragma("unroll") for (int k = 0; k < 2; ++k) dst[n][k] = *(const PG8_LAS bf16x8*)(lds + PG8_SB(b, h) + boff + n * 2048 + k * 1024); } while (0)
; #define PG8_MMA(ai, bj, At, Bt) do { __builtin_amdgcn_s_setprio(1); _Pragma("unroll") for (int m = 0; m < 4; ++m) _Pragma("unroll") for (int n = 0; n < 2; ++n) _Pragma("unroll") for (int k = 0; k < 2; ++k) \
;         acc[ai][bj][m][n] = __builtin_amdgcn_mfma_f32_16x16x32_bf16(Bt[n][k], At[m][k], acc[ai][bj][m][n], 0, 0, 0); __builtin_amdgcn_s_setprio(0); } while (0)
; #define PG8_WAIT_V(n) asm volatile("s_waitcnt vmcnt(" #n ")" ::: "memory")
; #define PG8_WAIT_L(n) asm volatile("s_waitcnt lgkmcnt(" #n ")" ::: "memory")
; #define PG8_BAR __builtin_amdgcn_s_barrier()
; #define PG8_SCHED __builtin_amdgcn_sched_barrier(0)
; template <class Epi, class Sched, bool ALIGN_EPI = false, bool SP2 = false>
; __device__ __forceinline__ void gemm_phase(PG8_LAS unsigned char* lds, const Gemm g, const Sched& S, const Epi& E) {
;     ...
;             PG8_WAIT_V(8); PG8_WAIT_L(0); PG8_BAR; PG8_MMA(1, 0, At, B0); PG8_MMA(1, 1, At, B1); PG8_BAR; PG8_SCHED;
;             PG8_LDB(B0, 1, 0); PG8_LDB(B1, 1, 1); PG8_SCHED; PG8_LDA(At, 1, 0); PG8_STAGE(PG8_SA(0, 1), a2 + hstep, voffA);
;             PG8_WAIT_V(8); PG8_WAIT_L(0); PG8_BAR; PG8_MMA(0, 0, At, B0); PG8_MMA(0, 1, At, B1); PG8_BAR; PG8_SCHED;
	v_mfma_f32_16x16x32_bf16 v[60:63], v[144:147], v[184:187], v[60:63]
	v_mfma_f32_16x16x32_bf16 v[56:59], v[160:163], v[184:187], v[56:59]
	v_mfma_f32_16x16x32_bf16 v[44:47], v[144:147], v[192:195], v[44:47]
	v_mfma_f32_16x16x32_bf16 v[40:43], v[160:163], v[192:195], v[40:43]
	v_mfma_f32_16x16x32_bf16 v[28:31], v[144:147], v[200:203], v[28:31]
	v_mfma_f32_16x16x32_bf16 v[24:27], v[160:163], v[200:203], v[24:27]
	v_mfma_f32_16x16x32_bf16 v[12:15], v[144:147], v[208:211], v[12:15]
	v_mfma_f32_16x16x32_bf16 v[8:11], v[160:163], v[208:211], v[8:11]
	v_mfma_f32_16x16x32_bf16 v[60:63], v[156:159], v[188:191], v[60:63]
	v_mfma_f32_16x16x32_bf16 v[56:59], v[164:167], v[188:191], v[56:59]
	v_mfma_f32_16x16x32_bf16 v[44:47], v[156:159], v[196:199], v[44:47]
	v_mfma_f32_16x16x32_bf16 v[40:43], v[164:167], v[196:199], v[40:43]
	v_mfma_f32_16x16x32_bf16 v[28:31], v[156:159], v[204:207], v[28:31]
	v_mfma_f32_16x16x32_bf16 v[24:27], v[164:167], v[204:207], v[24:27]
	v_mfma_f32_16x16x32_bf16 v[12:15], v[156:159], v[212:215], v[12:15]
	v_mfma_f32_16x16x32_bf16 v[8:11], v[164:167], v[212:215], v[8:11]
	v_mfma_f32_16x16x32_bf16 v[52:55], v[168:171], v[184:187], v[52:55]
	v_mfma_f32_16x16x32_bf16 v[48:51], v[176:179], v[184:187], v[48:51]
	v_mfma_f32_16x16x32_bf16 v[36:39], v[168:171], v[192:195], v[36:39]
	v_mfma_f32_16x16x32_bf16 v[32:35], v[176:179], v[192:195], v[32:35]
	v_mfma_f32_16x16x32_bf16 v[20:23], v[168:171], v[200:203], v[20:23]
	v_mfma_f32_16x16x32_bf16 v[16:19], v[176:179], v[200:203], v[16:19]
	v_mfma_f32_16x16x32_bf16 v[4:7], v[168:171], v[208:211], v[4:7]
	v_mfma_f32_16x16x32_bf16 v[0:3], v[176:179], v[208:211], v[0:3]
	v_mfma_f32_16x16x32_bf16 v[52:55], v[172:175], v[188:191], v[52:55]
	v_mfma_f32_16x16x32_bf16 v[48:51], v[180:183], v[188:191], v[48:51]
	v_mfma_f32_16x16x32_bf16 v[36:39], v[172:175], v[196:199], v[36:39]
	v_mfma_f32_16x16x32_bf16 v[32:35], v[180:183], v[196:199], v[32:35]
	v_mfma_f32_16x16x32_bf16 v[20:23], v[172:175], v[204:207], v[20:23]
	v_mfma_f32_16x16x32_bf16 v[16:19], v[180:183], v[204:207], v[16:19]
	v_mfma_f32_16x16x32_bf16 v[4:7], v[172:175], v[212:215], v[4:7]
	v_mfma_f32_16x16x32_bf16 v[0:3], v[180:183], v[212:215], v[0:3]
	s_barrier
	s_add_i32 s69, 0, 0x18000
	s_add_i32 s70, 0, 0x1c000
	v_add_u32_e32 v164, s69, v149
	v_add_u32_e32 v180, s70, v149
	ds_read_b128 v[144:147], v164
	ds_read_b128 v[156:159], v164 offset:1024
	ds_read_b128 v[160:163], v164 offset:2048
	ds_read_b128 v[164:167], v164 offset:3072
	ds_read_b128 v[168:171], v180
	ds_read_b128 v[172:175], v180 offset:1024
	ds_read_b128 v[176:179], v180 offset:2048
	ds_read_b128 v[180:183], v180 offset:3072
	s_add_u32 s42, s42, 0x40000
	s_addc_u32 s43, s43, 0
	s_mov_b32 m0, s51
	v_lshl_add_u64 v[224:225], s[42:43], 0, v[134:135]
	ds_read_b128 v[184:187], v153 offset:32768
	ds_read_b128 v[188:191], v153 offset:33792
	ds_read_b128 v[192:195], v153 offset:34816
	ds_read_b128 v[196:199], v153 offset:35840
	ds_read_b128 v[200:203], v153 offset:36864
	ds_read_b128 v[204:207], v153 offset:37888
	ds_read_b128 v[208:211], v153 offset:38912
	ds_read_b128 v[212:215], v153 offset:39936
	global_load_lds_dwordx4 v[224:225], off
	v_lshl_add_u64 v[224:225], s[42:43], 0, v[130:131]
	s_mov_b32 m0, s52
	s_nop 0
	global_load_lds_dwordx4 v[224:225], off
	s_waitcnt vmcnt(8)
	s_waitcnt lgkmcnt(0)
	s_barrier
	v_mfma_f32_16x16x32_bf16 v[124:127], v[144:147], v[184:187], v[124:127]
	v_mfma_f32_16x16x32_bf16 v[120:123], v[160:163], v[184:187], v[120:123]
	v_mfma_f32_16x16x32_bf16 v[108:111], v[144:147], v[192:195], v[108:111]
	v_mfma_f32_16x16x32_bf16 v[104:107], v[160:163], v[192:195], v[104:107]
	v_mfma_f32_16x16x32_bf16 v[92:95], v[144:147], v[200:203], v[92:95]
	v_mfma_f32_16x16x32_bf16 v[88:91], v[160:163], v[200:203], v[88:91]
	v_mfma_f32_16x16x32_bf16 v[76:79], v[144:147], v[208:211], v[76:79]
	v_mfma_f32_16x16x32_bf16 v[72:75], v[160:163], v[208:211], v[72:75]
	v_mfma_f32_16x16x32_bf16 v[124:127], v[156:159], v[188:191], v[124:127]
	v_mfma_f32_16x16x32_bf16 v[120:123], v[164:167], v[188:191], v[120:123]
	v_mfma_f32_16x16x32_bf16 v[108:111], v[156:159], v[196:199], v[108:111]
	v_mfma_f32_16x16x32_bf16 v[104:107], v[164:167], v[196:199], v[104:107]
	v_mfma_f32_16x16x32_bf16 v[92:95], v[156:159], v[204:207], v[92:95]
	v_mfma_f32_16x16x32_bf16 v[88:91], v[164:167], v[204:207], v[88:91]
	v_mfma_f32_16x16x32_bf16 v[76:79], v[156:159], v[212:215], v[76:79]
	v_mfma_f32_16x16x32_bf16 v[72:75], v[164:167], v[212:215], v[72:75]
	v_mfma_f32_16x16x32_bf16 v[116:119], v[168:171], v[184:187], v[116:119]
	v_mfma_f32_16x16x32_bf16 v[112:115], v[176:179], v[184:187], v[112:115]
	v_mfma_f32_16x16x32_bf16 v[100:103], v[168:171], v[192:195], v[100:103]
	v_mfma_f32_16x16x32_bf16 v[96:99], v[176:179], v[192:195], v[96:99]
	v_mfma_f32_16x16x32_bf16 v[84:87], v[168:171], v[200:203], v[84:87]
	v_mfma_f32_16x16x32_bf16 v[80:83], v[176:179], v[200:203], v[80:83]
	v_mfma_f32_16x16x32_bf16 v[68:71], v[168:171], v[208:211], v[68:71]
	v_mfma_f32_16x16x32_bf16 v[64:67], v[176:179], v[208:211], v[64:67]
	v_mfma_f32_16x16x32_bf16 v[116:119], v[172:175], v[188:191], v[116:119]
	v_mfma_f32_16x16x32_bf16 v[112:115], v[180:183], v[188:191], v[112:115]
	v_mfma_f32_16x16x32_bf16 v[100:103], v[172:175], v[196:199], v[100:103]
	v_mfma_f32_16x16x32_bf16 v[96:99], v[180:183], v[196:199], v[96:99]
	v_mfma_f32_16x16x32_bf16 v[84:87], v[172:175], v[204:207], v[84:87]
	v_mfma_f32_16x16x32_bf16 v[80:83], v[180:183], v[204:207], v[80:83]
	v_mfma_f32_16x16x32_bf16 v[68:71], v[172:175], v[212:215], v[68:71]
	v_mfma_f32_16x16x32_bf16 v[64:67], v[180:183], v[212:215], v[64:67]
	s_barrier
; #define PG8_STAGE(bufoff, gbase, voff) do { _Pragma("unroll") for (int _i = 0; _i < 2; ++_i) \
;         __builtin_amdgcn_global_load_lds((const unsigned*)((const char*)(gbase) + (voff)[_i]), (PG8_LAS unsigned*)(lds + (bufoff) + ldsw + _i * 8192), 16, 0, 0); } while (0)
; #define PG8_LDA(dst, b, h) do { _Pragma("unroll") for (int m = 0; m < 4; ++m) _Pragma("unroll") for (int k = 0; k < 2; ++k) dst[m][k] = *(const PG8_LAS bf16x8*)(lds + PG8_SA(b, h) + aoff + m * 2048 + k * 1024); } while (0)
; #define PG8_MMA(ai, bj, At, Bt) do { __builtin_amdgcn_s_setprio(1); _Pragma("unroll") for (int m = 0; m < 4; ++m) _Pragma("unroll") for (int n = 0; n < 2; ++n) _Pragma("unroll") for (int k = 0; k < 2; ++k) \
;         acc[ai][bj][m][n] = __builtin_amdgcn_mfma_f32_16x16x32_bf16(Bt[n][k], At[m][k], acc[ai][bj][m][n], 0, 0, 0); __builtin_amdgcn_s_setprio(0); } while (0)
; #define PG8_WAIT_V(n) asm volatile("s_waitcnt vmcnt(" #n ")" ::: "memory")
; #define PG8_WAIT_L(n) asm volatile("s_waitcnt lgkmcnt(" #n ")" ::: "memory")
; #define PG8_BAR __builtin_amdgcn_s_barrier()
; #define PG8_SCHED __builtin_amdgcn_sched_barrier(0)
; template <class Epi, class Sched, bool ALIGN_EPI = false, bool SP2 = false>
; __device__ __forceinline__ void gemm_phase(PG8_LAS unsigned char* lds, const Gemm g, const Sched& S, const Epi& E) {
;     ...
;             PG8_LDA(At, 1, 1); PG8_STAGE(PG8_SB(1, 0), b3, voffB); PG8_STAGE(PG8_SB(1, 1), b3 + hstep, voffB); PG8_STAGE(PG8_SA(1, 0), a3, voffA);
;             PG8_WAIT_V(8); PG8_WAIT_L(0); PG8_BAR; PG8_MMA(1, 0, At, B0); PG8_MMA(1, 1, At, B1); PG8_BAR; PG8_SCHED;
;     ...
;         if constexpr (ALIGN_EPI) { if (wr == 0) PG8_BAR; }
	s_add_i32 s42, s69, s48
	v_lshl_add_u64 v[216:217], v[216:217], 0, s[14:15]
	s_mov_b32 m0, s42
	ds_read_b128 v[184:187], v153 offset:49152
	ds_read_b128 v[188:191], v153 offset:50176
	ds_read_b128 v[192:195], v153 offset:51200
	ds_read_b128 v[196:199], v153 offset:52224
	ds_read_b128 v[200:203], v153 offset:53248
	ds_read_b128 v[204:207], v153 offset:54272
	ds_read_b128 v[208:211], v153 offset:55296
	ds_read_b128 v[212:215], v153 offset:56320
	global_load_lds_dwordx4 v[216:217], off
	s_add_i32 m0, s42, 0x2000
	s_add_u32 s40, s40, 0x40080
	v_lshl_add_u64 v[216:217], v[218:219], 0, s[14:15]
	s_addc_u32 s41, s41, 0
	s_add_i32 s42, s70, s48
	global_load_lds_dwordx4 v[216:217], off
	v_lshl_add_u64 v[216:217], s[40:41], 0, v[132:133]
	s_mov_b32 m0, s42
	s_nop 0
	global_load_lds_dwordx4 v[216:217], off
	v_lshl_add_u64 v[216:217], s[40:41], 0, v[128:129]
	s_add_i32 m0, s42, 0x2000
	s_nop 0
	global_load_lds_dwordx4 v[216:217], off
	v_lshl_add_u64 v[216:217], v[220:221], 0, s[14:15]
	s_mov_b32 m0, s53
	s_nop 0
	global_load_lds_dwordx4 v[216:217], off
	v_lshl_add_u64 v[216:217], v[222:223], 0, s[14:15]
	s_mov_b32 m0, s54
	s_nop 0
	global_load_lds_dwordx4 v[216:217], off
	s_waitcnt vmcnt(8)
	s_waitcnt lgkmcnt(0)
	s_barrier
	v_mfma_f32_16x16x32_bf16 v[60:63], v[144:147], v[184:187], v[60:63]
	v_mfma_f32_16x16x32_bf16 v[56:59], v[160:163], v[184:187], v[56:59]
	v_mfma_f32_16x16x32_bf16 v[44:47], v[144:147], v[192:195], v[44:47]
	v_mfma_f32_16x16x32_bf16 v[40:43], v[160:163], v[192:195], v[40:43]
	v_mfma_f32_16x16x32_bf16 v[28:31], v[144:147], v[200:203], v[28:31]
	v_mfma_f32_16x16x32_bf16 v[24:27], v[160:163], v[200:203], v[24:27]
	v_mfma_f32_16x16x32_bf16 v[12:15], v[144:147], v[208:211], v[12:15]
	v_mfma_f32_16x16x32_bf16 v[8:11], v[160:163], v[208:211], v[8:11]
	v_mfma_f32_16x16x32_bf16 v[60:63], v[156:159], v[188:191], v[60:63]
	v_mfma_f32_16x16x32_bf16 v[56:59], v[164:167], v[188:191], v[56:59]
	v_mfma_f32_16x16x32_bf16 v[44:47], v[156:159], v[196:199], v[44:47]
	v_mfma_f32_16x16x32_bf16 v[40:43], v[164:167], v[196:199], v[40:43]
	v_mfma_f32_16x16x32_bf16 v[28:31], v[156:159], v[204:207], v[28:31]
	v_mfma_f32_16x16x32_bf16 v[24:27], v[164:167], v[204:207], v[24:27]
	v_mfma_f32_16x16x32_bf16 v[12:15], v[156:159], v[212:215], v[12:15]
	v_mfma_f32_16x16x32_bf16 v[8:11], v[164:167], v[212:215], v[8:11]
	v_mfma_f32_16x16x32_bf16 v[52:55], v[168:171], v[184:187], v[52:55]
	v_mfma_f32_16x16x32_bf16 v[48:51], v[176:179], v[184:187], v[48:51]
	v_mfma_f32_16x16x32_bf16 v[36:39], v[168:171], v[192:195], v[36:39]
	v_mfma_f32_16x16x32_bf16 v[32:35], v[176:179], v[192:195], v[32:35]
	v_mfma_f32_16x16x32_bf16 v[20:23], v[168:171], v[200:203], v[20:23]
	v_mfma_f32_16x16x32_bf16 v[16:19], v[176:179], v[200:203], v[16:19]
	v_mfma_f32_16x16x32_bf16 v[4:7], v[168:171], v[208:211], v[4:7]
	v_mfma_f32_16x16x32_bf16 v[0:3], v[176:179], v[208:211], v[0:3]
	v_mfma_f32_16x16x32_bf16 v[52:55], v[172:175], v[188:191], v[52:55]
	v_mfma_f32_16x16x32_bf16 v[48:51], v[180:183], v[188:191], v[48:51]
	v_mfma_f32_16x16x32_bf16 v[36:39], v[172:175], v[196:199], v[36:39]
	v_mfma_f32_16x16x32_bf16 v[32:35], v[180:183], v[196:199], v[32:35]
	v_mfma_f32_16x16x32_bf16 v[20:23], v[172:175], v[204:207], v[20:23]
	v_mfma_f32_16x16x32_bf16 v[16:19], v[180:183], v[204:207], v[16:19]
	v_mfma_f32_16x16x32_bf16 v[4:7], v[172:175], v[212:215], v[4:7]
	v_mfma_f32_16x16x32_bf16 v[0:3], v[180:183], v[212:215], v[0:3]
	s_barrier
	s_add_i32 s68, s68, 2
	s_add_u32 s38, s38, 0x100
	s_addc_u32 s39, s39, 0
	s_add_u32 s66, s66, 0x100
	s_addc_u32 s67, s67, 0
	s_cmp_gt_u32 s68, 13
	s_cbranch_scc0 .LBB0_1906
	s_and_b64 vcc, exec, s[16:17]
	s_cbranch_vccz .LBB0_1909
	s_barrier

; #define PG8_STAGE(bufoff, gbase, voff) do { _Pragma("unroll") for (int _i = 0; _i < 2; ++_i) \
;         __builtin_amdgcn_global_load_lds((const unsigned*)((const char*)(gbase) + (voff)[_i]), (PG8_LAS unsigned*)(lds + (bufoff) + ldsw + _i * 8192), 16, 0, 0); } while (0)
; #define PG8_LDA(dst, b, h) do { _Pragma("unroll") for (int m = 0; m < 4; ++m) _Pragma("unroll") for (int k = 0; k < 2; ++k) dst[m][k] = *(const PG8_LAS bf16x8*)(lds + PG8_SA(b, h) + aoff + m * 2048 + k * 1024); } while (0)
; #define PG8_LDB(dst, b, h) do { _Pragma("unroll") for (int n = 0; n < 2; ++n) _Pragma("unroll") for (int k = 0; k < 2; ++k) dst[n][k] = *(const PG8_LAS bf16x8*)(lds + PG8_SB(b, h) + boff + n * 2048 + k * 1024); } while (0)
; #define PG8_MMA(ai, bj, At, Bt) do { __builtin_amdgcn_s_setprio(1); _Pragma("unroll") for (int m = 0; m < 4; ++m) _Pragma("unroll") for (int n = 0; n < 2; ++n) _Pragma("unroll") for (int k = 0; k < 2; ++k) \
;         acc[ai][bj][m][n] = __builtin_amdgcn_mfma_f32_16x16x32_bf16(Bt[n][k], At[m][k], acc[ai][bj][m][n], 0, 0, 0); __builtin_amdgcn_s_setprio(0); } while (0)
; template <class Epi, class Sched, bool ALIGN_EPI = false, bool SP2 = false>
; __device__ __forceinline__ void gemm_phase(PG8_LAS unsigned char* lds, const Gemm g, const Sched& S, const Epi& E) {
;     ...
;         for (int t = 0; t < nt; t += 2) {
;             const bool last = (t == nt - 2);
;             if constexpr (Epi::PREFETCH) { if (t == nt - 4) E.prefetch(cur, lds + STAGE_BYTES + 1024, tid); }
;             const char* a1 = cA + (size_t)(t + 1) * kstep;
;             const char* a2 = last ? nA : cA + (size_t)(t + 2) * kstep; const char* b2 = last ? nB : cB + (size_t)(t + 2) * kstep;
;             const char* a3 = a2 + kstep; const char* b3 = b2 + kstep;
;             if (last && has_next) S.a_ready(nxt);
;             if constexpr (SP2) {
;             PG8_LDB(B0, 0, 0); PG8_LDB(B1, 0, 1); PG8_SCHED; PG8_LDA(At, 0, 0); PG8_STAGE(PG8_SA(1, 1), a1 + hstep, voffA);
;             PG8_WAIT_V(8); PG8_WAIT_L(0); PG8_BAR; PG8_MMA(0, 0, At, B0); PG8_MMA(0, 1, At, B1); PG8_BAR; PG8_SCHED;
;             PG8_LDA(At, 0, 1); PG8_STAGE(PG8_SB(0, 0), b2, voffB); PG8_STAGE(PG8_SB(0, 1), b2 + hstep, voffB); PG8_STAGE(PG8_SA(0, 0), a2, voffA);
;             PG8_WAIT_V(8); PG8_WAIT_L(0); PG8_BAR; PG8_MMA(1, 0, At, B0); PG8_MMA(1, 1, At, B1); PG8_BAR; PG8_SCHED;
.LBB0_2597:
	ds_read_b128 v[128:131], v201
	ds_read_b128 v[132:135], v201 offset:1024
	ds_read_b128 v[136:139], v201 offset:2048
	ds_read_b128 v[140:143], v201 offset:3072
	ds_read_b128 v[144:147], v202
	ds_read_b128 v[148:151], v202 offset:1024
	ds_read_b128 v[152:155], v202 offset:2048
	ds_read_b128 v[156:159], v202 offset:3072
	s_add_u32 s40, s38, 0xfff50080
	s_addc_u32 s41, s39, -1
	s_cmp_eq_u32 s68, 40
	s_cselect_b32 s43, s7, s41
	s_cselect_b32 s42, s6, s40
	s_cselect_b32 s41, s37, s67
	s_cselect_b32 s40, s36, s66
	v_lshl_add_u64 v[196:197], s[38:39], 0, v[176:177]
	s_add_i32 m0, s49, 0xc000
	ds_read_b128 v[160:163], v203
	ds_read_b128 v[164:167], v203 offset:1024
	ds_read_b128 v[184:187], v203 offset:2048
	ds_read_b128 v[188:191], v203 offset:3072
	ds_read_b128 v[192:195], v203 offset:4096
	ds_read_b128 v[204:207], v203 offset:5120
	ds_read_b128 v[208:211], v203 offset:6144
	ds_read_b128 v[212:215], v203 offset:7168
	global_load_lds_dwordx4 v[196:197], off
	v_lshl_add_u64 v[196:197], s[38:39], 0, v[178:179]
	s_add_i32 m0, s49, 0xe000
	s_nop 0
	global_load_lds_dwordx4 v[196:197], off
	s_waitcnt vmcnt(8)
	s_waitcnt lgkmcnt(0)
	s_barrier
	v_mfma_f32_16x16x32_bf16 v[124:127], v[128:131], v[160:163], v[124:127]
	v_mfma_f32_16x16x32_bf16 v[120:123], v[136:139], v[160:163], v[120:123]
	v_mfma_f32_16x16x32_bf16 v[116:119], v[128:131], v[184:187], v[116:119]
	v_mfma_f32_16x16x32_bf16 v[104:107], v[136:139], v[184:187], v[104:107]
	v_mfma_f32_16x16x32_bf16 v[92:95], v[128:131], v[192:195], v[92:95]
	v_mfma_f32_16x16x32_bf16 v[88:91], v[136:139], v[192:195], v[88:91]
	v_mfma_f32_16x16x32_bf16 v[76:79], v[128:131], v[208:211], v[76:79]
	v_mfma_f32_16x16x32_bf16 v[72:75], v[136:139], v[208:211], v[72:75]
	v_mfma_f32_16x16x32_bf16 v[124:127], v[132:135], v[164:167], v[124:127]
	v_mfma_f32_16x16x32_bf16 v[120:123], v[140:143], v[164:167], v[120:123]
	v_mfma_f32_16x16x32_bf16 v[116:119], v[132:135], v[188:191], v[116:119]
	v_mfma_f32_16x16x32_bf16 v[104:107], v[140:143], v[188:191], v[104:107]
	v_mfma_f32_16x16x32_bf16 v[92:95], v[132:135], v[204:207], v[92:95]
	v_mfma_f32_16x16x32_bf16 v[88:91], v[140:143], v[204:207], v[88:91]
	v_mfma_f32_16x16x32_bf16 v[76:79], v[132:135], v[212:215], v[76:79]
	v_mfma_f32_16x16x32_bf16 v[72:75], v[140:143], v[212:215], v[72:75]
	v_mfma_f32_16x16x32_bf16 v[112:115], v[144:147], v[160:163], v[112:115]
	v_mfma_f32_16x16x32_bf16 v[108:111], v[152:155], v[160:163], v[108:111]
	v_mfma_f32_16x16x32_bf16 v[100:103], v[144:147], v[184:187], v[100:103]
	v_mfma_f32_16x16x32_bf16 v[96:99], v[152:155], v[184:187], v[96:99]
	v_mfma_f32_16x16x32_bf16 v[84:87], v[144:147], v[192:195], v[84:87]
	v_mfma_f32_16x16x32_bf16 v[80:83], v[152:155], v[192:195], v[80:83]
	v_mfma_f32_16x16x32_bf16 v[68:71], v[144:147], v[208:211], v[68:71]
	v_mfma_f32_16x16x32_bf16 v[64:67], v[152:155], v[208:211], v[64:67]
	v_mfma_f32_16x16x32_bf16 v[112:115], v[148:151], v[164:167], v[112:115]
	v_mfma_f32_16x16x32_bf16 v[108:111], v[156:159], v[164:167], v[108:111]
	v_mfma_f32_16x16x32_bf16 v[100:103], v[148:151], v[188:191], v[100:103]
	v_mfma_f32_16x16x32_bf16 v[96:99], v[156:159], v[188:191], v[96:99]
	v_mfma_f32_16x16x32_bf16 v[84:87], v[148:151], v[204:207], v[84:87]
	v_mfma_f32_16x16x32_bf16 v[80:83], v[156:159], v[204:207], v[80:83]
	v_mfma_f32_16x16x32_bf16 v[68:71], v[148:151], v[212:215], v[68:71]
	v_mfma_f32_16x16x32_bf16 v[64:67], v[156:159], v[212:215], v[64:67]
	s_barrier
	s_add_i32 s69, s57, s48
	v_lshl_add_u64 v[196:197], s[40:41], 0, v[170:171]
	s_mov_b32 m0, s69
	ds_read_b128 v[160:163], v203 offset:16384
	ds_read_b128 v[164:167], v203 offset:17408
	ds_read_b128 v[184:187], v203 offset:18432
	ds_read_b128 v[188:191], v203 offset:19456
	ds_read_b128 v[192:195], v203 offset:20480
	ds_read_b128 v[204:207], v203 offset:21504
	ds_read_b128 v[208:211], v203 offset:22528
	ds_read_b128 v[212:215], v203 offset:23552
	global_load_lds_dwordx4 v[196:197], off
	s_add_i32 m0, s69, 0x2000
	s_add_u32 s70, s40, 0xb0000
	v_lshl_add_u64 v[216:217], s[40:41], 0, v[174:175]
	s_addc_u32 s71, s41, 0
	s_add_i32 s69, s58, s48
	global_load_lds_dwordx4 v[216:217], off
	v_lshl_add_u64 v[218:219], s[70:71], 0, v[170:171]
	s_mov_b32 m0, s69
	v_lshl_add_u64 v[220:221], s[42:43], 0, v[172:173]
	global_load_lds_dwordx4 v[218:219], off
	v_lshl_add_u64 v[218:219], s[70:71], 0, v[174:175]
	s_add_i32 m0, s69, 0x2000
	s_nop 0
	global_load_lds_dwordx4 v[218:219], off
	v_lshl_add_u64 v[218:219], s[42:43], 0, v[168:169]
	s_mov_b32 m0, s49
	s_nop 0
	global_load_lds_dwordx4 v[218:219], off
	s_mov_b32 m0, s50
	s_nop 0
	global_load_lds_dwordx4 v[220:221], off
	s_waitcnt vmcnt(8)
	s_waitcnt lgkmcnt(0)
	s_barrier
; #define PG8_STAGE(bufoff, gbase, voff) do { _Pragma("unroll") for (int _i = 0; _i < 2; ++_i) \
;         __builtin_amdgcn_global_load_lds((const unsigned*)((const char*)(gbase) + (voff)[_i]), (PG8_LAS unsigned*)(lds + (bufoff) + ldsw + _i * 8192), 16, 0, 0); } while (0)
; #define PG8_LDA(dst, b, h) do { _Pragma("unroll") for (int m = 0; m < 4; ++m) _Pragma("unroll") for (int k = 0; k < 2; ++k) dst[m][k] = *(const PG8_LAS bf16x8*)(lds + PG8_SA(b, h) + aoff + m * 2048 + k * 1024); } while (0)
; #define PG8_LDB(dst, b, h) do { _Pragma("unroll") for (int n = 0; n < 2; ++n) _Pragma("unroll") for (int k = 0; k < 2; ++k) dst[n][k] = *(const PG8_LAS bf16x8*)(lds + PG8_SB(b, h) + boff + n * 2048 + k * 1024); } while (0)
; #define PG8_MMA(ai, bj, At, Bt) do { __builtin_amdgcn_s_setprio(1); _Pragma("unroll") for (int m = 0; m < 4; ++m) _Pragma("unroll") for (int n = 0; n < 2; ++n) _Pragma("unroll") for (int k = 0; k < 2; ++k) \
;         acc[ai][bj][m][n] = __builtin_amdgcn_mfma_f32_16x16x32_bf16(Bt[n][k], At[m][k], acc[ai][bj][m][n], 0, 0, 0); __builtin_amdgcn_s_setprio(0); } while (0)
; #define PG8_WAIT_V(n) asm volatile("s_waitcnt vmcnt(" #n ")" ::: "memory")
; #define PG8_WAIT_L(n) asm volatile("s_waitcnt lgkmcnt(" #n ")" ::: "memory")
; #define PG8_BAR __builtin_amdgcn_s_barrier()
; #define PG8_SCHED __builtin_amdgcn_sched_barrier(0)
; template <class Epi, class Sched, bool ALIGN_EPI = false, bool SP2 = false>
; __device__ __forceinline__ void gemm_phase(PG8_LAS unsigned char* lds, const Gemm g, const Sched& S, const Epi& E) {
;     ...
;             PG8_WAIT_V(8); PG8_WAIT_L(0); PG8_BAR; PG8_MMA(1, 0, At, B0); PG8_MMA(1, 1, At, B1); PG8_BAR; PG8_SCHED;
;             PG8_LDB(B0, 1, 0); PG8_LDB(B1, 1, 1); PG8_SCHED; PG8_LDA(At, 1, 0); PG8_STAGE(PG8_SA(0, 1), a2 + hstep, voffA);
;             PG8_WAIT_V(8); PG8_WAIT_L(0); PG8_BAR; PG8_MMA(0, 0, At, B0); PG8_MMA(0, 1, At, B1); PG8_BAR; PG8_SCHED;
	v_mfma_f32_16x16x32_bf16 v[60:63], v[128:131], v[160:163], v[60:63]
	v_mfma_f32_16x16x32_bf16 v[56:59], v[136:139], v[160:163], v[56:59]
	v_mfma_f32_16x16x32_bf16 v[44:47], v[128:131], v[184:187], v[44:47]
	v_mfma_f32_16x16x32_bf16 v[40:43], v[136:139], v[184:187], v[40:43]
	v_mfma_f32_16x16x32_bf16 v[28:31], v[128:131], v[192:195], v[28:31]
	v_mfma_f32_16x16x32_bf16 v[24:27], v[136:139], v[192:195], v[24:27]
	v_mfma_f32_16x16x32_bf16 v[12:15], v[128:131], v[208:211], v[12:15]
	v_mfma_f32_16x16x32_bf16 v[8:11], v[136:139], v[208:211], v[8:11]
	v_mfma_f32_16x16x32_bf16 v[60:63], v[132:135], v[164:167], v[60:63]
	v_mfma_f32_16x16x32_bf16 v[56:59], v[140:143], v[164:167], v[56:59]
	v_mfma_f32_16x16x32_bf16 v[44:47], v[132:135], v[188:191], v[44:47]
	v_mfma_f32_16x16x32_bf16 v[40:43], v[140:143], v[188:191], v[40:43]
	v_mfma_f32_16x16x32_bf16 v[28:31], v[132:135], v[204:207], v[28:31]
	v_mfma_f32_16x16x32_bf16 v[24:27], v[140:143], v[204:207], v[24:27]
	v_mfma_f32_16x16x32_bf16 v[12:15], v[132:135], v[212:215], v[12:15]
	v_mfma_f32_16x16x32_bf16 v[8:11], v[140:143], v[212:215], v[8:11]
	v_mfma_f32_16x16x32_bf16 v[52:55], v[144:147], v[160:163], v[52:55]
	v_mfma_f32_16x16x32_bf16 v[48:51], v[152:155], v[160:163], v[48:51]
	v_mfma_f32_16x16x32_bf16 v[36:39], v[144:147], v[184:187], v[36:39]
	v_mfma_f32_16x16x32_bf16 v[32:35], v[152:155], v[184:187], v[32:35]
	v_mfma_f32_16x16x32_bf16 v[20:23], v[144:147], v[192:195], v[20:23]
	v_mfma_f32_16x16x32_bf16 v[16:19], v[152:155], v[192:195], v[16:19]
	v_mfma_f32_16x16x32_bf16 v[4:7], v[144:147], v[208:211], v[4:7]
	v_mfma_f32_16x16x32_bf16 v[0:3], v[152:155], v[208:211], v[0:3]
	v_mfma_f32_16x16x32_bf16 v[52:55], v[148:151], v[164:167], v[52:55]
	v_mfma_f32_16x16x32_bf16 v[48:51], v[156:159], v[164:167], v[48:51]
	v_mfma_f32_16x16x32_bf16 v[36:39], v[148:151], v[188:191], v[36:39]
	v_mfma_f32_16x16x32_bf16 v[32:35], v[156:159], v[188:191], v[32:35]
	v_mfma_f32_16x16x32_bf16 v[20:23], v[148:151], v[204:207], v[20:23]
	v_mfma_f32_16x16x32_bf16 v[16:19], v[156:159], v[204:207], v[16:19]
	v_mfma_f32_16x16x32_bf16 v[4:7], v[148:151], v[212:215], v[4:7]
	v_mfma_f32_16x16x32_bf16 v[0:3], v[156:159], v[212:215], v[0:3]
	s_barrier
	s_add_i32 s69, 0, 0x18000
	s_add_i32 s70, 0, 0x1c000
	v_add_u32_e32 v140, s69, v199
	v_add_u32_e32 v156, s70, v199
	ds_read_b128 v[128:131], v140
	ds_read_b128 v[132:135], v140 offset:1024
	ds_read_b128 v[136:139], v140 offset:2048
	ds_read_b128 v[140:143], v140 offset:3072
	ds_read_b128 v[144:147], v156
	ds_read_b128 v[148:151], v156 offset:1024
	ds_read_b128 v[152:155], v156 offset:2048
	ds_read_b128 v[156:159], v156 offset:3072
	s_add_u32 s42, s42, 0xb0000
	s_addc_u32 s43, s43, 0
	s_mov_b32 m0, s51
	v_lshl_add_u64 v[222:223], s[42:43], 0, v[168:169]
	ds_read_b128 v[160:163], v203 offset:32768
	ds_read_b128 v[164:167], v203 offset:33792
	ds_read_b128 v[184:187], v203 offset:34816
	ds_read_b128 v[188:191], v203 offset:35840
	ds_read_b128 v[192:195], v203 offset:36864
	ds_read_b128 v[204:207], v203 offset:37888
	ds_read_b128 v[208:211], v203 offset:38912
	ds_read_b128 v[212:215], v203 offset:39936
	global_load_lds_dwordx4 v[222:223], off
	v_lshl_add_u64 v[222:223], s[42:43], 0, v[172:173]
	s_mov_b32 m0, s52
	s_nop 0
	global_load_lds_dwordx4 v[222:223], off
	s_waitcnt vmcnt(8)
	s_waitcnt lgkmcnt(0)
	s_barrier
	v_mfma_f32_16x16x32_bf16 v[124:127], v[128:131], v[160:163], v[124:127]
	v_mfma_f32_16x16x32_bf16 v[120:123], v[136:139], v[160:163], v[120:123]
	v_mfma_f32_16x16x32_bf16 v[116:119], v[128:131], v[184:187], v[116:119]
	v_mfma_f32_16x16x32_bf16 v[104:107], v[136:139], v[184:187], v[104:107]
	v_mfma_f32_16x16x32_bf16 v[92:95], v[128:131], v[192:195], v[92:95]
	v_mfma_f32_16x16x32_bf16 v[88:91], v[136:139], v[192:195], v[88:91]
	v_mfma_f32_16x16x32_bf16 v[76:79], v[128:131], v[208:211], v[76:79]
	v_mfma_f32_16x16x32_bf16 v[72:75], v[136:139], v[208:211], v[72:75]
	v_mfma_f32_16x16x32_bf16 v[124:127], v[132:135], v[164:167], v[124:127]
	v_mfma_f32_16x16x32_bf16 v[120:123], v[140:143], v[164:167], v[120:123]
	v_mfma_f32_16x16x32_bf16 v[116:119], v[132:135], v[188:191], v[116:119]
	v_mfma_f32_16x16x32_bf16 v[104:107], v[140:143], v[188:191], v[104:107]
	v_mfma_f32_16x16x32_bf16 v[92:95], v[132:135], v[204:207], v[92:95]
	v_mfma_f32_16x16x32_bf16 v[88:91], v[140:143], v[204:207], v[88:91]
	v_mfma_f32_16x16x32_bf16 v[76:79], v[132:135], v[212:215], v[76:79]
	v_mfma_f32_16x16x32_bf16 v[72:75], v[140:143], v[212:215], v[72:75]
	v_mfma_f32_16x16x32_bf16 v[112:115], v[144:147], v[160:163], v[112:115]
	v_mfma_f32_16x16x32_bf16 v[108:111], v[152:155], v[160:163], v[108:111]
	v_mfma_f32_16x16x32_bf16 v[100:103], v[144:147], v[184:187], v[100:103]
	v_mfma_f32_16x16x32_bf16 v[96:99], v[152:155], v[184:187], v[96:99]
	v_mfma_f32_16x16x32_bf16 v[84:87], v[144:147], v[192:195], v[84:87]
	v_mfma_f32_16x16x32_bf16 v[80:83], v[152:155], v[192:195], v[80:83]
	v_mfma_f32_16x16x32_bf16 v[68:71], v[144:147], v[208:211], v[68:71]
	v_mfma_f32_16x16x32_bf16 v[64:67], v[152:155], v[208:211], v[64:67]
	v_mfma_f32_16x16x32_bf16 v[112:115], v[148:151], v[164:167], v[112:115]
	v_mfma_f32_16x16x32_bf16 v[108:111], v[156:159], v[164:167], v[108:111]
	v_mfma_f32_16x16x32_bf16 v[100:103], v[148:151], v[188:191], v[100:103]
	v_mfma_f32_16x16x32_bf16 v[96:99], v[156:159], v[188:191], v[96:99]
	v_mfma_f32_16x16x32_bf16 v[84:87], v[148:151], v[204:207], v[84:87]
	v_mfma_f32_16x16x32_bf16 v[80:83], v[156:159], v[204:207], v[80:83]
	v_mfma_f32_16x16x32_bf16 v[68:71], v[148:151], v[212:215], v[68:71]
	v_mfma_f32_16x16x32_bf16 v[64:67], v[156:159], v[212:215], v[64:67]
	s_barrier
; #define PG8_STAGE(bufoff, gbase, voff) do { _Pragma("unroll") for (int _i = 0; _i < 2; ++_i) \
;         __builtin_amdgcn_global_load_lds((const unsigned*)((const char*)(gbase) + (voff)[_i]), (PG8_LAS unsigned*)(lds + (bufoff) + ldsw + _i * 8192), 16, 0, 0); } while (0)
; #define PG8_LDA(dst, b, h) do { _Pragma("unroll") for (int m = 0; m < 4; ++m) _Pragma("unroll") for (int k = 0; k < 2; ++k) dst[m][k] = *(const PG8_LAS bf16x8*)(lds + PG8_SA(b, h) + aoff + m * 2048 + k * 1024); } while (0)
; #define PG8_MMA(ai, bj, At, Bt) do { __builtin_amdgcn_s_setprio(1); _Pragma("unroll") for (int m = 0; m < 4; ++m) _Pragma("unroll") for (int n = 0; n < 2; ++n) _Pragma("unroll") for (int k = 0; k < 2; ++k) \
;         acc[ai][bj][m][n] = __builtin_amdgcn_mfma_f32_16x16x32_bf16(Bt[n][k], At[m][k], acc[ai][bj][m][n], 0, 0, 0); __builtin_amdgcn_s_setprio(0); } while (0)
; #define PG8_WAIT_V(n) asm volatile("s_waitcnt vmcnt(" #n ")" ::: "memory")
; #define PG8_WAIT_L(n) asm volatile("s_waitcnt lgkmcnt(" #n ")" ::: "memory")
; #define PG8_BAR __builtin_amdgcn_s_barrier()
; #define PG8_SCHED __builtin_amdgcn_sched_barrier(0)
; template <class Epi, class Sched, bool ALIGN_EPI = false, bool SP2 = false>
; __device__ __forceinline__ void gemm_phase(PG8_LAS unsigned char* lds, const Gemm g, const Sched& S, const Epi& E) {
;     ...
;             PG8_LDA(At, 1, 1); PG8_STAGE(PG8_SB(1, 0), b3, voffB); PG8_STAGE(PG8_SB(1, 1), b3 + hstep, voffB); PG8_STAGE(PG8_SA(1, 0), a3, voffA);
;             PG8_WAIT_V(8); PG8_WAIT_L(0); PG8_BAR; PG8_MMA(1, 0, At, B0); PG8_MMA(1, 1, At, B1); PG8_BAR; PG8_SCHED;
;     ...
;         if constexpr (ALIGN_EPI) { if (wr == 0) PG8_BAR; }
	s_add_i32 s42, s69, s48
	v_lshl_add_u64 v[196:197], v[196:197], 0, s[14:15]
	s_mov_b32 m0, s42
	ds_read_b128 v[160:163], v203 offset:49152
	ds_read_b128 v[164:167], v203 offset:50176
	ds_read_b128 v[184:187], v203 offset:51200
	ds_read_b128 v[188:191], v203 offset:52224
	ds_read_b128 v[192:195], v203 offset:53248
	ds_read_b128 v[204:207], v203 offset:54272
	ds_read_b128 v[208:211], v203 offset:55296
	ds_read_b128 v[212:215], v203 offset:56320
	global_load_lds_dwordx4 v[196:197], off
	s_add_i32 m0, s42, 0x2000
	s_add_u32 s40, s40, 0xb0080
	v_lshl_add_u64 v[196:197], v[216:217], 0, s[14:15]
	s_addc_u32 s41, s41, 0
	s_add_i32 s42, s70, s48
	global_load_lds_dwordx4 v[196:197], off
	v_lshl_add_u64 v[196:197], s[40:41], 0, v[170:171]
	s_mov_b32 m0, s42
	s_nop 0
	global_load_lds_dwordx4 v[196:197], off
	v_lshl_add_u64 v[196:197], s[40:41], 0, v[174:175]
	s_add_i32 m0, s42, 0x2000
	s_nop 0
	global_load_lds_dwordx4 v[196:197], off
	v_lshl_add_u64 v[196:197], v[218:219], 0, s[14:15]
	s_mov_b32 m0, s54
	s_nop 0
	global_load_lds_dwordx4 v[196:197], off
	v_lshl_add_u64 v[196:197], v[220:221], 0, s[14:15]
	s_mov_b32 m0, s55
	s_nop 0
	global_load_lds_dwordx4 v[196:197], off
	s_waitcnt vmcnt(8)
	s_waitcnt lgkmcnt(0)
	s_barrier
	v_mfma_f32_16x16x32_bf16 v[60:63], v[128:131], v[160:163], v[60:63]
	v_mfma_f32_16x16x32_bf16 v[56:59], v[136:139], v[160:163], v[56:59]
	v_mfma_f32_16x16x32_bf16 v[44:47], v[128:131], v[184:187], v[44:47]
	v_mfma_f32_16x16x32_bf16 v[40:43], v[136:139], v[184:187], v[40:43]
	v_mfma_f32_16x16x32_bf16 v[28:31], v[128:131], v[192:195], v[28:31]
	v_mfma_f32_16x16x32_bf16 v[24:27], v[136:139], v[192:195], v[24:27]
	v_mfma_f32_16x16x32_bf16 v[12:15], v[128:131], v[208:211], v[12:15]
	v_mfma_f32_16x16x32_bf16 v[8:11], v[136:139], v[208:211], v[8:11]
	v_mfma_f32_16x16x32_bf16 v[60:63], v[132:135], v[164:167], v[60:63]
	v_mfma_f32_16x16x32_bf16 v[56:59], v[140:143], v[164:167], v[56:59]
	v_mfma_f32_16x16x32_bf16 v[44:47], v[132:135], v[188:191], v[44:47]
	v_mfma_f32_16x16x32_bf16 v[40:43], v[140:143], v[188:191], v[40:43]
	v_mfma_f32_16x16x32_bf16 v[28:31], v[132:135], v[204:207], v[28:31]
	v_mfma_f32_16x16x32_bf16 v[24:27], v[140:143], v[204:207], v[24:27]
	v_mfma_f32_16x16x32_bf16 v[12:15], v[132:135], v[212:215], v[12:15]
	v_mfma_f32_16x16x32_bf16 v[8:11], v[140:143], v[212:215], v[8:11]
	v_mfma_f32_16x16x32_bf16 v[52:55], v[144:147], v[160:163], v[52:55]
	v_mfma_f32_16x16x32_bf16 v[48:51], v[152:155], v[160:163], v[48:51]
	v_mfma_f32_16x16x32_bf16 v[36:39], v[144:147], v[184:187], v[36:39]
	v_mfma_f32_16x16x32_bf16 v[32:35], v[152:155], v[184:187], v[32:35]
	v_mfma_f32_16x16x32_bf16 v[20:23], v[144:147], v[192:195], v[20:23]
	v_mfma_f32_16x16x32_bf16 v[16:19], v[152:155], v[192:195], v[16:19]
	v_mfma_f32_16x16x32_bf16 v[4:7], v[144:147], v[208:211], v[4:7]
	v_mfma_f32_16x16x32_bf16 v[0:3], v[152:155], v[208:211], v[0:3]
	v_mfma_f32_16x16x32_bf16 v[52:55], v[148:151], v[164:167], v[52:55]
	v_mfma_f32_16x16x32_bf16 v[48:51], v[156:159], v[164:167], v[48:51]
	v_mfma_f32_16x16x32_bf16 v[36:39], v[148:151], v[188:191], v[36:39]
	v_mfma_f32_16x16x32_bf16 v[32:35], v[156:159], v[188:191], v[32:35]
	v_mfma_f32_16x16x32_bf16 v[20:23], v[148:151], v[204:207], v[20:23]
	v_mfma_f32_16x16x32_bf16 v[16:19], v[156:159], v[204:207], v[16:19]
	v_mfma_f32_16x16x32_bf16 v[4:7], v[148:151], v[212:215], v[4:7]
	v_mfma_f32_16x16x32_bf16 v[0:3], v[156:159], v[212:215], v[0:3]
	s_barrier
	s_add_i32 s68, s68, 2
	s_add_u32 s38, s38, 0x100
	s_addc_u32 s39, s39, 0
	s_add_u32 s66, s66, 0x100
	s_addc_u32 s67, s67, 0
	s_cmp_gt_u32 s68, 41
	s_cbranch_scc0 .LBB0_2597
	s_and_b64 vcc, exec, s[16:17]
	s_cbranch_vccz .LBB0_2600
	s_barrier
